# MFMA issue order inside each 8-group changed to a snake so only one operand changes between consecutive MFMAs (operand toggling)
# baseline (speedup 1.0000x reference)
; #define PG8_STAGE(bufoff, gbase, voff) do { _Pragma("unroll") for (int _i = 0; _i < 2; ++_i) \
;         __builtin_amdgcn_global_load_lds((const unsigned*)((const char*)(gbase) + (voff)[_i]), (PG8_LAS unsigned*)(lds + (bufoff) + ldsw + _i * 8192), 16, 0, 0); } while (0)
; #define PG8_LDA(dst, b, h) do { _Pragma("unroll") for (int m = 0; m < 4; ++m) _Pragma("unroll") for (int k = 0; k < 2; ++k) dst[m][k] = *(const PG8_LAS bf16x8*)(lds + PG8_SA(b, h) + aoff + m * 2048 + k * 1024); } while (0)
; #define PG8_MMA(ai, bj, At, Bt) do { __builtin_amdgcn_s_setprio(1); _Pragma("unroll") for (int m = 0; m < 4; ++m) _Pragma("unroll") for (int n = 0; n < 2; ++n) _Pragma("unroll") for (int k = 0; k < 2; ++k) \
;         acc[ai][bj][m][n] = __builtin_amdgcn_mfma_f32_16x16x32_bf16(Bt[n][k], At[m][k], acc[ai][bj][m][n], 0, 0, 0); __builtin_amdgcn_s_setprio(0); } while (0)
; #define PG8_WAIT_V(n) asm volatile("s_waitcnt vmcnt(" #n ")" ::: "memory")
; #define PG8_WAIT_L(n) asm volatile("s_waitcnt lgkmcnt(" #n ")" ::: "memory")
; #define PG8_BAR __builtin_amdgcn_s_barrier()
; #define PG8_SCHED __builtin_amdgcn_sched_barrier(0)
; template <class Epi, class Sched, bool ALIGN_EPI = false, bool SP2 = false>
; __device__ __forceinline__ void gemm_phase(PG8_LAS unsigned char* lds, const Gemm g, const Sched& S, const Epi& E) {
;     ...
;             PG8_WAIT_V(8); PG8_WAIT_L(0); PG8_BAR; PG8_MMA(0, 0, At, B0); PG8_MMA(0, 1, At, B1); PG8_BAR; PG8_SCHED;
;             PG8_LDA(At, 0, 1); PG8_STAGE(PG8_SB(0, 0), b2, voffB); PG8_STAGE(PG8_SB(0, 1), b2 + hstep, voffB); PG8_STAGE(PG8_SA(0, 0), a2, voffA);
;             PG8_WAIT_V(8); PG8_WAIT_L(0); PG8_BAR; PG8_MMA(1, 0, At, B0); PG8_MMA(1, 1, At, B1); PG8_BAR; PG8_SCHED;
.Lvw_0:
	s_waitcnt lgkmcnt(0)
	s_barrier
	s_setprio 1
	s_waitcnt lgkmcnt(0)
	v_mfma_f32_16x16x32_bf16 v[124:127], v[150:153], v[182:185], v[124:127]
	v_mfma_f32_16x16x32_bf16 v[120:123], v[158:161], v[182:185], v[120:123]
	v_mfma_f32_16x16x32_bf16 v[104:107], v[158:161], v[194:197], v[104:107]
	v_mfma_f32_16x16x32_bf16 v[108:111], v[150:153], v[194:197], v[108:111]
	v_mfma_f32_16x16x32_bf16 v[92:95], v[150:153], v[202:205], v[92:95]
	v_mfma_f32_16x16x32_bf16 v[88:91], v[158:161], v[202:205], v[88:91]
	v_mfma_f32_16x16x32_bf16 v[72:75], v[158:161], v[210:213], v[72:75]
	v_mfma_f32_16x16x32_bf16 v[76:79], v[150:153], v[210:213], v[76:79]
	v_mfma_f32_16x16x32_bf16 v[124:127], v[154:157], v[186:189], v[124:127]
	v_mfma_f32_16x16x32_bf16 v[120:123], v[162:165], v[186:189], v[120:123]
	v_mfma_f32_16x16x32_bf16 v[104:107], v[162:165], v[198:201], v[104:107]
	v_mfma_f32_16x16x32_bf16 v[108:111], v[154:157], v[198:201], v[108:111]
	v_mfma_f32_16x16x32_bf16 v[92:95], v[154:157], v[206:209], v[92:95]
	v_mfma_f32_16x16x32_bf16 v[88:91], v[162:165], v[206:209], v[88:91]
	v_mfma_f32_16x16x32_bf16 v[72:75], v[162:165], v[214:217], v[72:75]
	v_mfma_f32_16x16x32_bf16 v[76:79], v[154:157], v[214:217], v[76:79]
	s_setprio 0
	s_setprio 1
	v_mfma_f32_16x16x32_bf16 v[116:119], v[166:169], v[182:185], v[116:119]
	v_mfma_f32_16x16x32_bf16 v[112:115], v[174:177], v[182:185], v[112:115]
	v_mfma_f32_16x16x32_bf16 v[96:99], v[174:177], v[194:197], v[96:99]
	v_mfma_f32_16x16x32_bf16 v[100:103], v[166:169], v[194:197], v[100:103]
	v_mfma_f32_16x16x32_bf16 v[84:87], v[166:169], v[202:205], v[84:87]
	v_mfma_f32_16x16x32_bf16 v[80:83], v[174:177], v[202:205], v[80:83]
	v_mfma_f32_16x16x32_bf16 v[64:67], v[174:177], v[210:213], v[64:67]
	v_mfma_f32_16x16x32_bf16 v[68:71], v[166:169], v[210:213], v[68:71]
	v_mfma_f32_16x16x32_bf16 v[116:119], v[170:173], v[186:189], v[116:119]
	v_mfma_f32_16x16x32_bf16 v[112:115], v[178:181], v[186:189], v[112:115]
	v_mfma_f32_16x16x32_bf16 v[96:99], v[178:181], v[198:201], v[96:99]
	v_mfma_f32_16x16x32_bf16 v[100:103], v[170:173], v[198:201], v[100:103]
	v_mfma_f32_16x16x32_bf16 v[84:87], v[170:173], v[206:209], v[84:87]
	v_mfma_f32_16x16x32_bf16 v[80:83], v[178:181], v[206:209], v[80:83]
	v_mfma_f32_16x16x32_bf16 v[64:67], v[178:181], v[214:217], v[64:67]
	v_mfma_f32_16x16x32_bf16 v[68:71], v[170:173], v[214:217], v[68:71]
	s_setprio 0
	s_waitcnt vmcnt(8)
	s_barrier
	s_add_i32 s63, s54, s46
	v_lshl_add_u64 v[190:191], s[42:43], 0, v[132:133]
	s_mov_b32 m0, s63
	ds_read_b128 v[182:185], v149 offset:16384
	ds_read_b128 v[186:189], v149 offset:17408
	ds_read_b128 v[194:197], v149 offset:18432
	ds_read_b128 v[198:201], v149 offset:19456
	ds_read_b128 v[202:205], v149 offset:20480
	ds_read_b128 v[206:209], v149 offset:21504
	ds_read_b128 v[210:213], v149 offset:22528
	ds_read_b128 v[214:217], v149 offset:23552
	global_load_lds_dwordx4 v[190:191], off
	s_add_i32 m0, s63, 0x2000
	s_add_u32 s64, s42, 0x80000
	v_lshl_add_u64 v[218:219], s[42:43], 0, v[128:129]
	s_addc_u32 s65, s43, 0
	s_add_i32 s63, s55, s46
	global_load_lds_dwordx4 v[218:219], off
	v_lshl_add_u64 v[220:221], s[64:65], 0, v[132:133]
	s_mov_b32 m0, s63
	v_lshl_add_u64 v[222:223], s[44:45], 0, v[130:131]
	global_load_lds_dwordx4 v[220:221], off
	v_lshl_add_u64 v[220:221], s[64:65], 0, v[128:129]
	s_add_i32 m0, s63, 0x2000
	s_nop 0
	global_load_lds_dwordx4 v[220:221], off
	v_lshl_add_u64 v[220:221], s[44:45], 0, v[134:135]
	s_mov_b32 m0, s33
	s_nop 0
	global_load_lds_dwordx4 v[220:221], off
	s_mov_b32 m0, s39
	s_nop 0
	global_load_lds_dwordx4 v[222:223], off
	s_mov_b64 vcc, s[98:99]
	s_cbranch_vccnz .Lvw_1
	s_waitcnt vmcnt(8)
.Lvw_1:
	s_waitcnt lgkmcnt(0)
	s_barrier
	s_setprio 1
	s_waitcnt lgkmcnt(0)
	v_mfma_f32_16x16x32_bf16 v[60:63], v[150:153], v[182:185], v[60:63]
	v_mfma_f32_16x16x32_bf16 v[56:59], v[158:161], v[182:185], v[56:59]
	v_mfma_f32_16x16x32_bf16 v[40:43], v[158:161], v[194:197], v[40:43]
	v_mfma_f32_16x16x32_bf16 v[44:47], v[150:153], v[194:197], v[44:47]
	v_mfma_f32_16x16x32_bf16 v[28:31], v[150:153], v[202:205], v[28:31]
	v_mfma_f32_16x16x32_bf16 v[24:27], v[158:161], v[202:205], v[24:27]
	v_mfma_f32_16x16x32_bf16 v[8:11], v[158:161], v[210:213], v[8:11]
	v_mfma_f32_16x16x32_bf16 v[12:15], v[150:153], v[210:213], v[12:15]
	v_mfma_f32_16x16x32_bf16 v[60:63], v[154:157], v[186:189], v[60:63]
	v_mfma_f32_16x16x32_bf16 v[56:59], v[162:165], v[186:189], v[56:59]
	v_mfma_f32_16x16x32_bf16 v[40:43], v[162:165], v[198:201], v[40:43]
	v_mfma_f32_16x16x32_bf16 v[44:47], v[154:157], v[198:201], v[44:47]
	v_mfma_f32_16x16x32_bf16 v[28:31], v[154:157], v[206:209], v[28:31]
	v_mfma_f32_16x16x32_bf16 v[24:27], v[162:165], v[206:209], v[24:27]
	v_mfma_f32_16x16x32_bf16 v[8:11], v[162:165], v[214:217], v[8:11]
	v_mfma_f32_16x16x32_bf16 v[12:15], v[154:157], v[214:217], v[12:15]
	s_setprio 0
	s_setprio 1
	v_mfma_f32_16x16x32_bf16 v[52:55], v[166:169], v[182:185], v[52:55]
	v_mfma_f32_16x16x32_bf16 v[48:51], v[174:177], v[182:185], v[48:51]
	v_mfma_f32_16x16x32_bf16 v[32:35], v[174:177], v[194:197], v[32:35]
	v_mfma_f32_16x16x32_bf16 v[36:39], v[166:169], v[194:197], v[36:39]
	v_mfma_f32_16x16x32_bf16 v[20:23], v[166:169], v[202:205], v[20:23]
	v_mfma_f32_16x16x32_bf16 v[16:19], v[174:177], v[202:205], v[16:19]
	v_mfma_f32_16x16x32_bf16 v[0:3], v[174:177], v[210:213], v[0:3]
	v_mfma_f32_16x16x32_bf16 v[4:7], v[166:169], v[210:213], v[4:7]
	v_mfma_f32_16x16x32_bf16 v[52:55], v[170:173], v[186:189], v[52:55]
	v_mfma_f32_16x16x32_bf16 v[48:51], v[178:181], v[186:189], v[48:51]
	v_mfma_f32_16x16x32_bf16 v[32:35], v[178:181], v[198:201], v[32:35]
	v_mfma_f32_16x16x32_bf16 v[36:39], v[170:173], v[198:201], v[36:39]
	v_mfma_f32_16x16x32_bf16 v[20:23], v[170:173], v[206:209], v[20:23]
	v_mfma_f32_16x16x32_bf16 v[16:19], v[178:181], v[206:209], v[16:19]
	v_mfma_f32_16x16x32_bf16 v[0:3], v[178:181], v[214:217], v[0:3]
	v_mfma_f32_16x16x32_bf16 v[4:7], v[170:173], v[214:217], v[4:7]
	s_setprio 0
	s_waitcnt vmcnt(8)
	s_barrier
; #define PG8_STAGE(bufoff, gbase, voff) do { _Pragma("unroll") for (int _i = 0; _i < 2; ++_i) \
;         __builtin_amdgcn_global_load_lds((const unsigned*)((const char*)(gbase) + (voff)[_i]), (PG8_LAS unsigned*)(lds + (bufoff) + ldsw + _i * 8192), 16, 0, 0); } while (0)
; #define PG8_LDA(dst, b, h) do { _Pragma("unroll") for (int m = 0; m < 4; ++m) _Pragma("unroll") for (int k = 0; k < 2; ++k) dst[m][k] = *(const PG8_LAS bf16x8*)(lds + PG8_SA(b, h) + aoff + m * 2048 + k * 1024); } while (0)
; #define PG8_LDB(dst, b, h) do { _Pragma("unroll") for (int n = 0; n < 2; ++n) _Pragma("unroll") for (int k = 0; k < 2; ++k) dst[n][k] = *(const PG8_LAS bf16x8*)(lds + PG8_SB(b, h) + boff + n * 2048 + k * 1024); } while (0)
; #define PG8_MMA(ai, bj, At, Bt) do { __builtin_amdgcn_s_setprio(1); _Pragma("unroll") for (int m = 0; m < 4; ++m) _Pragma("unroll") for (int n = 0; n < 2; ++n) _Pragma("unroll") for (int k = 0; k < 2; ++k) \
;         acc[ai][bj][m][n] = __builtin_amdgcn_mfma_f32_16x16x32_bf16(Bt[n][k], At[m][k], acc[ai][bj][m][n], 0, 0, 0); __builtin_amdgcn_s_setprio(0); } while (0)
; #define PG8_WAIT_V(n) asm volatile("s_waitcnt vmcnt(" #n ")" ::: "memory")
; #define PG8_WAIT_L(n) asm volatile("s_waitcnt lgkmcnt(" #n ")" ::: "memory")
; #define PG8_BAR __builtin_amdgcn_s_barrier()
; #define PG8_SCHED __builtin_amdgcn_sched_barrier(0)
; template <class Epi, class Sched, bool ALIGN_EPI = false, bool SP2 = false>
; __device__ __forceinline__ void gemm_phase(PG8_LAS unsigned char* lds, const Gemm g, const Sched& S, const Epi& E) {
;     ...
;             PG8_LDB(B0, 1, 0); PG8_LDB(B1, 1, 1); PG8_SCHED; PG8_LDA(At, 1, 0); PG8_STAGE(PG8_SA(0, 1), a2 + hstep, voffA);
;             PG8_WAIT_V(8); PG8_WAIT_L(0); PG8_BAR; PG8_MMA(0, 0, At, B0); PG8_MMA(0, 1, At, B1); PG8_BAR; PG8_SCHED;
;             PG8_LDA(At, 1, 1); PG8_STAGE(PG8_SB(1, 0), b3, voffB); PG8_STAGE(PG8_SB(1, 1), b3 + hstep, voffB); PG8_STAGE(PG8_SA(1, 0), a3, voffA);
	s_add_i32 s63, 0, 0x18000
	s_add_i32 s64, 0, 0x1c000
	v_add_u32_e32 v162, s63, v145
	v_add_u32_e32 v178, s64, v145
	ds_read_b128 v[150:153], v162
	ds_read_b128 v[154:157], v162 offset:1024
	ds_read_b128 v[158:161], v162 offset:2048
	ds_read_b128 v[162:165], v162 offset:3072
	ds_read_b128 v[166:169], v178
	ds_read_b128 v[170:173], v178 offset:1024
	ds_read_b128 v[174:177], v178 offset:2048
	ds_read_b128 v[178:181], v178 offset:3072
	s_add_u32 s44, s44, 0x80000
	s_addc_u32 s45, s45, 0
	s_mov_b32 m0, s47
	v_lshl_add_u64 v[224:225], s[44:45], 0, v[134:135]
	ds_read_b128 v[182:185], v149 offset:32768
	ds_read_b128 v[186:189], v149 offset:33792
	ds_read_b128 v[194:197], v149 offset:34816
	ds_read_b128 v[198:201], v149 offset:35840
	ds_read_b128 v[202:205], v149 offset:36864
	ds_read_b128 v[206:209], v149 offset:37888
	ds_read_b128 v[210:213], v149 offset:38912
	ds_read_b128 v[214:217], v149 offset:39936
	global_load_lds_dwordx4 v[224:225], off
	v_lshl_add_u64 v[224:225], s[44:45], 0, v[130:131]
	s_mov_b32 m0, s48
	s_nop 0
	global_load_lds_dwordx4 v[224:225], off
	s_mov_b64 vcc, s[98:99]
	s_cbranch_vccnz .Lvw_2
	s_waitcnt vmcnt(8)
.Lvw_2:
	s_waitcnt lgkmcnt(0)
	s_barrier
	s_setprio 1
	s_waitcnt lgkmcnt(0)
	v_mfma_f32_16x16x32_bf16 v[124:127], v[150:153], v[182:185], v[124:127]
	v_mfma_f32_16x16x32_bf16 v[120:123], v[158:161], v[182:185], v[120:123]
	v_mfma_f32_16x16x32_bf16 v[104:107], v[158:161], v[194:197], v[104:107]
	v_mfma_f32_16x16x32_bf16 v[108:111], v[150:153], v[194:197], v[108:111]
	v_mfma_f32_16x16x32_bf16 v[92:95], v[150:153], v[202:205], v[92:95]
	v_mfma_f32_16x16x32_bf16 v[88:91], v[158:161], v[202:205], v[88:91]
	v_mfma_f32_16x16x32_bf16 v[72:75], v[158:161], v[210:213], v[72:75]
	v_mfma_f32_16x16x32_bf16 v[76:79], v[150:153], v[210:213], v[76:79]
	v_mfma_f32_16x16x32_bf16 v[124:127], v[154:157], v[186:189], v[124:127]
	v_mfma_f32_16x16x32_bf16 v[120:123], v[162:165], v[186:189], v[120:123]
	v_mfma_f32_16x16x32_bf16 v[104:107], v[162:165], v[198:201], v[104:107]
	v_mfma_f32_16x16x32_bf16 v[108:111], v[154:157], v[198:201], v[108:111]
	v_mfma_f32_16x16x32_bf16 v[92:95], v[154:157], v[206:209], v[92:95]
	v_mfma_f32_16x16x32_bf16 v[88:91], v[162:165], v[206:209], v[88:91]
	v_mfma_f32_16x16x32_bf16 v[72:75], v[162:165], v[214:217], v[72:75]
	v_mfma_f32_16x16x32_bf16 v[76:79], v[154:157], v[214:217], v[76:79]
	s_setprio 0
	s_setprio 1
	v_mfma_f32_16x16x32_bf16 v[116:119], v[166:169], v[182:185], v[116:119]
	v_mfma_f32_16x16x32_bf16 v[112:115], v[174:177], v[182:185], v[112:115]
	v_mfma_f32_16x16x32_bf16 v[96:99], v[174:177], v[194:197], v[96:99]
	v_mfma_f32_16x16x32_bf16 v[100:103], v[166:169], v[194:197], v[100:103]
	v_mfma_f32_16x16x32_bf16 v[84:87], v[166:169], v[202:205], v[84:87]
	v_mfma_f32_16x16x32_bf16 v[80:83], v[174:177], v[202:205], v[80:83]
	v_mfma_f32_16x16x32_bf16 v[64:67], v[174:177], v[210:213], v[64:67]
	v_mfma_f32_16x16x32_bf16 v[68:71], v[166:169], v[210:213], v[68:71]
	v_mfma_f32_16x16x32_bf16 v[116:119], v[170:173], v[186:189], v[116:119]
	v_mfma_f32_16x16x32_bf16 v[112:115], v[178:181], v[186:189], v[112:115]
	v_mfma_f32_16x16x32_bf16 v[96:99], v[178:181], v[198:201], v[96:99]
	v_mfma_f32_16x16x32_bf16 v[100:103], v[170:173], v[198:201], v[100:103]
	v_mfma_f32_16x16x32_bf16 v[84:87], v[170:173], v[206:209], v[84:87]
	v_mfma_f32_16x16x32_bf16 v[80:83], v[178:181], v[206:209], v[80:83]
	v_mfma_f32_16x16x32_bf16 v[64:67], v[178:181], v[214:217], v[64:67]
	v_mfma_f32_16x16x32_bf16 v[68:71], v[170:173], v[214:217], v[68:71]
	s_setprio 0
	s_waitcnt vmcnt(8)
	s_barrier
	s_add_i32 s44, s63, s46
	v_lshl_add_u64 v[190:191], v[190:191], 0, s[6:7]
	s_mov_b32 m0, s44
	ds_read_b128 v[182:185], v149 offset:49152
	ds_read_b128 v[186:189], v149 offset:50176
	ds_read_b128 v[194:197], v149 offset:51200
	ds_read_b128 v[198:201], v149 offset:52224
	ds_read_b128 v[202:205], v149 offset:53248
	ds_read_b128 v[206:209], v149 offset:54272
	ds_read_b128 v[210:213], v149 offset:55296
	ds_read_b128 v[214:217], v149 offset:56320
	global_load_lds_dwordx4 v[190:191], off
	s_add_i32 m0, s44, 0x2000
	s_add_u32 s42, s42, 0x80080
	v_lshl_add_u64 v[190:191], v[218:219], 0, s[6:7]
	s_addc_u32 s43, s43, 0
	s_add_i32 s44, s64, s46
	global_load_lds_dwordx4 v[190:191], off
	v_lshl_add_u64 v[190:191], s[42:43], 0, v[132:133]
	s_mov_b32 m0, s44
	s_nop 0
	global_load_lds_dwordx4 v[190:191], off
	v_lshl_add_u64 v[190:191], s[42:43], 0, v[128:129]
	s_add_i32 m0, s44, 0x2000
	s_nop 0
	global_load_lds_dwordx4 v[190:191], off
	v_lshl_add_u64 v[190:191], v[220:221], 0, s[6:7]
	s_mov_b32 m0, s50
	s_nop 0
	global_load_lds_dwordx4 v[190:191], off
	v_lshl_add_u64 v[190:191], v[222:223], 0, s[6:7]
	s_mov_b32 m0, s51
	s_nop 0
	global_load_lds_dwordx4 v[190:191], off
	s_mov_b64 vcc, s[98:99]
	s_cbranch_vccnz .Lvw_3
	s_waitcnt vmcnt(8)
; #define PG8_STAGE(bufoff, gbase, voff) do { _Pragma("unroll") for (int _i = 0; _i < 2; ++_i) \
;         __builtin_amdgcn_global_load_lds((const unsigned*)((const char*)(gbase) + (voff)[_i]), (PG8_LAS unsigned*)(lds + (bufoff) + ldsw + _i * 8192), 16, 0, 0); } while (0)
; #define PG8_LDA(dst, b, h) do { _Pragma("unroll") for (int m = 0; m < 4; ++m) _Pragma("unroll") for (int k = 0; k < 2; ++k) dst[m][k] = *(const PG8_LAS bf16x8*)(lds + PG8_SA(b, h) + aoff + m * 2048 + k * 1024); } while (0)
; #define PG8_LDB(dst, b, h) do { _Pragma("unroll") for (int n = 0; n < 2; ++n) _Pragma("unroll") for (int k = 0; k < 2; ++k) dst[n][k] = *(const PG8_LAS bf16x8*)(lds + PG8_SB(b, h) + boff + n * 2048 + k * 1024); } while (0)
; template <class Epi, class Sched, bool ALIGN_EPI = false, bool SP2 = false>
; __device__ __forceinline__ void gemm_phase(PG8_LAS unsigned char* lds, const Gemm g, const Sched& S, const Epi& E) {
;     ...
;             PG8_WAIT_V(8); PG8_WAIT_L(0); PG8_BAR; PG8_MMA(1, 0, At, B0); PG8_MMA(1, 1, At, B1); PG8_BAR; PG8_SCHED;
;             } else {
;             PG8_LDB(B0, 0, 0); PG8_SCHED; PG8_LDA(At, 0, 0); PG8_STAGE(PG8_SA(1, 1), a1 + hstep, voffA);
;             PG8_WAIT_L(8); PG8_BAR; PG8_WAIT_L(0); PG8_MMA(0, 0, At, B0); PG8_BAR; PG8_SCHED;
;             PG8_LDB(B1, 0, 1); PG8_STAGE(PG8_SB(0, 0), b2, voffB);
;             PG8_BAR; PG8_WAIT_L(0); PG8_MMA(0, 1, At, B1); PG8_BAR;
;             PG8_LDA(At, 0, 1); PG8_STAGE(PG8_SA(0, 0), a2, voffA);
;             PG8_BAR; PG8_WAIT_L(0); PG8_MMA(1, 0, At, B0); PG8_BAR; PG8_SCHED;
;             PG8_STAGE(PG8_SB(0, 1), b2 + hstep, voffB);
;             PG8_WAIT_V(6); PG8_BAR; PG8_MMA(1, 1, At, B1); PG8_BAR;
;             PG8_LDB(B0, 1, 0); PG8_SCHED; PG8_LDA(At, 1, 0); PG8_STAGE(PG8_SA(0, 1), a2 + hstep, voffA);
;             PG8_WAIT_L(8); PG8_BAR; PG8_WAIT_L(0); PG8_MMA(0, 0, At, B0); PG8_BAR; PG8_SCHED;
;             PG8_LDB(B1, 1, 1); PG8_STAGE(PG8_SB(1, 0), b3, voffB);
;             PG8_BAR; PG8_WAIT_L(0); PG8_MMA(0, 1, At, B1); PG8_BAR;
;             PG8_LDA(At, 1, 1); PG8_STAGE(PG8_SA(1, 0), a3, voffA);
;             PG8_BAR; PG8_WAIT_L(0); PG8_MMA(1, 0, At, B0); PG8_BAR; PG8_SCHED;
;             PG8_STAGE(PG8_SB(1, 1), b3 + hstep, voffB);
;             PG8_WAIT_V(6); PG8_BAR; PG8_MMA(1, 1, At, B1); PG8_BAR;
;             }
;         }
;         if constexpr (ALIGN_EPI) { if (wr == 0) PG8_BAR; }
.Lvw_3:
	s_waitcnt lgkmcnt(0)
	s_barrier
	s_setprio 1
	s_waitcnt lgkmcnt(0)
	v_mfma_f32_16x16x32_bf16 v[60:63], v[150:153], v[182:185], v[60:63]
	v_mfma_f32_16x16x32_bf16 v[56:59], v[158:161], v[182:185], v[56:59]
	v_mfma_f32_16x16x32_bf16 v[40:43], v[158:161], v[194:197], v[40:43]
	v_mfma_f32_16x16x32_bf16 v[44:47], v[150:153], v[194:197], v[44:47]
	v_mfma_f32_16x16x32_bf16 v[28:31], v[150:153], v[202:205], v[28:31]
	v_mfma_f32_16x16x32_bf16 v[24:27], v[158:161], v[202:205], v[24:27]
	v_mfma_f32_16x16x32_bf16 v[8:11], v[158:161], v[210:213], v[8:11]
	v_mfma_f32_16x16x32_bf16 v[12:15], v[150:153], v[210:213], v[12:15]
	v_mfma_f32_16x16x32_bf16 v[60:63], v[154:157], v[186:189], v[60:63]
	v_mfma_f32_16x16x32_bf16 v[56:59], v[162:165], v[186:189], v[56:59]
	v_mfma_f32_16x16x32_bf16 v[40:43], v[162:165], v[198:201], v[40:43]
	v_mfma_f32_16x16x32_bf16 v[44:47], v[154:157], v[198:201], v[44:47]
	v_mfma_f32_16x16x32_bf16 v[28:31], v[154:157], v[206:209], v[28:31]
	v_mfma_f32_16x16x32_bf16 v[24:27], v[162:165], v[206:209], v[24:27]
	v_mfma_f32_16x16x32_bf16 v[8:11], v[162:165], v[214:217], v[8:11]
	v_mfma_f32_16x16x32_bf16 v[12:15], v[154:157], v[214:217], v[12:15]
	s_setprio 0
	s_setprio 1
	v_mfma_f32_16x16x32_bf16 v[52:55], v[166:169], v[182:185], v[52:55]
	v_mfma_f32_16x16x32_bf16 v[48:51], v[174:177], v[182:185], v[48:51]
	v_mfma_f32_16x16x32_bf16 v[32:35], v[174:177], v[194:197], v[32:35]
	v_mfma_f32_16x16x32_bf16 v[36:39], v[166:169], v[194:197], v[36:39]
	v_mfma_f32_16x16x32_bf16 v[20:23], v[166:169], v[202:205], v[20:23]
	v_mfma_f32_16x16x32_bf16 v[16:19], v[174:177], v[202:205], v[16:19]
	v_mfma_f32_16x16x32_bf16 v[0:3], v[174:177], v[210:213], v[0:3]
	v_mfma_f32_16x16x32_bf16 v[4:7], v[166:169], v[210:213], v[4:7]
	v_mfma_f32_16x16x32_bf16 v[52:55], v[170:173], v[186:189], v[52:55]
	v_mfma_f32_16x16x32_bf16 v[48:51], v[178:181], v[186:189], v[48:51]
	v_mfma_f32_16x16x32_bf16 v[32:35], v[178:181], v[198:201], v[32:35]
	v_mfma_f32_16x16x32_bf16 v[36:39], v[170:173], v[198:201], v[36:39]
	v_mfma_f32_16x16x32_bf16 v[20:23], v[170:173], v[206:209], v[20:23]
	v_mfma_f32_16x16x32_bf16 v[16:19], v[178:181], v[206:209], v[16:19]
	v_mfma_f32_16x16x32_bf16 v[0:3], v[178:181], v[214:217], v[0:3]
	v_mfma_f32_16x16x32_bf16 v[4:7], v[170:173], v[214:217], v[4:7]
	s_setprio 0
	s_waitcnt vmcnt(8)
	s_barrier
	s_add_i32 s62, s62, 2
	s_add_u32 s40, s40, 0x100
	s_addc_u32 s41, s41, 0
	s_add_u32 s60, s60, 0x100
	s_addc_u32 s61, s61, 0
	s_cmp_gt_u32 s62, 29
	s_cbranch_scc0 .LBB0_73
	s_and_b64 vcc, exec, s[24:25]
	s_cbranch_vccz .LBB0_76
	s_barrier

; #define PG8_STAGE(bufoff, gbase, voff) do { _Pragma("unroll") for (int _i = 0; _i < 2; ++_i) \
;         __builtin_amdgcn_global_load_lds((const unsigned*)((const char*)(gbase) + (voff)[_i]), (PG8_LAS unsigned*)(lds + (bufoff) + ldsw + _i * 8192), 16, 0, 0); } while (0)
; #define PG8_LDA(dst, b, h) do { _Pragma("unroll") for (int m = 0; m < 4; ++m) _Pragma("unroll") for (int k = 0; k < 2; ++k) dst[m][k] = *(const PG8_LAS bf16x8*)(lds + PG8_SA(b, h) + aoff + m * 2048 + k * 1024); } while (0)
; #define PG8_MMA(ai, bj, At, Bt) do { __builtin_amdgcn_s_setprio(1); _Pragma("unroll") for (int m = 0; m < 4; ++m) _Pragma("unroll") for (int n = 0; n < 2; ++n) _Pragma("unroll") for (int k = 0; k < 2; ++k) \
;         acc[ai][bj][m][n] = __builtin_amdgcn_mfma_f32_16x16x32_bf16(Bt[n][k], At[m][k], acc[ai][bj][m][n], 0, 0, 0); __builtin_amdgcn_s_setprio(0); } while (0)
; #define PG8_WAIT_V(n) asm volatile("s_waitcnt vmcnt(" #n ")" ::: "memory")
; #define PG8_WAIT_L(n) asm volatile("s_waitcnt lgkmcnt(" #n ")" ::: "memory")
; #define PG8_BAR __builtin_amdgcn_s_barrier()
; #define PG8_SCHED __builtin_amdgcn_sched_barrier(0)
; template <class Epi, class Sched, bool ALIGN_EPI = false, bool SP2 = false>
; __device__ __forceinline__ void gemm_phase(PG8_LAS unsigned char* lds, const Gemm g, const Sched& S, const Epi& E) {
;     ...
;             PG8_WAIT_V(8); PG8_WAIT_L(0); PG8_BAR; PG8_MMA(0, 0, At, B0); PG8_MMA(0, 1, At, B1); PG8_BAR; PG8_SCHED;
;             PG8_LDA(At, 0, 1); PG8_STAGE(PG8_SB(0, 0), b2, voffB); PG8_STAGE(PG8_SB(0, 1), b2 + hstep, voffB); PG8_STAGE(PG8_SA(0, 0), a2, voffA);
;             PG8_WAIT_V(8); PG8_WAIT_L(0); PG8_BAR; PG8_MMA(1, 0, At, B0); PG8_MMA(1, 1, At, B1); PG8_BAR; PG8_SCHED;
.Lvw_4:
	s_waitcnt lgkmcnt(0)
	s_barrier
	s_setprio 1
	s_waitcnt lgkmcnt(0)
	v_mfma_f32_16x16x32_bf16 v[124:127], v[150:153], v[182:185], v[124:127]
	v_mfma_f32_16x16x32_bf16 v[120:123], v[158:161], v[182:185], v[120:123]
	v_mfma_f32_16x16x32_bf16 v[112:115], v[158:161], v[194:197], v[112:115]
	v_mfma_f32_16x16x32_bf16 v[116:119], v[150:153], v[194:197], v[116:119]
	v_mfma_f32_16x16x32_bf16 v[100:103], v[150:153], v[202:205], v[100:103]
	v_mfma_f32_16x16x32_bf16 v[96:99], v[158:161], v[202:205], v[96:99]
	v_mfma_f32_16x16x32_bf16 v[80:83], v[158:161], v[210:213], v[80:83]
	v_mfma_f32_16x16x32_bf16 v[84:87], v[150:153], v[210:213], v[84:87]
	v_mfma_f32_16x16x32_bf16 v[124:127], v[154:157], v[186:189], v[124:127]
	v_mfma_f32_16x16x32_bf16 v[120:123], v[162:165], v[186:189], v[120:123]
	v_mfma_f32_16x16x32_bf16 v[112:115], v[162:165], v[198:201], v[112:115]
	v_mfma_f32_16x16x32_bf16 v[116:119], v[154:157], v[198:201], v[116:119]
	v_mfma_f32_16x16x32_bf16 v[100:103], v[154:157], v[206:209], v[100:103]
	v_mfma_f32_16x16x32_bf16 v[96:99], v[162:165], v[206:209], v[96:99]
	v_mfma_f32_16x16x32_bf16 v[80:83], v[162:165], v[214:217], v[80:83]
	v_mfma_f32_16x16x32_bf16 v[84:87], v[154:157], v[214:217], v[84:87]
	s_setprio 0
	s_setprio 1
	v_mfma_f32_16x16x32_bf16 v[108:111], v[166:169], v[182:185], v[108:111]
	v_mfma_f32_16x16x32_bf16 v[104:107], v[174:177], v[182:185], v[104:107]
	v_mfma_f32_16x16x32_bf16 v[88:91], v[174:177], v[194:197], v[88:91]
	v_mfma_f32_16x16x32_bf16 v[92:95], v[166:169], v[194:197], v[92:95]
	v_mfma_f32_16x16x32_bf16 v[76:79], v[166:169], v[202:205], v[76:79]
	v_mfma_f32_16x16x32_bf16 v[72:75], v[174:177], v[202:205], v[72:75]
	v_mfma_f32_16x16x32_bf16 v[64:67], v[174:177], v[210:213], v[64:67]
	v_mfma_f32_16x16x32_bf16 v[68:71], v[166:169], v[210:213], v[68:71]
	v_mfma_f32_16x16x32_bf16 v[108:111], v[170:173], v[186:189], v[108:111]
	v_mfma_f32_16x16x32_bf16 v[104:107], v[178:181], v[186:189], v[104:107]
	v_mfma_f32_16x16x32_bf16 v[88:91], v[178:181], v[198:201], v[88:91]
	v_mfma_f32_16x16x32_bf16 v[92:95], v[170:173], v[198:201], v[92:95]
	v_mfma_f32_16x16x32_bf16 v[76:79], v[170:173], v[206:209], v[76:79]
	v_mfma_f32_16x16x32_bf16 v[72:75], v[178:181], v[206:209], v[72:75]
	v_mfma_f32_16x16x32_bf16 v[64:67], v[178:181], v[214:217], v[64:67]
	v_mfma_f32_16x16x32_bf16 v[68:71], v[170:173], v[214:217], v[68:71]
	s_setprio 0
	s_waitcnt vmcnt(8)
	s_barrier
	s_add_i32 s38, s55, s2
	v_lshl_add_u64 v[190:191], s[42:43], 0, v[132:133]
	s_mov_b32 m0, s38
	ds_read_b128 v[182:185], v149 offset:16384
	ds_read_b128 v[186:189], v149 offset:17408
	ds_read_b128 v[194:197], v149 offset:18432
	ds_read_b128 v[198:201], v149 offset:19456
	ds_read_b128 v[202:205], v149 offset:20480
	ds_read_b128 v[206:209], v149 offset:21504
	ds_read_b128 v[210:213], v149 offset:22528
	ds_read_b128 v[214:217], v149 offset:23552
	global_load_lds_dwordx4 v[190:191], off
	s_add_i32 m0, s38, 0x2000
	s_add_u32 s38, s42, 0x160000
	v_lshl_add_u64 v[218:219], s[42:43], 0, v[128:129]
	s_addc_u32 s39, s43, 0
	s_add_i32 s63, s56, s2
	global_load_lds_dwordx4 v[218:219], off
	v_lshl_add_u64 v[220:221], s[38:39], 0, v[132:133]
	s_mov_b32 m0, s63
	v_lshl_add_u64 v[222:223], s[44:45], 0, v[130:131]
	global_load_lds_dwordx4 v[220:221], off
	v_lshl_add_u64 v[220:221], s[38:39], 0, v[128:129]
	s_add_i32 m0, s63, 0x2000
	s_nop 0
	global_load_lds_dwordx4 v[220:221], off
	v_lshl_add_u64 v[220:221], s[44:45], 0, v[134:135]
	s_mov_b32 m0, s33
	s_nop 0
	global_load_lds_dwordx4 v[220:221], off
	s_mov_b32 m0, s46
	s_nop 0
	global_load_lds_dwordx4 v[222:223], off
	s_mov_b64 vcc, s[98:99]
	s_cbranch_vccnz .Lvw_5
	s_waitcnt vmcnt(8)
.Lvw_5:
	s_waitcnt lgkmcnt(0)
	s_barrier
	s_setprio 1
	s_waitcnt lgkmcnt(0)
	v_mfma_f32_16x16x32_bf16 v[60:63], v[150:153], v[182:185], v[60:63]
	v_mfma_f32_16x16x32_bf16 v[56:59], v[158:161], v[182:185], v[56:59]
	v_mfma_f32_16x16x32_bf16 v[48:51], v[158:161], v[194:197], v[48:51]
	v_mfma_f32_16x16x32_bf16 v[52:55], v[150:153], v[194:197], v[52:55]
	v_mfma_f32_16x16x32_bf16 v[36:39], v[150:153], v[202:205], v[36:39]
	v_mfma_f32_16x16x32_bf16 v[32:35], v[158:161], v[202:205], v[32:35]
	v_mfma_f32_16x16x32_bf16 v[16:19], v[158:161], v[210:213], v[16:19]
	v_mfma_f32_16x16x32_bf16 v[20:23], v[150:153], v[210:213], v[20:23]
	v_mfma_f32_16x16x32_bf16 v[60:63], v[154:157], v[186:189], v[60:63]
	v_mfma_f32_16x16x32_bf16 v[56:59], v[162:165], v[186:189], v[56:59]
	v_mfma_f32_16x16x32_bf16 v[48:51], v[162:165], v[198:201], v[48:51]
	v_mfma_f32_16x16x32_bf16 v[52:55], v[154:157], v[198:201], v[52:55]
	v_mfma_f32_16x16x32_bf16 v[36:39], v[154:157], v[206:209], v[36:39]
	v_mfma_f32_16x16x32_bf16 v[32:35], v[162:165], v[206:209], v[32:35]
	v_mfma_f32_16x16x32_bf16 v[16:19], v[162:165], v[214:217], v[16:19]
	v_mfma_f32_16x16x32_bf16 v[20:23], v[154:157], v[214:217], v[20:23]
	s_setprio 0
	s_setprio 1
	v_mfma_f32_16x16x32_bf16 v[44:47], v[166:169], v[182:185], v[44:47]
	v_mfma_f32_16x16x32_bf16 v[40:43], v[174:177], v[182:185], v[40:43]
	v_mfma_f32_16x16x32_bf16 v[24:27], v[174:177], v[194:197], v[24:27]
	v_mfma_f32_16x16x32_bf16 v[28:31], v[166:169], v[194:197], v[28:31]
	v_mfma_f32_16x16x32_bf16 v[12:15], v[166:169], v[202:205], v[12:15]
	v_mfma_f32_16x16x32_bf16 v[8:11], v[174:177], v[202:205], v[8:11]
	v_mfma_f32_16x16x32_bf16 v[0:3], v[174:177], v[210:213], v[0:3]
	v_mfma_f32_16x16x32_bf16 v[4:7], v[166:169], v[210:213], v[4:7]
	v_mfma_f32_16x16x32_bf16 v[44:47], v[170:173], v[186:189], v[44:47]
	v_mfma_f32_16x16x32_bf16 v[40:43], v[178:181], v[186:189], v[40:43]
	v_mfma_f32_16x16x32_bf16 v[24:27], v[178:181], v[198:201], v[24:27]
	v_mfma_f32_16x16x32_bf16 v[28:31], v[170:173], v[198:201], v[28:31]
	v_mfma_f32_16x16x32_bf16 v[12:15], v[170:173], v[206:209], v[12:15]
	v_mfma_f32_16x16x32_bf16 v[8:11], v[178:181], v[206:209], v[8:11]
	v_mfma_f32_16x16x32_bf16 v[0:3], v[178:181], v[214:217], v[0:3]
	v_mfma_f32_16x16x32_bf16 v[4:7], v[170:173], v[214:217], v[4:7]
	s_setprio 0
	s_waitcnt vmcnt(8)
	s_barrier
; #define PG8_STAGE(bufoff, gbase, voff) do { _Pragma("unroll") for (int _i = 0; _i < 2; ++_i) \
;         __builtin_amdgcn_global_load_lds((const unsigned*)((const char*)(gbase) + (voff)[_i]), (PG8_LAS unsigned*)(lds + (bufoff) + ldsw + _i * 8192), 16, 0, 0); } while (0)
; #define PG8_LDA(dst, b, h) do { _Pragma("unroll") for (int m = 0; m < 4; ++m) _Pragma("unroll") for (int k = 0; k < 2; ++k) dst[m][k] = *(const PG8_LAS bf16x8*)(lds + PG8_SA(b, h) + aoff + m * 2048 + k * 1024); } while (0)
; #define PG8_LDB(dst, b, h) do { _Pragma("unroll") for (int n = 0; n < 2; ++n) _Pragma("unroll") for (int k = 0; k < 2; ++k) dst[n][k] = *(const PG8_LAS bf16x8*)(lds + PG8_SB(b, h) + boff + n * 2048 + k * 1024); } while (0)
; #define PG8_MMA(ai, bj, At, Bt) do { __builtin_amdgcn_s_setprio(1); _Pragma("unroll") for (int m = 0; m < 4; ++m) _Pragma("unroll") for (int n = 0; n < 2; ++n) _Pragma("unroll") for (int k = 0; k < 2; ++k) \
;         acc[ai][bj][m][n] = __builtin_amdgcn_mfma_f32_16x16x32_bf16(Bt[n][k], At[m][k], acc[ai][bj][m][n], 0, 0, 0); __builtin_amdgcn_s_setprio(0); } while (0)
; #define PG8_WAIT_V(n) asm volatile("s_waitcnt vmcnt(" #n ")" ::: "memory")
; #define PG8_WAIT_L(n) asm volatile("s_waitcnt lgkmcnt(" #n ")" ::: "memory")
; #define PG8_BAR __builtin_amdgcn_s_barrier()
; #define PG8_SCHED __builtin_amdgcn_sched_barrier(0)
; template <class Epi, class Sched, bool ALIGN_EPI = false, bool SP2 = false>
; __device__ __forceinline__ void gemm_phase(PG8_LAS unsigned char* lds, const Gemm g, const Sched& S, const Epi& E) {
;     ...
;             PG8_LDB(B0, 1, 0); PG8_LDB(B1, 1, 1); PG8_SCHED; PG8_LDA(At, 1, 0); PG8_STAGE(PG8_SA(0, 1), a2 + hstep, voffA);
;             PG8_WAIT_V(8); PG8_WAIT_L(0); PG8_BAR; PG8_MMA(0, 0, At, B0); PG8_MMA(0, 1, At, B1); PG8_BAR; PG8_SCHED;
;             PG8_LDA(At, 1, 1); PG8_STAGE(PG8_SB(1, 0), b3, voffB); PG8_STAGE(PG8_SB(1, 1), b3 + hstep, voffB); PG8_STAGE(PG8_SA(1, 0), a3, voffA);
	s_add_i32 s63, 0, 0x18000
	s_add_i32 s64, 0, 0x1c000
	v_add_u32_e32 v162, s63, v145
	v_add_u32_e32 v178, s64, v145
	ds_read_b128 v[150:153], v162
	ds_read_b128 v[154:157], v162 offset:1024
	ds_read_b128 v[158:161], v162 offset:2048
	ds_read_b128 v[162:165], v162 offset:3072
	ds_read_b128 v[166:169], v178
	ds_read_b128 v[170:173], v178 offset:1024
	ds_read_b128 v[174:177], v178 offset:2048
	ds_read_b128 v[178:181], v178 offset:3072
	s_add_u32 s38, s44, 0x160000
	s_addc_u32 s39, s45, 0
	s_mov_b32 m0, s47
	v_lshl_add_u64 v[224:225], s[38:39], 0, v[134:135]
	ds_read_b128 v[182:185], v149 offset:32768
	ds_read_b128 v[186:189], v149 offset:33792
	ds_read_b128 v[194:197], v149 offset:34816
	ds_read_b128 v[198:201], v149 offset:35840
	ds_read_b128 v[202:205], v149 offset:36864
	ds_read_b128 v[206:209], v149 offset:37888
	ds_read_b128 v[210:213], v149 offset:38912
	ds_read_b128 v[214:217], v149 offset:39936
	global_load_lds_dwordx4 v[224:225], off
	v_lshl_add_u64 v[224:225], s[38:39], 0, v[130:131]
	s_mov_b32 m0, s48
	s_nop 0
	global_load_lds_dwordx4 v[224:225], off
	s_mov_b64 vcc, s[98:99]
	s_cbranch_vccnz .Lvw_6
	s_waitcnt vmcnt(8)
.Lvw_6:
	s_waitcnt lgkmcnt(0)
	s_barrier
	s_setprio 1
	s_waitcnt lgkmcnt(0)
	v_mfma_f32_16x16x32_bf16 v[124:127], v[150:153], v[182:185], v[124:127]
	v_mfma_f32_16x16x32_bf16 v[120:123], v[158:161], v[182:185], v[120:123]
	v_mfma_f32_16x16x32_bf16 v[112:115], v[158:161], v[194:197], v[112:115]
	v_mfma_f32_16x16x32_bf16 v[116:119], v[150:153], v[194:197], v[116:119]
	v_mfma_f32_16x16x32_bf16 v[100:103], v[150:153], v[202:205], v[100:103]
	v_mfma_f32_16x16x32_bf16 v[96:99], v[158:161], v[202:205], v[96:99]
	v_mfma_f32_16x16x32_bf16 v[80:83], v[158:161], v[210:213], v[80:83]
	v_mfma_f32_16x16x32_bf16 v[84:87], v[150:153], v[210:213], v[84:87]
	v_mfma_f32_16x16x32_bf16 v[124:127], v[154:157], v[186:189], v[124:127]
	v_mfma_f32_16x16x32_bf16 v[120:123], v[162:165], v[186:189], v[120:123]
	v_mfma_f32_16x16x32_bf16 v[112:115], v[162:165], v[198:201], v[112:115]
	v_mfma_f32_16x16x32_bf16 v[116:119], v[154:157], v[198:201], v[116:119]
	v_mfma_f32_16x16x32_bf16 v[100:103], v[154:157], v[206:209], v[100:103]
	v_mfma_f32_16x16x32_bf16 v[96:99], v[162:165], v[206:209], v[96:99]
	v_mfma_f32_16x16x32_bf16 v[80:83], v[162:165], v[214:217], v[80:83]
	v_mfma_f32_16x16x32_bf16 v[84:87], v[154:157], v[214:217], v[84:87]
	s_setprio 0
	s_setprio 1
	v_mfma_f32_16x16x32_bf16 v[108:111], v[166:169], v[182:185], v[108:111]
	v_mfma_f32_16x16x32_bf16 v[104:107], v[174:177], v[182:185], v[104:107]
	v_mfma_f32_16x16x32_bf16 v[88:91], v[174:177], v[194:197], v[88:91]
	v_mfma_f32_16x16x32_bf16 v[92:95], v[166:169], v[194:197], v[92:95]
	v_mfma_f32_16x16x32_bf16 v[76:79], v[166:169], v[202:205], v[76:79]
	v_mfma_f32_16x16x32_bf16 v[72:75], v[174:177], v[202:205], v[72:75]
	v_mfma_f32_16x16x32_bf16 v[64:67], v[174:177], v[210:213], v[64:67]
	v_mfma_f32_16x16x32_bf16 v[68:71], v[166:169], v[210:213], v[68:71]
	v_mfma_f32_16x16x32_bf16 v[108:111], v[170:173], v[186:189], v[108:111]
	v_mfma_f32_16x16x32_bf16 v[104:107], v[178:181], v[186:189], v[104:107]
	v_mfma_f32_16x16x32_bf16 v[88:91], v[178:181], v[198:201], v[88:91]
	v_mfma_f32_16x16x32_bf16 v[92:95], v[170:173], v[198:201], v[92:95]
	v_mfma_f32_16x16x32_bf16 v[76:79], v[170:173], v[206:209], v[76:79]
	v_mfma_f32_16x16x32_bf16 v[72:75], v[178:181], v[206:209], v[72:75]
	v_mfma_f32_16x16x32_bf16 v[64:67], v[178:181], v[214:217], v[64:67]
	v_mfma_f32_16x16x32_bf16 v[68:71], v[170:173], v[214:217], v[68:71]
	s_setprio 0
	s_waitcnt vmcnt(8)
	s_barrier
	s_add_i32 s38, s63, s2
	v_lshl_add_u64 v[190:191], v[190:191], 0, s[30:31]
	s_mov_b32 m0, s38
	ds_read_b128 v[182:185], v149 offset:49152
	ds_read_b128 v[186:189], v149 offset:50176
	ds_read_b128 v[194:197], v149 offset:51200
	ds_read_b128 v[198:201], v149 offset:52224
	ds_read_b128 v[202:205], v149 offset:53248
	ds_read_b128 v[206:209], v149 offset:54272
	ds_read_b128 v[210:213], v149 offset:55296
	ds_read_b128 v[214:217], v149 offset:56320
	global_load_lds_dwordx4 v[190:191], off
	s_add_i32 m0, s38, 0x2000
	s_add_u32 s38, s42, 0x160080
	v_lshl_add_u64 v[190:191], v[218:219], 0, s[30:31]
	s_addc_u32 s39, s43, 0
	s_add_i32 s42, s64, s2
	global_load_lds_dwordx4 v[190:191], off
	v_lshl_add_u64 v[190:191], s[38:39], 0, v[132:133]
	s_mov_b32 m0, s42
	s_nop 0
	global_load_lds_dwordx4 v[190:191], off
	v_lshl_add_u64 v[190:191], s[38:39], 0, v[128:129]
	s_add_i32 m0, s42, 0x2000
	s_nop 0
	global_load_lds_dwordx4 v[190:191], off
	v_lshl_add_u64 v[190:191], v[220:221], 0, s[30:31]
	s_mov_b32 m0, s50
	s_nop 0
	global_load_lds_dwordx4 v[190:191], off
	v_lshl_add_u64 v[190:191], v[222:223], 0, s[30:31]
	s_mov_b32 m0, s51
	s_nop 0
	global_load_lds_dwordx4 v[190:191], off
	s_mov_b64 vcc, s[98:99]
	s_cbranch_vccnz .Lvw_7
	s_waitcnt vmcnt(8)
; #define PG8_STAGE(bufoff, gbase, voff) do { _Pragma("unroll") for (int _i = 0; _i < 2; ++_i) \
;         __builtin_amdgcn_global_load_lds((const unsigned*)((const char*)(gbase) + (voff)[_i]), (PG8_LAS unsigned*)(lds + (bufoff) + ldsw + _i * 8192), 16, 0, 0); } while (0)
; #define PG8_LDA(dst, b, h) do { _Pragma("unroll") for (int m = 0; m < 4; ++m) _Pragma("unroll") for (int k = 0; k < 2; ++k) dst[m][k] = *(const PG8_LAS bf16x8*)(lds + PG8_SA(b, h) + aoff + m * 2048 + k * 1024); } while (0)
; #define PG8_LDB(dst, b, h) do { _Pragma("unroll") for (int n = 0; n < 2; ++n) _Pragma("unroll") for (int k = 0; k < 2; ++k) dst[n][k] = *(const PG8_LAS bf16x8*)(lds + PG8_SB(b, h) + boff + n * 2048 + k * 1024); } while (0)
; template <class Epi, class Sched, bool ALIGN_EPI = false, bool SP2 = false>
; __device__ __forceinline__ void gemm_phase(PG8_LAS unsigned char* lds, const Gemm g, const Sched& S, const Epi& E) {
;     ...
;             PG8_WAIT_V(8); PG8_WAIT_L(0); PG8_BAR; PG8_MMA(1, 0, At, B0); PG8_MMA(1, 1, At, B1); PG8_BAR; PG8_SCHED;
;             } else {
;             PG8_LDB(B0, 0, 0); PG8_SCHED; PG8_LDA(At, 0, 0); PG8_STAGE(PG8_SA(1, 1), a1 + hstep, voffA);
;             PG8_WAIT_L(8); PG8_BAR; PG8_WAIT_L(0); PG8_MMA(0, 0, At, B0); PG8_BAR; PG8_SCHED;
;             PG8_LDB(B1, 0, 1); PG8_STAGE(PG8_SB(0, 0), b2, voffB);
;             PG8_BAR; PG8_WAIT_L(0); PG8_MMA(0, 1, At, B1); PG8_BAR;
;             PG8_LDA(At, 0, 1); PG8_STAGE(PG8_SA(0, 0), a2, voffA);
;             PG8_BAR; PG8_WAIT_L(0); PG8_MMA(1, 0, At, B0); PG8_BAR; PG8_SCHED;
;             PG8_STAGE(PG8_SB(0, 1), b2 + hstep, voffB);
;             PG8_WAIT_V(6); PG8_BAR; PG8_MMA(1, 1, At, B1); PG8_BAR;
;             PG8_LDB(B0, 1, 0); PG8_SCHED; PG8_LDA(At, 1, 0); PG8_STAGE(PG8_SA(0, 1), a2 + hstep, voffA);
;             PG8_WAIT_L(8); PG8_BAR; PG8_WAIT_L(0); PG8_MMA(0, 0, At, B0); PG8_BAR; PG8_SCHED;
;             PG8_LDB(B1, 1, 1); PG8_STAGE(PG8_SB(1, 0), b3, voffB);
;             PG8_BAR; PG8_WAIT_L(0); PG8_MMA(0, 1, At, B1); PG8_BAR;
;             PG8_LDA(At, 1, 1); PG8_STAGE(PG8_SA(1, 0), a3, voffA);
;             PG8_BAR; PG8_WAIT_L(0); PG8_MMA(1, 0, At, B0); PG8_BAR; PG8_SCHED;
;             PG8_STAGE(PG8_SB(1, 1), b3 + hstep, voffB);
;             PG8_WAIT_V(6); PG8_BAR; PG8_MMA(1, 1, At, B1); PG8_BAR;
;             }
;         }
;         if constexpr (ALIGN_EPI) { if (wr == 0) PG8_BAR; }
.Lvw_7:
	s_waitcnt lgkmcnt(0)
	s_barrier
	s_setprio 1
	s_waitcnt lgkmcnt(0)
	v_mfma_f32_16x16x32_bf16 v[60:63], v[150:153], v[182:185], v[60:63]
	v_mfma_f32_16x16x32_bf16 v[56:59], v[158:161], v[182:185], v[56:59]
	v_mfma_f32_16x16x32_bf16 v[48:51], v[158:161], v[194:197], v[48:51]
	v_mfma_f32_16x16x32_bf16 v[52:55], v[150:153], v[194:197], v[52:55]
	v_mfma_f32_16x16x32_bf16 v[36:39], v[150:153], v[202:205], v[36:39]
	v_mfma_f32_16x16x32_bf16 v[32:35], v[158:161], v[202:205], v[32:35]
	v_mfma_f32_16x16x32_bf16 v[16:19], v[158:161], v[210:213], v[16:19]
	v_mfma_f32_16x16x32_bf16 v[20:23], v[150:153], v[210:213], v[20:23]
	v_mfma_f32_16x16x32_bf16 v[60:63], v[154:157], v[186:189], v[60:63]
	v_mfma_f32_16x16x32_bf16 v[56:59], v[162:165], v[186:189], v[56:59]
	v_mfma_f32_16x16x32_bf16 v[48:51], v[162:165], v[198:201], v[48:51]
	v_mfma_f32_16x16x32_bf16 v[52:55], v[154:157], v[198:201], v[52:55]
	v_mfma_f32_16x16x32_bf16 v[36:39], v[154:157], v[206:209], v[36:39]
	v_mfma_f32_16x16x32_bf16 v[32:35], v[162:165], v[206:209], v[32:35]
	v_mfma_f32_16x16x32_bf16 v[16:19], v[162:165], v[214:217], v[16:19]
	v_mfma_f32_16x16x32_bf16 v[20:23], v[154:157], v[214:217], v[20:23]
	s_setprio 0
	s_setprio 1
	v_mfma_f32_16x16x32_bf16 v[44:47], v[166:169], v[182:185], v[44:47]
	v_mfma_f32_16x16x32_bf16 v[40:43], v[174:177], v[182:185], v[40:43]
	v_mfma_f32_16x16x32_bf16 v[24:27], v[174:177], v[194:197], v[24:27]
	v_mfma_f32_16x16x32_bf16 v[28:31], v[166:169], v[194:197], v[28:31]
	v_mfma_f32_16x16x32_bf16 v[12:15], v[166:169], v[202:205], v[12:15]
	v_mfma_f32_16x16x32_bf16 v[8:11], v[174:177], v[202:205], v[8:11]
	v_mfma_f32_16x16x32_bf16 v[0:3], v[174:177], v[210:213], v[0:3]
	v_mfma_f32_16x16x32_bf16 v[4:7], v[166:169], v[210:213], v[4:7]
	v_mfma_f32_16x16x32_bf16 v[44:47], v[170:173], v[186:189], v[44:47]
	v_mfma_f32_16x16x32_bf16 v[40:43], v[178:181], v[186:189], v[40:43]
	v_mfma_f32_16x16x32_bf16 v[24:27], v[178:181], v[198:201], v[24:27]
	v_mfma_f32_16x16x32_bf16 v[28:31], v[170:173], v[198:201], v[28:31]
	v_mfma_f32_16x16x32_bf16 v[12:15], v[170:173], v[206:209], v[12:15]
	v_mfma_f32_16x16x32_bf16 v[8:11], v[178:181], v[206:209], v[8:11]
	v_mfma_f32_16x16x32_bf16 v[0:3], v[178:181], v[214:217], v[0:3]
	v_mfma_f32_16x16x32_bf16 v[4:7], v[170:173], v[214:217], v[4:7]
	s_setprio 0
	s_waitcnt vmcnt(8)
	s_barrier
	s_add_i32 s62, s62, 2
	s_add_u32 s60, s60, 0x100
	s_addc_u32 s61, s61, 0
	s_cmpk_gt_u32 s62, 0x55
	s_mov_b64 s[38:39], s[40:41]
	s_cbranch_scc0 .LBB0_145
	s_and_b64 vcc, exec, s[34:35]
	s_cbranch_vccz .LBB0_148
	s_barrier

; #define PG8_STAGE(bufoff, gbase, voff) do { _Pragma("unroll") for (int _i = 0; _i < 2; ++_i) \
;         __builtin_amdgcn_global_load_lds((const unsigned*)((const char*)(gbase) + (voff)[_i]), (PG8_LAS unsigned*)(lds + (bufoff) + ldsw + _i * 8192), 16, 0, 0); } while (0)
; #define PG8_LDA(dst, b, h) do { _Pragma("unroll") for (int m = 0; m < 4; ++m) _Pragma("unroll") for (int k = 0; k < 2; ++k) dst[m][k] = *(const PG8_LAS bf16x8*)(lds + PG8_SA(b, h) + aoff + m * 2048 + k * 1024); } while (0)
; #define PG8_MMA(ai, bj, At, Bt) do { __builtin_amdgcn_s_setprio(1); _Pragma("unroll") for (int m = 0; m < 4; ++m) _Pragma("unroll") for (int n = 0; n < 2; ++n) _Pragma("unroll") for (int k = 0; k < 2; ++k) \
;         acc[ai][bj][m][n] = __builtin_amdgcn_mfma_f32_16x16x32_bf16(Bt[n][k], At[m][k], acc[ai][bj][m][n], 0, 0, 0); __builtin_amdgcn_s_setprio(0); } while (0)
; #define PG8_WAIT_V(n) asm volatile("s_waitcnt vmcnt(" #n ")" ::: "memory")
; #define PG8_WAIT_L(n) asm volatile("s_waitcnt lgkmcnt(" #n ")" ::: "memory")
; #define PG8_BAR __builtin_amdgcn_s_barrier()
; #define PG8_SCHED __builtin_amdgcn_sched_barrier(0)
; template <class Epi, class Sched, bool ALIGN_EPI = false, bool SP2 = false>
; __device__ __forceinline__ void gemm_phase(PG8_LAS unsigned char* lds, const Gemm g, const Sched& S, const Epi& E) {
;     ...
;             PG8_WAIT_V(8); PG8_WAIT_L(0); PG8_BAR; PG8_MMA(0, 0, At, B0); PG8_MMA(0, 1, At, B1); PG8_BAR; PG8_SCHED;
;             PG8_LDA(At, 0, 1); PG8_STAGE(PG8_SB(0, 0), b2, voffB); PG8_STAGE(PG8_SB(0, 1), b2 + hstep, voffB); PG8_STAGE(PG8_SA(0, 0), a2, voffA);
;             PG8_WAIT_V(8); PG8_WAIT_L(0); PG8_BAR; PG8_MMA(1, 0, At, B0); PG8_MMA(1, 1, At, B1); PG8_BAR; PG8_SCHED;
.Lvw_8:
	s_waitcnt lgkmcnt(0)
	s_barrier
	s_setprio 1
	s_waitcnt lgkmcnt(0)
	v_mfma_f32_16x16x32_bf16 v[124:127], v[150:153], v[182:185], v[124:127]
	v_mfma_f32_16x16x32_bf16 v[120:123], v[158:161], v[182:185], v[120:123]
	v_mfma_f32_16x16x32_bf16 v[112:115], v[158:161], v[194:197], v[112:115]
	v_mfma_f32_16x16x32_bf16 v[116:119], v[150:153], v[194:197], v[116:119]
	v_mfma_f32_16x16x32_bf16 v[100:103], v[150:153], v[202:205], v[100:103]
	v_mfma_f32_16x16x32_bf16 v[96:99], v[158:161], v[202:205], v[96:99]
	v_mfma_f32_16x16x32_bf16 v[80:83], v[158:161], v[210:213], v[80:83]
	v_mfma_f32_16x16x32_bf16 v[84:87], v[150:153], v[210:213], v[84:87]
	v_mfma_f32_16x16x32_bf16 v[124:127], v[154:157], v[186:189], v[124:127]
	v_mfma_f32_16x16x32_bf16 v[120:123], v[162:165], v[186:189], v[120:123]
	v_mfma_f32_16x16x32_bf16 v[112:115], v[162:165], v[198:201], v[112:115]
	v_mfma_f32_16x16x32_bf16 v[116:119], v[154:157], v[198:201], v[116:119]
	v_mfma_f32_16x16x32_bf16 v[100:103], v[154:157], v[206:209], v[100:103]
	v_mfma_f32_16x16x32_bf16 v[96:99], v[162:165], v[206:209], v[96:99]
	v_mfma_f32_16x16x32_bf16 v[80:83], v[162:165], v[214:217], v[80:83]
	v_mfma_f32_16x16x32_bf16 v[84:87], v[154:157], v[214:217], v[84:87]
	s_setprio 0
	s_setprio 1
	v_mfma_f32_16x16x32_bf16 v[108:111], v[166:169], v[182:185], v[108:111]
	v_mfma_f32_16x16x32_bf16 v[104:107], v[174:177], v[182:185], v[104:107]
	v_mfma_f32_16x16x32_bf16 v[88:91], v[174:177], v[194:197], v[88:91]
	v_mfma_f32_16x16x32_bf16 v[92:95], v[166:169], v[194:197], v[92:95]
	v_mfma_f32_16x16x32_bf16 v[76:79], v[166:169], v[202:205], v[76:79]
	v_mfma_f32_16x16x32_bf16 v[72:75], v[174:177], v[202:205], v[72:75]
	v_mfma_f32_16x16x32_bf16 v[64:67], v[174:177], v[210:213], v[64:67]
	v_mfma_f32_16x16x32_bf16 v[68:71], v[166:169], v[210:213], v[68:71]
	v_mfma_f32_16x16x32_bf16 v[108:111], v[170:173], v[186:189], v[108:111]
	v_mfma_f32_16x16x32_bf16 v[104:107], v[178:181], v[186:189], v[104:107]
	v_mfma_f32_16x16x32_bf16 v[88:91], v[178:181], v[198:201], v[88:91]
	v_mfma_f32_16x16x32_bf16 v[92:95], v[170:173], v[198:201], v[92:95]
	v_mfma_f32_16x16x32_bf16 v[76:79], v[170:173], v[206:209], v[76:79]
	v_mfma_f32_16x16x32_bf16 v[72:75], v[178:181], v[206:209], v[72:75]
	v_mfma_f32_16x16x32_bf16 v[64:67], v[178:181], v[214:217], v[64:67]
	v_mfma_f32_16x16x32_bf16 v[68:71], v[170:173], v[214:217], v[68:71]
	s_setprio 0
	s_waitcnt vmcnt(8)
	s_barrier
	s_add_i32 s58, s49, s33
	v_lshl_add_u64 v[190:191], s[36:37], 0, v[132:133]
	s_mov_b32 m0, s58
	ds_read_b128 v[182:185], v149 offset:16384
	ds_read_b128 v[186:189], v149 offset:17408
	ds_read_b128 v[194:197], v149 offset:18432
	ds_read_b128 v[198:201], v149 offset:19456
	ds_read_b128 v[202:205], v149 offset:20480
	ds_read_b128 v[206:209], v149 offset:21504
	ds_read_b128 v[210:213], v149 offset:22528
	ds_read_b128 v[214:217], v149 offset:23552
	global_load_lds_dwordx4 v[190:191], off
	s_add_i32 m0, s58, 0x2000
	s_add_u32 s58, s36, 0x80000
	v_lshl_add_u64 v[218:219], s[36:37], 0, v[128:129]
	s_addc_u32 s59, s37, 0
	s_add_i32 s60, s50, s33
	global_load_lds_dwordx4 v[218:219], off
	v_lshl_add_u64 v[220:221], s[58:59], 0, v[132:133]
	s_mov_b32 m0, s60
	v_lshl_add_u64 v[222:223], s[38:39], 0, v[130:131]
	global_load_lds_dwordx4 v[220:221], off
	v_lshl_add_u64 v[220:221], s[58:59], 0, v[128:129]
	s_add_i32 m0, s60, 0x2000
	s_nop 0
	global_load_lds_dwordx4 v[220:221], off
	v_lshl_add_u64 v[220:221], s[38:39], 0, v[134:135]
	s_mov_b32 m0, s21
	s_nop 0
	global_load_lds_dwordx4 v[220:221], off
	s_mov_b32 m0, s41
	s_nop 0
	global_load_lds_dwordx4 v[222:223], off
	s_mov_b64 vcc, s[98:99]
	s_cbranch_vccnz .Lvw_9
	s_waitcnt vmcnt(8)
.Lvw_9:
	s_waitcnt lgkmcnt(0)
	s_barrier
	s_setprio 1
	s_waitcnt lgkmcnt(0)
	v_mfma_f32_16x16x32_bf16 v[60:63], v[150:153], v[182:185], v[60:63]
	v_mfma_f32_16x16x32_bf16 v[56:59], v[158:161], v[182:185], v[56:59]
	v_mfma_f32_16x16x32_bf16 v[48:51], v[158:161], v[194:197], v[48:51]
	v_mfma_f32_16x16x32_bf16 v[52:55], v[150:153], v[194:197], v[52:55]
	v_mfma_f32_16x16x32_bf16 v[36:39], v[150:153], v[202:205], v[36:39]
	v_mfma_f32_16x16x32_bf16 v[32:35], v[158:161], v[202:205], v[32:35]
	v_mfma_f32_16x16x32_bf16 v[16:19], v[158:161], v[210:213], v[16:19]
	v_mfma_f32_16x16x32_bf16 v[20:23], v[150:153], v[210:213], v[20:23]
	v_mfma_f32_16x16x32_bf16 v[60:63], v[154:157], v[186:189], v[60:63]
	v_mfma_f32_16x16x32_bf16 v[56:59], v[162:165], v[186:189], v[56:59]
	v_mfma_f32_16x16x32_bf16 v[48:51], v[162:165], v[198:201], v[48:51]
	v_mfma_f32_16x16x32_bf16 v[52:55], v[154:157], v[198:201], v[52:55]
	v_mfma_f32_16x16x32_bf16 v[36:39], v[154:157], v[206:209], v[36:39]
	v_mfma_f32_16x16x32_bf16 v[32:35], v[162:165], v[206:209], v[32:35]
	v_mfma_f32_16x16x32_bf16 v[16:19], v[162:165], v[214:217], v[16:19]
	v_mfma_f32_16x16x32_bf16 v[20:23], v[154:157], v[214:217], v[20:23]
	s_setprio 0
	s_setprio 1
	v_mfma_f32_16x16x32_bf16 v[44:47], v[166:169], v[182:185], v[44:47]
	v_mfma_f32_16x16x32_bf16 v[40:43], v[174:177], v[182:185], v[40:43]
	v_mfma_f32_16x16x32_bf16 v[24:27], v[174:177], v[194:197], v[24:27]
	v_mfma_f32_16x16x32_bf16 v[28:31], v[166:169], v[194:197], v[28:31]
	v_mfma_f32_16x16x32_bf16 v[12:15], v[166:169], v[202:205], v[12:15]
	v_mfma_f32_16x16x32_bf16 v[8:11], v[174:177], v[202:205], v[8:11]
	v_mfma_f32_16x16x32_bf16 v[0:3], v[174:177], v[210:213], v[0:3]
	v_mfma_f32_16x16x32_bf16 v[4:7], v[166:169], v[210:213], v[4:7]
	v_mfma_f32_16x16x32_bf16 v[44:47], v[170:173], v[186:189], v[44:47]
	v_mfma_f32_16x16x32_bf16 v[40:43], v[178:181], v[186:189], v[40:43]
	v_mfma_f32_16x16x32_bf16 v[24:27], v[178:181], v[198:201], v[24:27]
	v_mfma_f32_16x16x32_bf16 v[28:31], v[170:173], v[198:201], v[28:31]
	v_mfma_f32_16x16x32_bf16 v[12:15], v[170:173], v[206:209], v[12:15]
	v_mfma_f32_16x16x32_bf16 v[8:11], v[178:181], v[206:209], v[8:11]
	v_mfma_f32_16x16x32_bf16 v[0:3], v[178:181], v[214:217], v[0:3]
	v_mfma_f32_16x16x32_bf16 v[4:7], v[170:173], v[214:217], v[4:7]
	s_setprio 0
	s_waitcnt vmcnt(8)
	s_barrier
; #define PG8_STAGE(bufoff, gbase, voff) do { _Pragma("unroll") for (int _i = 0; _i < 2; ++_i) \
;         __builtin_amdgcn_global_load_lds((const unsigned*)((const char*)(gbase) + (voff)[_i]), (PG8_LAS unsigned*)(lds + (bufoff) + ldsw + _i * 8192), 16, 0, 0); } while (0)
; #define PG8_LDA(dst, b, h) do { _Pragma("unroll") for (int m = 0; m < 4; ++m) _Pragma("unroll") for (int k = 0; k < 2; ++k) dst[m][k] = *(const PG8_LAS bf16x8*)(lds + PG8_SA(b, h) + aoff + m * 2048 + k * 1024); } while (0)
; #define PG8_LDB(dst, b, h) do { _Pragma("unroll") for (int n = 0; n < 2; ++n) _Pragma("unroll") for (int k = 0; k < 2; ++k) dst[n][k] = *(const PG8_LAS bf16x8*)(lds + PG8_SB(b, h) + boff + n * 2048 + k * 1024); } while (0)
; #define PG8_MMA(ai, bj, At, Bt) do { __builtin_amdgcn_s_setprio(1); _Pragma("unroll") for (int m = 0; m < 4; ++m) _Pragma("unroll") for (int n = 0; n < 2; ++n) _Pragma("unroll") for (int k = 0; k < 2; ++k) \
;         acc[ai][bj][m][n] = __builtin_amdgcn_mfma_f32_16x16x32_bf16(Bt[n][k], At[m][k], acc[ai][bj][m][n], 0, 0, 0); __builtin_amdgcn_s_setprio(0); } while (0)
; #define PG8_WAIT_V(n) asm volatile("s_waitcnt vmcnt(" #n ")" ::: "memory")
; #define PG8_WAIT_L(n) asm volatile("s_waitcnt lgkmcnt(" #n ")" ::: "memory")
; #define PG8_BAR __builtin_amdgcn_s_barrier()
; #define PG8_SCHED __builtin_amdgcn_sched_barrier(0)
; template <class Epi, class Sched, bool ALIGN_EPI = false, bool SP2 = false>
; __device__ __forceinline__ void gemm_phase(PG8_LAS unsigned char* lds, const Gemm g, const Sched& S, const Epi& E) {
;     ...
;             PG8_LDB(B0, 1, 0); PG8_LDB(B1, 1, 1); PG8_SCHED; PG8_LDA(At, 1, 0); PG8_STAGE(PG8_SA(0, 1), a2 + hstep, voffA);
;             PG8_WAIT_V(8); PG8_WAIT_L(0); PG8_BAR; PG8_MMA(0, 0, At, B0); PG8_MMA(0, 1, At, B1); PG8_BAR; PG8_SCHED;
;             PG8_LDA(At, 1, 1); PG8_STAGE(PG8_SB(1, 0), b3, voffB); PG8_STAGE(PG8_SB(1, 1), b3 + hstep, voffB); PG8_STAGE(PG8_SA(1, 0), a3, voffA);
	s_add_i32 s58, 0, 0x18000
	s_add_i32 s59, 0, 0x1c000
	v_add_u32_e32 v162, s58, v145
	v_add_u32_e32 v178, s59, v145
	ds_read_b128 v[150:153], v162
	ds_read_b128 v[154:157], v162 offset:1024
	ds_read_b128 v[158:161], v162 offset:2048
	ds_read_b128 v[162:165], v162 offset:3072
	ds_read_b128 v[166:169], v178
	ds_read_b128 v[170:173], v178 offset:1024
	ds_read_b128 v[174:177], v178 offset:2048
	ds_read_b128 v[178:181], v178 offset:3072
	s_add_u32 s38, s38, 0x80000
	s_addc_u32 s39, s39, 0
	s_mov_b32 m0, s42
	v_lshl_add_u64 v[224:225], s[38:39], 0, v[134:135]
	ds_read_b128 v[182:185], v149 offset:32768
	ds_read_b128 v[186:189], v149 offset:33792
	ds_read_b128 v[194:197], v149 offset:34816
	ds_read_b128 v[198:201], v149 offset:35840
	ds_read_b128 v[202:205], v149 offset:36864
	ds_read_b128 v[206:209], v149 offset:37888
	ds_read_b128 v[210:213], v149 offset:38912
	ds_read_b128 v[214:217], v149 offset:39936
	global_load_lds_dwordx4 v[224:225], off
	v_lshl_add_u64 v[224:225], s[38:39], 0, v[130:131]
	s_mov_b32 m0, s43
	s_nop 0
	global_load_lds_dwordx4 v[224:225], off
	s_mov_b64 vcc, s[98:99]
	s_cbranch_vccnz .Lvw_10
	s_waitcnt vmcnt(8)
.Lvw_10:
	s_waitcnt lgkmcnt(0)
	s_barrier
	s_setprio 1
	s_waitcnt lgkmcnt(0)
	v_mfma_f32_16x16x32_bf16 v[124:127], v[150:153], v[182:185], v[124:127]
	v_mfma_f32_16x16x32_bf16 v[120:123], v[158:161], v[182:185], v[120:123]
	v_mfma_f32_16x16x32_bf16 v[112:115], v[158:161], v[194:197], v[112:115]
	v_mfma_f32_16x16x32_bf16 v[116:119], v[150:153], v[194:197], v[116:119]
	v_mfma_f32_16x16x32_bf16 v[100:103], v[150:153], v[202:205], v[100:103]
	v_mfma_f32_16x16x32_bf16 v[96:99], v[158:161], v[202:205], v[96:99]
	v_mfma_f32_16x16x32_bf16 v[80:83], v[158:161], v[210:213], v[80:83]
	v_mfma_f32_16x16x32_bf16 v[84:87], v[150:153], v[210:213], v[84:87]
	v_mfma_f32_16x16x32_bf16 v[124:127], v[154:157], v[186:189], v[124:127]
	v_mfma_f32_16x16x32_bf16 v[120:123], v[162:165], v[186:189], v[120:123]
	v_mfma_f32_16x16x32_bf16 v[112:115], v[162:165], v[198:201], v[112:115]
	v_mfma_f32_16x16x32_bf16 v[116:119], v[154:157], v[198:201], v[116:119]
	v_mfma_f32_16x16x32_bf16 v[100:103], v[154:157], v[206:209], v[100:103]
	v_mfma_f32_16x16x32_bf16 v[96:99], v[162:165], v[206:209], v[96:99]
	v_mfma_f32_16x16x32_bf16 v[80:83], v[162:165], v[214:217], v[80:83]
	v_mfma_f32_16x16x32_bf16 v[84:87], v[154:157], v[214:217], v[84:87]
	s_setprio 0
	s_setprio 1
	v_mfma_f32_16x16x32_bf16 v[108:111], v[166:169], v[182:185], v[108:111]
	v_mfma_f32_16x16x32_bf16 v[104:107], v[174:177], v[182:185], v[104:107]
	v_mfma_f32_16x16x32_bf16 v[88:91], v[174:177], v[194:197], v[88:91]
	v_mfma_f32_16x16x32_bf16 v[92:95], v[166:169], v[194:197], v[92:95]
	v_mfma_f32_16x16x32_bf16 v[76:79], v[166:169], v[202:205], v[76:79]
	v_mfma_f32_16x16x32_bf16 v[72:75], v[174:177], v[202:205], v[72:75]
	v_mfma_f32_16x16x32_bf16 v[64:67], v[174:177], v[210:213], v[64:67]
	v_mfma_f32_16x16x32_bf16 v[68:71], v[166:169], v[210:213], v[68:71]
	v_mfma_f32_16x16x32_bf16 v[108:111], v[170:173], v[186:189], v[108:111]
	v_mfma_f32_16x16x32_bf16 v[104:107], v[178:181], v[186:189], v[104:107]
	v_mfma_f32_16x16x32_bf16 v[88:91], v[178:181], v[198:201], v[88:91]
	v_mfma_f32_16x16x32_bf16 v[92:95], v[170:173], v[198:201], v[92:95]
	v_mfma_f32_16x16x32_bf16 v[76:79], v[170:173], v[206:209], v[76:79]
	v_mfma_f32_16x16x32_bf16 v[72:75], v[178:181], v[206:209], v[72:75]
	v_mfma_f32_16x16x32_bf16 v[64:67], v[178:181], v[214:217], v[64:67]
	v_mfma_f32_16x16x32_bf16 v[68:71], v[170:173], v[214:217], v[68:71]
	s_setprio 0
	s_waitcnt vmcnt(8)
	s_barrier
	s_add_i32 s38, s58, s33
	v_lshl_add_u64 v[190:191], v[190:191], 0, s[6:7]
	s_mov_b32 m0, s38
	ds_read_b128 v[182:185], v149 offset:49152
	ds_read_b128 v[186:189], v149 offset:50176
	ds_read_b128 v[194:197], v149 offset:51200
	ds_read_b128 v[198:201], v149 offset:52224
	ds_read_b128 v[202:205], v149 offset:53248
	ds_read_b128 v[206:209], v149 offset:54272
	ds_read_b128 v[210:213], v149 offset:55296
	ds_read_b128 v[214:217], v149 offset:56320
	global_load_lds_dwordx4 v[190:191], off
	s_add_i32 m0, s38, 0x2000
	s_add_u32 s36, s36, 0x80080
	v_lshl_add_u64 v[190:191], v[218:219], 0, s[6:7]
	s_addc_u32 s37, s37, 0
	s_add_i32 s38, s59, s33
	global_load_lds_dwordx4 v[190:191], off
	v_lshl_add_u64 v[190:191], s[36:37], 0, v[132:133]
	s_mov_b32 m0, s38
	s_nop 0
	global_load_lds_dwordx4 v[190:191], off
	v_lshl_add_u64 v[190:191], s[36:37], 0, v[128:129]
	s_add_i32 m0, s38, 0x2000
	s_nop 0
	global_load_lds_dwordx4 v[190:191], off
	v_lshl_add_u64 v[190:191], v[220:221], 0, s[6:7]
	s_mov_b32 m0, s45
	s_nop 0
	global_load_lds_dwordx4 v[190:191], off
	v_lshl_add_u64 v[190:191], v[222:223], 0, s[6:7]
	s_mov_b32 m0, s46
	s_nop 0
	global_load_lds_dwordx4 v[190:191], off
	s_mov_b64 vcc, s[98:99]
	s_cbranch_vccnz .Lvw_11
	s_waitcnt vmcnt(8)
; #define PG8_STAGE(bufoff, gbase, voff) do { _Pragma("unroll") for (int _i = 0; _i < 2; ++_i) \
;         __builtin_amdgcn_global_load_lds((const unsigned*)((const char*)(gbase) + (voff)[_i]), (PG8_LAS unsigned*)(lds + (bufoff) + ldsw + _i * 8192), 16, 0, 0); } while (0)
; #define PG8_LDA(dst, b, h) do { _Pragma("unroll") for (int m = 0; m < 4; ++m) _Pragma("unroll") for (int k = 0; k < 2; ++k) dst[m][k] = *(const PG8_LAS bf16x8*)(lds + PG8_SA(b, h) + aoff + m * 2048 + k * 1024); } while (0)
; #define PG8_LDB(dst, b, h) do { _Pragma("unroll") for (int n = 0; n < 2; ++n) _Pragma("unroll") for (int k = 0; k < 2; ++k) dst[n][k] = *(const PG8_LAS bf16x8*)(lds + PG8_SB(b, h) + boff + n * 2048 + k * 1024); } while (0)
; template <class Epi, class Sched, bool ALIGN_EPI = false, bool SP2 = false>
; __device__ __forceinline__ void gemm_phase(PG8_LAS unsigned char* lds, const Gemm g, const Sched& S, const Epi& E) {
;     ...
;             PG8_WAIT_V(8); PG8_WAIT_L(0); PG8_BAR; PG8_MMA(1, 0, At, B0); PG8_MMA(1, 1, At, B1); PG8_BAR; PG8_SCHED;
;             } else {
;             PG8_LDB(B0, 0, 0); PG8_SCHED; PG8_LDA(At, 0, 0); PG8_STAGE(PG8_SA(1, 1), a1 + hstep, voffA);
;             PG8_WAIT_L(8); PG8_BAR; PG8_WAIT_L(0); PG8_MMA(0, 0, At, B0); PG8_BAR; PG8_SCHED;
;             PG8_LDB(B1, 0, 1); PG8_STAGE(PG8_SB(0, 0), b2, voffB);
;             PG8_BAR; PG8_WAIT_L(0); PG8_MMA(0, 1, At, B1); PG8_BAR;
;             PG8_LDA(At, 0, 1); PG8_STAGE(PG8_SA(0, 0), a2, voffA);
;             PG8_BAR; PG8_WAIT_L(0); PG8_MMA(1, 0, At, B0); PG8_BAR; PG8_SCHED;
;             PG8_STAGE(PG8_SB(0, 1), b2 + hstep, voffB);
;             PG8_WAIT_V(6); PG8_BAR; PG8_MMA(1, 1, At, B1); PG8_BAR;
;             PG8_LDB(B0, 1, 0); PG8_SCHED; PG8_LDA(At, 1, 0); PG8_STAGE(PG8_SA(0, 1), a2 + hstep, voffA);
;             PG8_WAIT_L(8); PG8_BAR; PG8_WAIT_L(0); PG8_MMA(0, 0, At, B0); PG8_BAR; PG8_SCHED;
;             PG8_LDB(B1, 1, 1); PG8_STAGE(PG8_SB(1, 0), b3, voffB);
;             PG8_BAR; PG8_WAIT_L(0); PG8_MMA(0, 1, At, B1); PG8_BAR;
;             PG8_LDA(At, 1, 1); PG8_STAGE(PG8_SA(1, 0), a3, voffA);
;             PG8_BAR; PG8_WAIT_L(0); PG8_MMA(1, 0, At, B0); PG8_BAR; PG8_SCHED;
;             PG8_STAGE(PG8_SB(1, 1), b3 + hstep, voffB);
;             PG8_WAIT_V(6); PG8_BAR; PG8_MMA(1, 1, At, B1); PG8_BAR;
;             }
;         }
;         if constexpr (ALIGN_EPI) { if (wr == 0) PG8_BAR; }
.Lvw_11:
	s_waitcnt lgkmcnt(0)
	s_barrier
	s_setprio 1
	s_waitcnt lgkmcnt(0)
	v_mfma_f32_16x16x32_bf16 v[60:63], v[150:153], v[182:185], v[60:63]
	v_mfma_f32_16x16x32_bf16 v[56:59], v[158:161], v[182:185], v[56:59]
	v_mfma_f32_16x16x32_bf16 v[48:51], v[158:161], v[194:197], v[48:51]
	v_mfma_f32_16x16x32_bf16 v[52:55], v[150:153], v[194:197], v[52:55]
	v_mfma_f32_16x16x32_bf16 v[36:39], v[150:153], v[202:205], v[36:39]
	v_mfma_f32_16x16x32_bf16 v[32:35], v[158:161], v[202:205], v[32:35]
	v_mfma_f32_16x16x32_bf16 v[16:19], v[158:161], v[210:213], v[16:19]
	v_mfma_f32_16x16x32_bf16 v[20:23], v[150:153], v[210:213], v[20:23]
	v_mfma_f32_16x16x32_bf16 v[60:63], v[154:157], v[186:189], v[60:63]
	v_mfma_f32_16x16x32_bf16 v[56:59], v[162:165], v[186:189], v[56:59]
	v_mfma_f32_16x16x32_bf16 v[48:51], v[162:165], v[198:201], v[48:51]
	v_mfma_f32_16x16x32_bf16 v[52:55], v[154:157], v[198:201], v[52:55]
	v_mfma_f32_16x16x32_bf16 v[36:39], v[154:157], v[206:209], v[36:39]
	v_mfma_f32_16x16x32_bf16 v[32:35], v[162:165], v[206:209], v[32:35]
	v_mfma_f32_16x16x32_bf16 v[16:19], v[162:165], v[214:217], v[16:19]
	v_mfma_f32_16x16x32_bf16 v[20:23], v[154:157], v[214:217], v[20:23]
	s_setprio 0
	s_setprio 1
	v_mfma_f32_16x16x32_bf16 v[44:47], v[166:169], v[182:185], v[44:47]
	v_mfma_f32_16x16x32_bf16 v[40:43], v[174:177], v[182:185], v[40:43]
	v_mfma_f32_16x16x32_bf16 v[24:27], v[174:177], v[194:197], v[24:27]
	v_mfma_f32_16x16x32_bf16 v[28:31], v[166:169], v[194:197], v[28:31]
	v_mfma_f32_16x16x32_bf16 v[12:15], v[166:169], v[202:205], v[12:15]
	v_mfma_f32_16x16x32_bf16 v[8:11], v[174:177], v[202:205], v[8:11]
	v_mfma_f32_16x16x32_bf16 v[0:3], v[174:177], v[210:213], v[0:3]
	v_mfma_f32_16x16x32_bf16 v[4:7], v[166:169], v[210:213], v[4:7]
	v_mfma_f32_16x16x32_bf16 v[44:47], v[170:173], v[186:189], v[44:47]
	v_mfma_f32_16x16x32_bf16 v[40:43], v[178:181], v[186:189], v[40:43]
	v_mfma_f32_16x16x32_bf16 v[24:27], v[178:181], v[198:201], v[24:27]
	v_mfma_f32_16x16x32_bf16 v[28:31], v[170:173], v[198:201], v[28:31]
	v_mfma_f32_16x16x32_bf16 v[12:15], v[170:173], v[206:209], v[12:15]
	v_mfma_f32_16x16x32_bf16 v[8:11], v[178:181], v[206:209], v[8:11]
	v_mfma_f32_16x16x32_bf16 v[0:3], v[178:181], v[214:217], v[0:3]
	v_mfma_f32_16x16x32_bf16 v[4:7], v[170:173], v[214:217], v[4:7]
	s_setprio 0
	s_waitcnt vmcnt(8)
	s_barrier
	s_add_i32 s57, s57, 2
	s_add_u32 s34, s34, 0x100
	s_addc_u32 s35, s35, 0
	s_add_u32 s55, s55, 0x100
	s_addc_u32 s56, s56, 0
	s_cmp_gt_u32 s57, 29
	s_cbranch_scc0 .LBB0_277
	s_and_b64 vcc, exec, s[8:9]
	s_cbranch_vccz .LBB0_280
	s_barrier

; #define PG8_STAGE(bufoff, gbase, voff) do { _Pragma("unroll") for (int _i = 0; _i < 2; ++_i) \
;         __builtin_amdgcn_global_load_lds((const unsigned*)((const char*)(gbase) + (voff)[_i]), (PG8_LAS unsigned*)(lds + (bufoff) + ldsw + _i * 8192), 16, 0, 0); } while (0)
; #define PG8_LDA(dst, b, h) do { _Pragma("unroll") for (int m = 0; m < 4; ++m) _Pragma("unroll") for (int k = 0; k < 2; ++k) dst[m][k] = *(const PG8_LAS bf16x8*)(lds + PG8_SA(b, h) + aoff + m * 2048 + k * 1024); } while (0)
; #define PG8_MMA(ai, bj, At, Bt) do { __builtin_amdgcn_s_setprio(1); _Pragma("unroll") for (int m = 0; m < 4; ++m) _Pragma("unroll") for (int n = 0; n < 2; ++n) _Pragma("unroll") for (int k = 0; k < 2; ++k) \
;         acc[ai][bj][m][n] = __builtin_amdgcn_mfma_f32_16x16x32_bf16(Bt[n][k], At[m][k], acc[ai][bj][m][n], 0, 0, 0); __builtin_amdgcn_s_setprio(0); } while (0)
; #define PG8_WAIT_V(n) asm volatile("s_waitcnt vmcnt(" #n ")" ::: "memory")
; #define PG8_WAIT_L(n) asm volatile("s_waitcnt lgkmcnt(" #n ")" ::: "memory")
; #define PG8_BAR __builtin_amdgcn_s_barrier()
; #define PG8_SCHED __builtin_amdgcn_sched_barrier(0)
; template <class Epi, class Sched, bool ALIGN_EPI = false, bool SP2 = false>
; __device__ __forceinline__ void gemm_phase(PG8_LAS unsigned char* lds, const Gemm g, const Sched& S, const Epi& E) {
;     ...
;             PG8_WAIT_V(8); PG8_WAIT_L(0); PG8_BAR; PG8_MMA(0, 0, At, B0); PG8_MMA(0, 1, At, B1); PG8_BAR; PG8_SCHED;
;             PG8_LDA(At, 0, 1); PG8_STAGE(PG8_SB(0, 0), b2, voffB); PG8_STAGE(PG8_SB(0, 1), b2 + hstep, voffB); PG8_STAGE(PG8_SA(0, 0), a2, voffA);
;             PG8_WAIT_V(8); PG8_WAIT_L(0); PG8_BAR; PG8_MMA(1, 0, At, B0); PG8_MMA(1, 1, At, B1); PG8_BAR; PG8_SCHED;
.Lvw_12:
	s_waitcnt lgkmcnt(0)
	s_barrier
	s_setprio 1
	s_waitcnt lgkmcnt(0)
	v_mfma_f32_16x16x32_bf16 v[124:127], v[152:155], v[194:197], v[124:127]
	v_mfma_f32_16x16x32_bf16 v[120:123], v[160:163], v[194:197], v[120:123]
	v_mfma_f32_16x16x32_bf16 v[108:111], v[160:163], v[202:205], v[108:111]
	v_mfma_f32_16x16x32_bf16 v[116:119], v[152:155], v[202:205], v[116:119]
	v_mfma_f32_16x16x32_bf16 v[100:103], v[152:155], v[210:213], v[100:103]
	v_mfma_f32_16x16x32_bf16 v[92:95], v[160:163], v[210:213], v[92:95]
	v_mfma_f32_16x16x32_bf16 v[76:79], v[160:163], v[218:221], v[76:79]
	v_mfma_f32_16x16x32_bf16 v[84:87], v[152:155], v[218:221], v[84:87]
	v_mfma_f32_16x16x32_bf16 v[124:127], v[156:159], v[198:201], v[124:127]
	v_mfma_f32_16x16x32_bf16 v[120:123], v[164:167], v[198:201], v[120:123]
	v_mfma_f32_16x16x32_bf16 v[108:111], v[164:167], v[206:209], v[108:111]
	v_mfma_f32_16x16x32_bf16 v[116:119], v[156:159], v[206:209], v[116:119]
	v_mfma_f32_16x16x32_bf16 v[100:103], v[156:159], v[214:217], v[100:103]
	v_mfma_f32_16x16x32_bf16 v[92:95], v[164:167], v[214:217], v[92:95]
	v_mfma_f32_16x16x32_bf16 v[76:79], v[164:167], v[222:225], v[76:79]
	v_mfma_f32_16x16x32_bf16 v[84:87], v[156:159], v[222:225], v[84:87]
	s_setprio 0
	s_setprio 1
	v_mfma_f32_16x16x32_bf16 v[112:115], v[174:177], v[194:197], v[112:115]
	v_mfma_f32_16x16x32_bf16 v[104:107], v[182:185], v[194:197], v[104:107]
	v_mfma_f32_16x16x32_bf16 v[88:91], v[182:185], v[202:205], v[88:91]
	v_mfma_f32_16x16x32_bf16 v[96:99], v[174:177], v[202:205], v[96:99]
	v_mfma_f32_16x16x32_bf16 v[80:83], v[174:177], v[210:213], v[80:83]
	v_mfma_f32_16x16x32_bf16 v[72:75], v[182:185], v[210:213], v[72:75]
	v_mfma_f32_16x16x32_bf16 v[64:67], v[182:185], v[218:221], v[64:67]
	v_mfma_f32_16x16x32_bf16 v[68:71], v[174:177], v[218:221], v[68:71]
	v_mfma_f32_16x16x32_bf16 v[112:115], v[178:181], v[198:201], v[112:115]
	v_mfma_f32_16x16x32_bf16 v[104:107], v[186:189], v[198:201], v[104:107]
	v_mfma_f32_16x16x32_bf16 v[88:91], v[186:189], v[206:209], v[88:91]
	v_mfma_f32_16x16x32_bf16 v[96:99], v[178:181], v[206:209], v[96:99]
	v_mfma_f32_16x16x32_bf16 v[80:83], v[178:181], v[214:217], v[80:83]
	v_mfma_f32_16x16x32_bf16 v[72:75], v[186:189], v[214:217], v[72:75]
	v_mfma_f32_16x16x32_bf16 v[64:67], v[186:189], v[222:225], v[64:67]
	v_mfma_f32_16x16x32_bf16 v[68:71], v[178:181], v[222:225], v[68:71]
	s_setprio 0
	s_waitcnt vmcnt(8)
	s_barrier
	s_add_i32 s61, s55, s23
	v_lshl_add_u64 v[168:169], s[38:39], 0, v[132:133]
	s_mov_b32 m0, s61
	ds_read_b128 v[194:197], v173 offset:16384
	ds_read_b128 v[198:201], v173 offset:17408
	ds_read_b128 v[202:205], v173 offset:18432
	ds_read_b128 v[206:209], v173 offset:19456
	ds_read_b128 v[210:213], v173 offset:20480
	ds_read_b128 v[214:217], v173 offset:21504
	ds_read_b128 v[218:221], v173 offset:22528
	ds_read_b128 v[222:225], v173 offset:23552
	global_load_lds_dwordx4 v[168:169], off
	s_add_i32 m0, s61, 0x2000
	s_add_u32 s62, s38, 0x20000
	v_lshl_add_u64 v[190:191], s[38:39], 0, v[128:129]
	s_addc_u32 s63, s39, 0
	s_add_i32 s61, s56, s23
	global_load_lds_dwordx4 v[190:191], off
	v_lshl_add_u64 v[226:227], s[62:63], 0, v[132:133]
	s_mov_b32 m0, s61
	v_lshl_add_u64 v[228:229], s[40:41], 0, v[130:131]
	global_load_lds_dwordx4 v[226:227], off
	v_lshl_add_u64 v[226:227], s[62:63], 0, v[128:129]
	s_add_i32 m0, s61, 0x2000
	s_nop 0
	global_load_lds_dwordx4 v[226:227], off
	v_lshl_add_u64 v[226:227], s[40:41], 0, v[134:135]
	s_mov_b32 m0, s46
	s_nop 0
	global_load_lds_dwordx4 v[226:227], off
	s_mov_b32 m0, s47
	s_nop 0
	global_load_lds_dwordx4 v[228:229], off
	s_mov_b64 vcc, s[98:99]
	s_cbranch_vccnz .Lvw_13
	s_waitcnt vmcnt(8)
.Lvw_13:
	s_waitcnt lgkmcnt(0)
	s_barrier
	s_setprio 1
	s_waitcnt lgkmcnt(0)
	v_mfma_f32_16x16x32_bf16 v[60:63], v[152:155], v[194:197], v[60:63]
	v_mfma_f32_16x16x32_bf16 v[56:59], v[160:163], v[194:197], v[56:59]
	v_mfma_f32_16x16x32_bf16 v[44:47], v[160:163], v[202:205], v[44:47]
	v_mfma_f32_16x16x32_bf16 v[52:55], v[152:155], v[202:205], v[52:55]
	v_mfma_f32_16x16x32_bf16 v[36:39], v[152:155], v[210:213], v[36:39]
	v_mfma_f32_16x16x32_bf16 v[28:31], v[160:163], v[210:213], v[28:31]
	v_mfma_f32_16x16x32_bf16 v[12:15], v[160:163], v[218:221], v[12:15]
	v_mfma_f32_16x16x32_bf16 v[20:23], v[152:155], v[218:221], v[20:23]
	v_mfma_f32_16x16x32_bf16 v[60:63], v[156:159], v[198:201], v[60:63]
	v_mfma_f32_16x16x32_bf16 v[56:59], v[164:167], v[198:201], v[56:59]
	v_mfma_f32_16x16x32_bf16 v[44:47], v[164:167], v[206:209], v[44:47]
	v_mfma_f32_16x16x32_bf16 v[52:55], v[156:159], v[206:209], v[52:55]
	v_mfma_f32_16x16x32_bf16 v[36:39], v[156:159], v[214:217], v[36:39]
	v_mfma_f32_16x16x32_bf16 v[28:31], v[164:167], v[214:217], v[28:31]
	v_mfma_f32_16x16x32_bf16 v[12:15], v[164:167], v[222:225], v[12:15]
	v_mfma_f32_16x16x32_bf16 v[20:23], v[156:159], v[222:225], v[20:23]
	s_setprio 0
	s_setprio 1
	v_mfma_f32_16x16x32_bf16 v[48:51], v[174:177], v[194:197], v[48:51]
	v_mfma_f32_16x16x32_bf16 v[40:43], v[182:185], v[194:197], v[40:43]
	v_mfma_f32_16x16x32_bf16 v[24:27], v[182:185], v[202:205], v[24:27]
	v_mfma_f32_16x16x32_bf16 v[32:35], v[174:177], v[202:205], v[32:35]
	v_mfma_f32_16x16x32_bf16 v[16:19], v[174:177], v[210:213], v[16:19]
	v_mfma_f32_16x16x32_bf16 v[8:11], v[182:185], v[210:213], v[8:11]
	v_mfma_f32_16x16x32_bf16 v[0:3], v[182:185], v[218:221], v[0:3]
	v_mfma_f32_16x16x32_bf16 v[4:7], v[174:177], v[218:221], v[4:7]
	v_mfma_f32_16x16x32_bf16 v[48:51], v[178:181], v[198:201], v[48:51]
	v_mfma_f32_16x16x32_bf16 v[40:43], v[186:189], v[198:201], v[40:43]
	v_mfma_f32_16x16x32_bf16 v[24:27], v[186:189], v[206:209], v[24:27]
	v_mfma_f32_16x16x32_bf16 v[32:35], v[178:181], v[206:209], v[32:35]
	v_mfma_f32_16x16x32_bf16 v[16:19], v[178:181], v[214:217], v[16:19]
	v_mfma_f32_16x16x32_bf16 v[8:11], v[186:189], v[214:217], v[8:11]
	v_mfma_f32_16x16x32_bf16 v[0:3], v[186:189], v[222:225], v[0:3]
	v_mfma_f32_16x16x32_bf16 v[4:7], v[178:181], v[222:225], v[4:7]
	s_setprio 0
	s_waitcnt vmcnt(8)
	s_barrier
; #define PG8_STAGE(bufoff, gbase, voff) do { _Pragma("unroll") for (int _i = 0; _i < 2; ++_i) \
;         __builtin_amdgcn_global_load_lds((const unsigned*)((const char*)(gbase) + (voff)[_i]), (PG8_LAS unsigned*)(lds + (bufoff) + ldsw + _i * 8192), 16, 0, 0); } while (0)
; #define PG8_LDA(dst, b, h) do { _Pragma("unroll") for (int m = 0; m < 4; ++m) _Pragma("unroll") for (int k = 0; k < 2; ++k) dst[m][k] = *(const PG8_LAS bf16x8*)(lds + PG8_SA(b, h) + aoff + m * 2048 + k * 1024); } while (0)
; #define PG8_LDB(dst, b, h) do { _Pragma("unroll") for (int n = 0; n < 2; ++n) _Pragma("unroll") for (int k = 0; k < 2; ++k) dst[n][k] = *(const PG8_LAS bf16x8*)(lds + PG8_SB(b, h) + boff + n * 2048 + k * 1024); } while (0)
; #define PG8_MMA(ai, bj, At, Bt) do { __builtin_amdgcn_s_setprio(1); _Pragma("unroll") for (int m = 0; m < 4; ++m) _Pragma("unroll") for (int n = 0; n < 2; ++n) _Pragma("unroll") for (int k = 0; k < 2; ++k) \
;         acc[ai][bj][m][n] = __builtin_amdgcn_mfma_f32_16x16x32_bf16(Bt[n][k], At[m][k], acc[ai][bj][m][n], 0, 0, 0); __builtin_amdgcn_s_setprio(0); } while (0)
; #define PG8_WAIT_V(n) asm volatile("s_waitcnt vmcnt(" #n ")" ::: "memory")
; #define PG8_WAIT_L(n) asm volatile("s_waitcnt lgkmcnt(" #n ")" ::: "memory")
; #define PG8_BAR __builtin_amdgcn_s_barrier()
; #define PG8_SCHED __builtin_amdgcn_sched_barrier(0)
; template <class Epi, class Sched, bool ALIGN_EPI = false, bool SP2 = false>
; __device__ __forceinline__ void gemm_phase(PG8_LAS unsigned char* lds, const Gemm g, const Sched& S, const Epi& E) {
;     ...
;             PG8_LDB(B0, 1, 0); PG8_LDB(B1, 1, 1); PG8_SCHED; PG8_LDA(At, 1, 0); PG8_STAGE(PG8_SA(0, 1), a2 + hstep, voffA);
;             PG8_WAIT_V(8); PG8_WAIT_L(0); PG8_BAR; PG8_MMA(0, 0, At, B0); PG8_MMA(0, 1, At, B1); PG8_BAR; PG8_SCHED;
;             PG8_LDA(At, 1, 1); PG8_STAGE(PG8_SB(1, 0), b3, voffB); PG8_STAGE(PG8_SB(1, 1), b3 + hstep, voffB); PG8_STAGE(PG8_SA(1, 0), a3, voffA);
	s_add_i32 s61, 0, 0x18000
	v_add_u32_e32 v136, s61, v170
	s_add_i32 s62, 0, 0x1c000
	ds_read_b128 v[152:155], v136
	ds_read_b128 v[156:159], v136 offset:1024
	ds_read_b128 v[160:163], v136 offset:2048
	ds_read_b128 v[164:167], v136 offset:3072
	v_add_u32_e32 v136, s62, v170
	ds_read_b128 v[174:177], v136
	ds_read_b128 v[178:181], v136 offset:1024
	ds_read_b128 v[182:185], v136 offset:2048
	ds_read_b128 v[186:189], v136 offset:3072
	s_add_u32 s40, s40, 0x20000
	s_addc_u32 s41, s41, 0
	s_mov_b32 m0, s48
	v_lshl_add_u64 v[230:231], s[40:41], 0, v[134:135]
	ds_read_b128 v[194:197], v173 offset:32768
	ds_read_b128 v[198:201], v173 offset:33792
	ds_read_b128 v[202:205], v173 offset:34816
	ds_read_b128 v[206:209], v173 offset:35840
	ds_read_b128 v[210:213], v173 offset:36864
	ds_read_b128 v[214:217], v173 offset:37888
	ds_read_b128 v[218:221], v173 offset:38912
	ds_read_b128 v[222:225], v173 offset:39936
	global_load_lds_dwordx4 v[230:231], off
	v_lshl_add_u64 v[230:231], s[40:41], 0, v[130:131]
	s_mov_b32 m0, s49
	s_nop 0
	global_load_lds_dwordx4 v[230:231], off
	s_mov_b64 vcc, s[98:99]
	s_cbranch_vccnz .Lvw_14
	s_waitcnt vmcnt(8)
.Lvw_14:
	s_waitcnt lgkmcnt(0)
	s_barrier
	s_setprio 1
	s_waitcnt lgkmcnt(0)
	v_mfma_f32_16x16x32_bf16 v[124:127], v[152:155], v[194:197], v[124:127]
	v_mfma_f32_16x16x32_bf16 v[120:123], v[160:163], v[194:197], v[120:123]
	v_mfma_f32_16x16x32_bf16 v[108:111], v[160:163], v[202:205], v[108:111]
	v_mfma_f32_16x16x32_bf16 v[116:119], v[152:155], v[202:205], v[116:119]
	v_mfma_f32_16x16x32_bf16 v[100:103], v[152:155], v[210:213], v[100:103]
	v_mfma_f32_16x16x32_bf16 v[92:95], v[160:163], v[210:213], v[92:95]
	v_mfma_f32_16x16x32_bf16 v[76:79], v[160:163], v[218:221], v[76:79]
	v_mfma_f32_16x16x32_bf16 v[84:87], v[152:155], v[218:221], v[84:87]
	v_mfma_f32_16x16x32_bf16 v[124:127], v[156:159], v[198:201], v[124:127]
	v_mfma_f32_16x16x32_bf16 v[120:123], v[164:167], v[198:201], v[120:123]
	v_mfma_f32_16x16x32_bf16 v[108:111], v[164:167], v[206:209], v[108:111]
	v_mfma_f32_16x16x32_bf16 v[116:119], v[156:159], v[206:209], v[116:119]
	v_mfma_f32_16x16x32_bf16 v[100:103], v[156:159], v[214:217], v[100:103]
	v_mfma_f32_16x16x32_bf16 v[92:95], v[164:167], v[214:217], v[92:95]
	v_mfma_f32_16x16x32_bf16 v[76:79], v[164:167], v[222:225], v[76:79]
	v_mfma_f32_16x16x32_bf16 v[84:87], v[156:159], v[222:225], v[84:87]
	s_setprio 0
	s_setprio 1
	v_mfma_f32_16x16x32_bf16 v[112:115], v[174:177], v[194:197], v[112:115]
	v_mfma_f32_16x16x32_bf16 v[104:107], v[182:185], v[194:197], v[104:107]
	v_mfma_f32_16x16x32_bf16 v[88:91], v[182:185], v[202:205], v[88:91]
	v_mfma_f32_16x16x32_bf16 v[96:99], v[174:177], v[202:205], v[96:99]
	v_mfma_f32_16x16x32_bf16 v[80:83], v[174:177], v[210:213], v[80:83]
	v_mfma_f32_16x16x32_bf16 v[72:75], v[182:185], v[210:213], v[72:75]
	v_mfma_f32_16x16x32_bf16 v[64:67], v[182:185], v[218:221], v[64:67]
	v_mfma_f32_16x16x32_bf16 v[68:71], v[174:177], v[218:221], v[68:71]
	v_mfma_f32_16x16x32_bf16 v[112:115], v[178:181], v[198:201], v[112:115]
	v_mfma_f32_16x16x32_bf16 v[104:107], v[186:189], v[198:201], v[104:107]
	v_mfma_f32_16x16x32_bf16 v[88:91], v[186:189], v[206:209], v[88:91]
	v_mfma_f32_16x16x32_bf16 v[96:99], v[178:181], v[206:209], v[96:99]
	v_mfma_f32_16x16x32_bf16 v[80:83], v[178:181], v[214:217], v[80:83]
	v_mfma_f32_16x16x32_bf16 v[72:75], v[186:189], v[214:217], v[72:75]
	v_mfma_f32_16x16x32_bf16 v[64:67], v[186:189], v[222:225], v[64:67]
	v_mfma_f32_16x16x32_bf16 v[68:71], v[178:181], v[222:225], v[68:71]
	s_setprio 0
	s_waitcnt vmcnt(8)
	s_barrier
	s_add_i32 s40, s61, s23
	v_lshl_add_u64 v[168:169], v[168:169], 0, s[10:11]
	s_mov_b32 m0, s40
	ds_read_b128 v[194:197], v173 offset:49152
	ds_read_b128 v[198:201], v173 offset:50176
	ds_read_b128 v[202:205], v173 offset:51200
	ds_read_b128 v[206:209], v173 offset:52224
	ds_read_b128 v[210:213], v173 offset:53248
	ds_read_b128 v[214:217], v173 offset:54272
	ds_read_b128 v[218:221], v173 offset:55296
	ds_read_b128 v[222:225], v173 offset:56320
	global_load_lds_dwordx4 v[168:169], off
	s_add_i32 m0, s40, 0x2000
	s_add_u32 s38, s38, 0x20080
	v_lshl_add_u64 v[168:169], v[190:191], 0, s[10:11]
	s_addc_u32 s39, s39, 0
	s_add_i32 s40, s62, s23
	global_load_lds_dwordx4 v[168:169], off
	v_lshl_add_u64 v[168:169], s[38:39], 0, v[132:133]
	s_mov_b32 m0, s40
	s_nop 0
	global_load_lds_dwordx4 v[168:169], off
	v_lshl_add_u64 v[168:169], s[38:39], 0, v[128:129]
	s_add_i32 m0, s40, 0x2000
	s_nop 0
	global_load_lds_dwordx4 v[168:169], off
	v_lshl_add_u64 v[168:169], v[226:227], 0, s[10:11]
	s_mov_b32 m0, s50
	s_nop 0
	global_load_lds_dwordx4 v[168:169], off
	v_lshl_add_u64 v[168:169], v[228:229], 0, s[10:11]
	s_mov_b32 m0, s51
	s_nop 0
	global_load_lds_dwordx4 v[168:169], off
	s_mov_b64 vcc, s[98:99]
	s_cbranch_vccnz .Lvw_15
	s_waitcnt vmcnt(8)
; #define PG8_STAGE(bufoff, gbase, voff) do { _Pragma("unroll") for (int _i = 0; _i < 2; ++_i) \
;         __builtin_amdgcn_global_load_lds((const unsigned*)((const char*)(gbase) + (voff)[_i]), (PG8_LAS unsigned*)(lds + (bufoff) + ldsw + _i * 8192), 16, 0, 0); } while (0)
; #define PG8_LDA(dst, b, h) do { _Pragma("unroll") for (int m = 0; m < 4; ++m) _Pragma("unroll") for (int k = 0; k < 2; ++k) dst[m][k] = *(const PG8_LAS bf16x8*)(lds + PG8_SA(b, h) + aoff + m * 2048 + k * 1024); } while (0)
; #define PG8_LDB(dst, b, h) do { _Pragma("unroll") for (int n = 0; n < 2; ++n) _Pragma("unroll") for (int k = 0; k < 2; ++k) dst[n][k] = *(const PG8_LAS bf16x8*)(lds + PG8_SB(b, h) + boff + n * 2048 + k * 1024); } while (0)
; template <class Epi, class Sched, bool ALIGN_EPI = false, bool SP2 = false>
; __device__ __forceinline__ void gemm_phase(PG8_LAS unsigned char* lds, const Gemm g, const Sched& S, const Epi& E) {
;     ...
;             PG8_WAIT_V(8); PG8_WAIT_L(0); PG8_BAR; PG8_MMA(1, 0, At, B0); PG8_MMA(1, 1, At, B1); PG8_BAR; PG8_SCHED;
;             } else {
;             PG8_LDB(B0, 0, 0); PG8_SCHED; PG8_LDA(At, 0, 0); PG8_STAGE(PG8_SA(1, 1), a1 + hstep, voffA);
;             PG8_WAIT_L(8); PG8_BAR; PG8_WAIT_L(0); PG8_MMA(0, 0, At, B0); PG8_BAR; PG8_SCHED;
;             PG8_LDB(B1, 0, 1); PG8_STAGE(PG8_SB(0, 0), b2, voffB);
;             PG8_BAR; PG8_WAIT_L(0); PG8_MMA(0, 1, At, B1); PG8_BAR;
;             PG8_LDA(At, 0, 1); PG8_STAGE(PG8_SA(0, 0), a2, voffA);
;             PG8_BAR; PG8_WAIT_L(0); PG8_MMA(1, 0, At, B0); PG8_BAR; PG8_SCHED;
;             PG8_STAGE(PG8_SB(0, 1), b2 + hstep, voffB);
;             PG8_WAIT_V(6); PG8_BAR; PG8_MMA(1, 1, At, B1); PG8_BAR;
;             PG8_LDB(B0, 1, 0); PG8_SCHED; PG8_LDA(At, 1, 0); PG8_STAGE(PG8_SA(0, 1), a2 + hstep, voffA);
;             PG8_WAIT_L(8); PG8_BAR; PG8_WAIT_L(0); PG8_MMA(0, 0, At, B0); PG8_BAR; PG8_SCHED;
;             PG8_LDB(B1, 1, 1); PG8_STAGE(PG8_SB(1, 0), b3, voffB);
;             PG8_BAR; PG8_WAIT_L(0); PG8_MMA(0, 1, At, B1); PG8_BAR;
;             PG8_LDA(At, 1, 1); PG8_STAGE(PG8_SA(1, 0), a3, voffA);
;             PG8_BAR; PG8_WAIT_L(0); PG8_MMA(1, 0, At, B0); PG8_BAR; PG8_SCHED;
;             PG8_STAGE(PG8_SB(1, 1), b3 + hstep, voffB);
;             PG8_WAIT_V(6); PG8_BAR; PG8_MMA(1, 1, At, B1); PG8_BAR;
;             }
;         }
;         if constexpr (ALIGN_EPI) { if (wr == 0) PG8_BAR; }
.Lvw_15:
	s_waitcnt lgkmcnt(0)
	s_barrier
	s_setprio 1
	s_waitcnt lgkmcnt(0)
	v_mfma_f32_16x16x32_bf16 v[60:63], v[152:155], v[194:197], v[60:63]
	v_mfma_f32_16x16x32_bf16 v[56:59], v[160:163], v[194:197], v[56:59]
	v_mfma_f32_16x16x32_bf16 v[44:47], v[160:163], v[202:205], v[44:47]
	v_mfma_f32_16x16x32_bf16 v[52:55], v[152:155], v[202:205], v[52:55]
	v_mfma_f32_16x16x32_bf16 v[36:39], v[152:155], v[210:213], v[36:39]
	v_mfma_f32_16x16x32_bf16 v[28:31], v[160:163], v[210:213], v[28:31]
	v_mfma_f32_16x16x32_bf16 v[12:15], v[160:163], v[218:221], v[12:15]
	v_mfma_f32_16x16x32_bf16 v[20:23], v[152:155], v[218:221], v[20:23]
	v_mfma_f32_16x16x32_bf16 v[60:63], v[156:159], v[198:201], v[60:63]
	v_mfma_f32_16x16x32_bf16 v[56:59], v[164:167], v[198:201], v[56:59]
	v_mfma_f32_16x16x32_bf16 v[44:47], v[164:167], v[206:209], v[44:47]
	v_mfma_f32_16x16x32_bf16 v[52:55], v[156:159], v[206:209], v[52:55]
	v_mfma_f32_16x16x32_bf16 v[36:39], v[156:159], v[214:217], v[36:39]
	v_mfma_f32_16x16x32_bf16 v[28:31], v[164:167], v[214:217], v[28:31]
	v_mfma_f32_16x16x32_bf16 v[12:15], v[164:167], v[222:225], v[12:15]
	v_mfma_f32_16x16x32_bf16 v[20:23], v[156:159], v[222:225], v[20:23]
	s_setprio 0
	s_setprio 1
	v_mfma_f32_16x16x32_bf16 v[48:51], v[174:177], v[194:197], v[48:51]
	v_mfma_f32_16x16x32_bf16 v[40:43], v[182:185], v[194:197], v[40:43]
	v_mfma_f32_16x16x32_bf16 v[24:27], v[182:185], v[202:205], v[24:27]
	v_mfma_f32_16x16x32_bf16 v[32:35], v[174:177], v[202:205], v[32:35]
	v_mfma_f32_16x16x32_bf16 v[16:19], v[174:177], v[210:213], v[16:19]
	v_mfma_f32_16x16x32_bf16 v[8:11], v[182:185], v[210:213], v[8:11]
	v_mfma_f32_16x16x32_bf16 v[0:3], v[182:185], v[218:221], v[0:3]
	v_mfma_f32_16x16x32_bf16 v[4:7], v[174:177], v[218:221], v[4:7]
	v_mfma_f32_16x16x32_bf16 v[48:51], v[178:181], v[198:201], v[48:51]
	v_mfma_f32_16x16x32_bf16 v[40:43], v[186:189], v[198:201], v[40:43]
	v_mfma_f32_16x16x32_bf16 v[24:27], v[186:189], v[206:209], v[24:27]
	v_mfma_f32_16x16x32_bf16 v[32:35], v[178:181], v[206:209], v[32:35]
	v_mfma_f32_16x16x32_bf16 v[16:19], v[178:181], v[214:217], v[16:19]
	v_mfma_f32_16x16x32_bf16 v[8:11], v[186:189], v[214:217], v[8:11]
	v_mfma_f32_16x16x32_bf16 v[0:3], v[186:189], v[222:225], v[0:3]
	v_mfma_f32_16x16x32_bf16 v[4:7], v[178:181], v[222:225], v[4:7]
	s_setprio 0
	s_waitcnt vmcnt(8)
	s_barrier
	s_add_i32 s60, s60, 2
	s_add_u32 s36, s36, 0x100
	s_addc_u32 s37, s37, 0
	s_add_u32 s33, s33, 0x100
	s_addc_u32 s59, s59, 0
	s_cmp_gt_u32 s60, 5
	s_cbranch_scc0 .LBB0_402
	s_and_b64 vcc, exec, s[20:21]
	s_cbranch_vccz .LBB0_405
	s_barrier

; #define PG8_STAGE(bufoff, gbase, voff) do { _Pragma("unroll") for (int _i = 0; _i < 2; ++_i) \
;         __builtin_amdgcn_global_load_lds((const unsigned*)((const char*)(gbase) + (voff)[_i]), (PG8_LAS unsigned*)(lds + (bufoff) + ldsw + _i * 8192), 16, 0, 0); } while (0)
; #define PG8_LDA(dst, b, h) do { _Pragma("unroll") for (int m = 0; m < 4; ++m) _Pragma("unroll") for (int k = 0; k < 2; ++k) dst[m][k] = *(const PG8_LAS bf16x8*)(lds + PG8_SA(b, h) + aoff + m * 2048 + k * 1024); } while (0)
; #define PG8_MMA(ai, bj, At, Bt) do { __builtin_amdgcn_s_setprio(1); _Pragma("unroll") for (int m = 0; m < 4; ++m) _Pragma("unroll") for (int n = 0; n < 2; ++n) _Pragma("unroll") for (int k = 0; k < 2; ++k) \
;         acc[ai][bj][m][n] = __builtin_amdgcn_mfma_f32_16x16x32_bf16(Bt[n][k], At[m][k], acc[ai][bj][m][n], 0, 0, 0); __builtin_amdgcn_s_setprio(0); } while (0)
; #define PG8_WAIT_V(n) asm volatile("s_waitcnt vmcnt(" #n ")" ::: "memory")
; #define PG8_WAIT_L(n) asm volatile("s_waitcnt lgkmcnt(" #n ")" ::: "memory")
; #define PG8_BAR __builtin_amdgcn_s_barrier()
; #define PG8_SCHED __builtin_amdgcn_sched_barrier(0)
; template <class Epi, class Sched, bool ALIGN_EPI = false, bool SP2 = false>
; __device__ __forceinline__ void gemm_phase(PG8_LAS unsigned char* lds, const Gemm g, const Sched& S, const Epi& E) {
;     ...
;             PG8_WAIT_V(8); PG8_WAIT_L(0); PG8_BAR; PG8_MMA(0, 0, At, B0); PG8_MMA(0, 1, At, B1); PG8_BAR; PG8_SCHED;
;             PG8_LDA(At, 0, 1); PG8_STAGE(PG8_SB(0, 0), b2, voffB); PG8_STAGE(PG8_SB(0, 1), b2 + hstep, voffB); PG8_STAGE(PG8_SA(0, 0), a2, voffA);
;             PG8_WAIT_V(8); PG8_WAIT_L(0); PG8_BAR; PG8_MMA(1, 0, At, B0); PG8_MMA(1, 1, At, B1); PG8_BAR; PG8_SCHED;
.Lvw_16:
	s_waitcnt lgkmcnt(0)
	s_barrier
	s_setprio 1
	s_waitcnt lgkmcnt(0)
	v_mfma_f32_16x16x32_bf16 v[124:127], v[150:153], v[182:185], v[124:127]
	v_mfma_f32_16x16x32_bf16 v[120:123], v[158:161], v[182:185], v[120:123]
	v_mfma_f32_16x16x32_bf16 v[112:115], v[158:161], v[194:197], v[112:115]
	v_mfma_f32_16x16x32_bf16 v[116:119], v[150:153], v[194:197], v[116:119]
	v_mfma_f32_16x16x32_bf16 v[100:103], v[150:153], v[202:205], v[100:103]
	v_mfma_f32_16x16x32_bf16 v[96:99], v[158:161], v[202:205], v[96:99]
	v_mfma_f32_16x16x32_bf16 v[80:83], v[158:161], v[210:213], v[80:83]
	v_mfma_f32_16x16x32_bf16 v[84:87], v[150:153], v[210:213], v[84:87]
	v_mfma_f32_16x16x32_bf16 v[124:127], v[154:157], v[186:189], v[124:127]
	v_mfma_f32_16x16x32_bf16 v[120:123], v[162:165], v[186:189], v[120:123]
	v_mfma_f32_16x16x32_bf16 v[112:115], v[162:165], v[198:201], v[112:115]
	v_mfma_f32_16x16x32_bf16 v[116:119], v[154:157], v[198:201], v[116:119]
	v_mfma_f32_16x16x32_bf16 v[100:103], v[154:157], v[206:209], v[100:103]
	v_mfma_f32_16x16x32_bf16 v[96:99], v[162:165], v[206:209], v[96:99]
	v_mfma_f32_16x16x32_bf16 v[80:83], v[162:165], v[214:217], v[80:83]
	v_mfma_f32_16x16x32_bf16 v[84:87], v[154:157], v[214:217], v[84:87]
	s_setprio 0
	s_setprio 1
	v_mfma_f32_16x16x32_bf16 v[108:111], v[166:169], v[182:185], v[108:111]
	v_mfma_f32_16x16x32_bf16 v[104:107], v[174:177], v[182:185], v[104:107]
	v_mfma_f32_16x16x32_bf16 v[88:91], v[174:177], v[194:197], v[88:91]
	v_mfma_f32_16x16x32_bf16 v[92:95], v[166:169], v[194:197], v[92:95]
	v_mfma_f32_16x16x32_bf16 v[76:79], v[166:169], v[202:205], v[76:79]
	v_mfma_f32_16x16x32_bf16 v[72:75], v[174:177], v[202:205], v[72:75]
	v_mfma_f32_16x16x32_bf16 v[64:67], v[174:177], v[210:213], v[64:67]
	v_mfma_f32_16x16x32_bf16 v[68:71], v[166:169], v[210:213], v[68:71]
	v_mfma_f32_16x16x32_bf16 v[108:111], v[170:173], v[186:189], v[108:111]
	v_mfma_f32_16x16x32_bf16 v[104:107], v[178:181], v[186:189], v[104:107]
	v_mfma_f32_16x16x32_bf16 v[88:91], v[178:181], v[198:201], v[88:91]
	v_mfma_f32_16x16x32_bf16 v[92:95], v[170:173], v[198:201], v[92:95]
	v_mfma_f32_16x16x32_bf16 v[76:79], v[170:173], v[206:209], v[76:79]
	v_mfma_f32_16x16x32_bf16 v[72:75], v[178:181], v[206:209], v[72:75]
	v_mfma_f32_16x16x32_bf16 v[64:67], v[178:181], v[214:217], v[64:67]
	v_mfma_f32_16x16x32_bf16 v[68:71], v[170:173], v[214:217], v[68:71]
	s_setprio 0
	s_waitcnt vmcnt(8)
	s_barrier
	s_add_i32 s59, s51, s3
	v_lshl_add_u64 v[190:191], s[38:39], 0, v[130:131]
	s_mov_b32 m0, s59
	ds_read_b128 v[182:185], v149 offset:16384
	ds_read_b128 v[186:189], v149 offset:17408
	ds_read_b128 v[194:197], v149 offset:18432
	ds_read_b128 v[198:201], v149 offset:19456
	ds_read_b128 v[202:205], v149 offset:20480
	ds_read_b128 v[206:209], v149 offset:21504
	ds_read_b128 v[210:213], v149 offset:22528
	ds_read_b128 v[214:217], v149 offset:23552
	global_load_lds_dwordx4 v[190:191], off
	s_add_i32 m0, s59, 0x2000
	s_add_u32 s60, s38, 0x20000
	v_lshl_add_u64 v[218:219], s[38:39], 0, v[134:135]
	s_addc_u32 s61, s39, 0
	s_add_i32 s59, s52, s3
	global_load_lds_dwordx4 v[218:219], off
	v_lshl_add_u64 v[220:221], s[60:61], 0, v[130:131]
	s_mov_b32 m0, s59
	v_lshl_add_u64 v[222:223], s[40:41], 0, v[132:133]
	global_load_lds_dwordx4 v[220:221], off
	v_lshl_add_u64 v[220:221], s[60:61], 0, v[134:135]
	s_add_i32 m0, s59, 0x2000
	s_nop 0
	global_load_lds_dwordx4 v[220:221], off
	v_lshl_add_u64 v[220:221], s[40:41], 0, v[128:129]
	s_mov_b32 m0, s23
	s_nop 0
	global_load_lds_dwordx4 v[220:221], off
	s_mov_b32 m0, s43
	s_nop 0
	global_load_lds_dwordx4 v[222:223], off
	s_mov_b64 vcc, s[98:99]
	s_cbranch_vccnz .Lvw_17
	s_waitcnt vmcnt(8)
.Lvw_17:
	s_waitcnt lgkmcnt(0)
	s_barrier
	s_setprio 1
	s_waitcnt lgkmcnt(0)
	v_mfma_f32_16x16x32_bf16 v[60:63], v[150:153], v[182:185], v[60:63]
	v_mfma_f32_16x16x32_bf16 v[56:59], v[158:161], v[182:185], v[56:59]
	v_mfma_f32_16x16x32_bf16 v[48:51], v[158:161], v[194:197], v[48:51]
	v_mfma_f32_16x16x32_bf16 v[52:55], v[150:153], v[194:197], v[52:55]
	v_mfma_f32_16x16x32_bf16 v[36:39], v[150:153], v[202:205], v[36:39]
	v_mfma_f32_16x16x32_bf16 v[32:35], v[158:161], v[202:205], v[32:35]
	v_mfma_f32_16x16x32_bf16 v[16:19], v[158:161], v[210:213], v[16:19]
	v_mfma_f32_16x16x32_bf16 v[20:23], v[150:153], v[210:213], v[20:23]
	v_mfma_f32_16x16x32_bf16 v[60:63], v[154:157], v[186:189], v[60:63]
	v_mfma_f32_16x16x32_bf16 v[56:59], v[162:165], v[186:189], v[56:59]
	v_mfma_f32_16x16x32_bf16 v[48:51], v[162:165], v[198:201], v[48:51]
	v_mfma_f32_16x16x32_bf16 v[52:55], v[154:157], v[198:201], v[52:55]
	v_mfma_f32_16x16x32_bf16 v[36:39], v[154:157], v[206:209], v[36:39]
	v_mfma_f32_16x16x32_bf16 v[32:35], v[162:165], v[206:209], v[32:35]
	v_mfma_f32_16x16x32_bf16 v[16:19], v[162:165], v[214:217], v[16:19]
	v_mfma_f32_16x16x32_bf16 v[20:23], v[154:157], v[214:217], v[20:23]
	s_setprio 0
	s_setprio 1
	v_mfma_f32_16x16x32_bf16 v[44:47], v[166:169], v[182:185], v[44:47]
	v_mfma_f32_16x16x32_bf16 v[40:43], v[174:177], v[182:185], v[40:43]
	v_mfma_f32_16x16x32_bf16 v[24:27], v[174:177], v[194:197], v[24:27]
	v_mfma_f32_16x16x32_bf16 v[28:31], v[166:169], v[194:197], v[28:31]
	v_mfma_f32_16x16x32_bf16 v[12:15], v[166:169], v[202:205], v[12:15]
	v_mfma_f32_16x16x32_bf16 v[8:11], v[174:177], v[202:205], v[8:11]
	v_mfma_f32_16x16x32_bf16 v[0:3], v[174:177], v[210:213], v[0:3]
	v_mfma_f32_16x16x32_bf16 v[4:7], v[166:169], v[210:213], v[4:7]
	v_mfma_f32_16x16x32_bf16 v[44:47], v[170:173], v[186:189], v[44:47]
	v_mfma_f32_16x16x32_bf16 v[40:43], v[178:181], v[186:189], v[40:43]
	v_mfma_f32_16x16x32_bf16 v[24:27], v[178:181], v[198:201], v[24:27]
	v_mfma_f32_16x16x32_bf16 v[28:31], v[170:173], v[198:201], v[28:31]
	v_mfma_f32_16x16x32_bf16 v[12:15], v[170:173], v[206:209], v[12:15]
	v_mfma_f32_16x16x32_bf16 v[8:11], v[178:181], v[206:209], v[8:11]
	v_mfma_f32_16x16x32_bf16 v[0:3], v[178:181], v[214:217], v[0:3]
	v_mfma_f32_16x16x32_bf16 v[4:7], v[170:173], v[214:217], v[4:7]
	s_setprio 0
	s_waitcnt vmcnt(8)
	s_barrier
; #define PG8_STAGE(bufoff, gbase, voff) do { _Pragma("unroll") for (int _i = 0; _i < 2; ++_i) \
;         __builtin_amdgcn_global_load_lds((const unsigned*)((const char*)(gbase) + (voff)[_i]), (PG8_LAS unsigned*)(lds + (bufoff) + ldsw + _i * 8192), 16, 0, 0); } while (0)
; #define PG8_LDA(dst, b, h) do { _Pragma("unroll") for (int m = 0; m < 4; ++m) _Pragma("unroll") for (int k = 0; k < 2; ++k) dst[m][k] = *(const PG8_LAS bf16x8*)(lds + PG8_SA(b, h) + aoff + m * 2048 + k * 1024); } while (0)
; #define PG8_LDB(dst, b, h) do { _Pragma("unroll") for (int n = 0; n < 2; ++n) _Pragma("unroll") for (int k = 0; k < 2; ++k) dst[n][k] = *(const PG8_LAS bf16x8*)(lds + PG8_SB(b, h) + boff + n * 2048 + k * 1024); } while (0)
; #define PG8_MMA(ai, bj, At, Bt) do { __builtin_amdgcn_s_setprio(1); _Pragma("unroll") for (int m = 0; m < 4; ++m) _Pragma("unroll") for (int n = 0; n < 2; ++n) _Pragma("unroll") for (int k = 0; k < 2; ++k) \
;         acc[ai][bj][m][n] = __builtin_amdgcn_mfma_f32_16x16x32_bf16(Bt[n][k], At[m][k], acc[ai][bj][m][n], 0, 0, 0); __builtin_amdgcn_s_setprio(0); } while (0)
; #define PG8_WAIT_V(n) asm volatile("s_waitcnt vmcnt(" #n ")" ::: "memory")
; #define PG8_WAIT_L(n) asm volatile("s_waitcnt lgkmcnt(" #n ")" ::: "memory")
; #define PG8_BAR __builtin_amdgcn_s_barrier()
; #define PG8_SCHED __builtin_amdgcn_sched_barrier(0)
; template <class Epi, class Sched, bool ALIGN_EPI = false, bool SP2 = false>
; __device__ __forceinline__ void gemm_phase(PG8_LAS unsigned char* lds, const Gemm g, const Sched& S, const Epi& E) {
;     ...
;             PG8_LDB(B0, 1, 0); PG8_LDB(B1, 1, 1); PG8_SCHED; PG8_LDA(At, 1, 0); PG8_STAGE(PG8_SA(0, 1), a2 + hstep, voffA);
;             PG8_WAIT_V(8); PG8_WAIT_L(0); PG8_BAR; PG8_MMA(0, 0, At, B0); PG8_MMA(0, 1, At, B1); PG8_BAR; PG8_SCHED;
;             PG8_LDA(At, 1, 1); PG8_STAGE(PG8_SB(1, 0), b3, voffB); PG8_STAGE(PG8_SB(1, 1), b3 + hstep, voffB); PG8_STAGE(PG8_SA(1, 0), a3, voffA);
	s_add_i32 s59, 0, 0x18000
	s_add_i32 s60, 0, 0x1c000
	v_add_u32_e32 v162, s59, v146
	v_add_u32_e32 v178, s60, v146
	ds_read_b128 v[150:153], v162
	ds_read_b128 v[154:157], v162 offset:1024
	ds_read_b128 v[158:161], v162 offset:2048
	ds_read_b128 v[162:165], v162 offset:3072
	ds_read_b128 v[166:169], v178
	ds_read_b128 v[170:173], v178 offset:1024
	ds_read_b128 v[174:177], v178 offset:2048
	ds_read_b128 v[178:181], v178 offset:3072
	s_add_u32 s40, s40, 0x20000
	s_addc_u32 s41, s41, 0
	s_mov_b32 m0, s44
	v_lshl_add_u64 v[224:225], s[40:41], 0, v[128:129]
	ds_read_b128 v[182:185], v149 offset:32768
	ds_read_b128 v[186:189], v149 offset:33792
	ds_read_b128 v[194:197], v149 offset:34816
	ds_read_b128 v[198:201], v149 offset:35840
	ds_read_b128 v[202:205], v149 offset:36864
	ds_read_b128 v[206:209], v149 offset:37888
	ds_read_b128 v[210:213], v149 offset:38912
	ds_read_b128 v[214:217], v149 offset:39936
	global_load_lds_dwordx4 v[224:225], off
	v_lshl_add_u64 v[224:225], s[40:41], 0, v[132:133]
	s_mov_b32 m0, s45
	s_nop 0
	global_load_lds_dwordx4 v[224:225], off
	s_mov_b64 vcc, s[98:99]
	s_cbranch_vccnz .Lvw_18
	s_waitcnt vmcnt(8)
.Lvw_18:
	s_waitcnt lgkmcnt(0)
	s_barrier
	s_setprio 1
	s_waitcnt lgkmcnt(0)
	v_mfma_f32_16x16x32_bf16 v[124:127], v[150:153], v[182:185], v[124:127]
	v_mfma_f32_16x16x32_bf16 v[120:123], v[158:161], v[182:185], v[120:123]
	v_mfma_f32_16x16x32_bf16 v[112:115], v[158:161], v[194:197], v[112:115]
	v_mfma_f32_16x16x32_bf16 v[116:119], v[150:153], v[194:197], v[116:119]
	v_mfma_f32_16x16x32_bf16 v[100:103], v[150:153], v[202:205], v[100:103]
	v_mfma_f32_16x16x32_bf16 v[96:99], v[158:161], v[202:205], v[96:99]
	v_mfma_f32_16x16x32_bf16 v[80:83], v[158:161], v[210:213], v[80:83]
	v_mfma_f32_16x16x32_bf16 v[84:87], v[150:153], v[210:213], v[84:87]
	v_mfma_f32_16x16x32_bf16 v[124:127], v[154:157], v[186:189], v[124:127]
	v_mfma_f32_16x16x32_bf16 v[120:123], v[162:165], v[186:189], v[120:123]
	v_mfma_f32_16x16x32_bf16 v[112:115], v[162:165], v[198:201], v[112:115]
	v_mfma_f32_16x16x32_bf16 v[116:119], v[154:157], v[198:201], v[116:119]
	v_mfma_f32_16x16x32_bf16 v[100:103], v[154:157], v[206:209], v[100:103]
	v_mfma_f32_16x16x32_bf16 v[96:99], v[162:165], v[206:209], v[96:99]
	v_mfma_f32_16x16x32_bf16 v[80:83], v[162:165], v[214:217], v[80:83]
	v_mfma_f32_16x16x32_bf16 v[84:87], v[154:157], v[214:217], v[84:87]
	s_setprio 0
	s_setprio 1
	v_mfma_f32_16x16x32_bf16 v[108:111], v[166:169], v[182:185], v[108:111]
	v_mfma_f32_16x16x32_bf16 v[104:107], v[174:177], v[182:185], v[104:107]
	v_mfma_f32_16x16x32_bf16 v[88:91], v[174:177], v[194:197], v[88:91]
	v_mfma_f32_16x16x32_bf16 v[92:95], v[166:169], v[194:197], v[92:95]
	v_mfma_f32_16x16x32_bf16 v[76:79], v[166:169], v[202:205], v[76:79]
	v_mfma_f32_16x16x32_bf16 v[72:75], v[174:177], v[202:205], v[72:75]
	v_mfma_f32_16x16x32_bf16 v[64:67], v[174:177], v[210:213], v[64:67]
	v_mfma_f32_16x16x32_bf16 v[68:71], v[166:169], v[210:213], v[68:71]
	v_mfma_f32_16x16x32_bf16 v[108:111], v[170:173], v[186:189], v[108:111]
	v_mfma_f32_16x16x32_bf16 v[104:107], v[178:181], v[186:189], v[104:107]
	v_mfma_f32_16x16x32_bf16 v[88:91], v[178:181], v[198:201], v[88:91]
	v_mfma_f32_16x16x32_bf16 v[92:95], v[170:173], v[198:201], v[92:95]
	v_mfma_f32_16x16x32_bf16 v[76:79], v[170:173], v[206:209], v[76:79]
	v_mfma_f32_16x16x32_bf16 v[72:75], v[178:181], v[206:209], v[72:75]
	v_mfma_f32_16x16x32_bf16 v[64:67], v[178:181], v[214:217], v[64:67]
	v_mfma_f32_16x16x32_bf16 v[68:71], v[170:173], v[214:217], v[68:71]
	s_setprio 0
	s_waitcnt vmcnt(8)
	s_barrier
	s_add_i32 s40, s59, s3
	v_lshl_add_u64 v[190:191], v[190:191], 0, s[6:7]
	s_mov_b32 m0, s40
	ds_read_b128 v[182:185], v149 offset:49152
	ds_read_b128 v[186:189], v149 offset:50176
	ds_read_b128 v[194:197], v149 offset:51200
	ds_read_b128 v[198:201], v149 offset:52224
	ds_read_b128 v[202:205], v149 offset:53248
	ds_read_b128 v[206:209], v149 offset:54272
	ds_read_b128 v[210:213], v149 offset:55296
	ds_read_b128 v[214:217], v149 offset:56320
	global_load_lds_dwordx4 v[190:191], off
	s_add_i32 m0, s40, 0x2000
	s_add_u32 s38, s38, 0x20080
	v_lshl_add_u64 v[190:191], v[218:219], 0, s[6:7]
	s_addc_u32 s39, s39, 0
	s_add_i32 s40, s60, s3
	global_load_lds_dwordx4 v[190:191], off
	v_lshl_add_u64 v[190:191], s[38:39], 0, v[130:131]
	s_mov_b32 m0, s40
	s_nop 0
	global_load_lds_dwordx4 v[190:191], off
	v_lshl_add_u64 v[190:191], s[38:39], 0, v[134:135]
	s_add_i32 m0, s40, 0x2000
	s_nop 0
	global_load_lds_dwordx4 v[190:191], off
	v_lshl_add_u64 v[190:191], v[220:221], 0, s[6:7]
	s_mov_b32 m0, s47
	s_nop 0
	global_load_lds_dwordx4 v[190:191], off
	v_lshl_add_u64 v[190:191], v[222:223], 0, s[6:7]
	s_mov_b32 m0, s48
	s_nop 0
	global_load_lds_dwordx4 v[190:191], off
	s_mov_b64 vcc, s[98:99]
	s_cbranch_vccnz .Lvw_19
	s_waitcnt vmcnt(8)
; #define PG8_STAGE(bufoff, gbase, voff) do { _Pragma("unroll") for (int _i = 0; _i < 2; ++_i) \
;         __builtin_amdgcn_global_load_lds((const unsigned*)((const char*)(gbase) + (voff)[_i]), (PG8_LAS unsigned*)(lds + (bufoff) + ldsw + _i * 8192), 16, 0, 0); } while (0)
; #define PG8_LDA(dst, b, h) do { _Pragma("unroll") for (int m = 0; m < 4; ++m) _Pragma("unroll") for (int k = 0; k < 2; ++k) dst[m][k] = *(const PG8_LAS bf16x8*)(lds + PG8_SA(b, h) + aoff + m * 2048 + k * 1024); } while (0)
; #define PG8_LDB(dst, b, h) do { _Pragma("unroll") for (int n = 0; n < 2; ++n) _Pragma("unroll") for (int k = 0; k < 2; ++k) dst[n][k] = *(const PG8_LAS bf16x8*)(lds + PG8_SB(b, h) + boff + n * 2048 + k * 1024); } while (0)
; template <class Epi, class Sched, bool ALIGN_EPI = false, bool SP2 = false>
; __device__ __forceinline__ void gemm_phase(PG8_LAS unsigned char* lds, const Gemm g, const Sched& S, const Epi& E) {
;     ...
;             PG8_WAIT_V(8); PG8_WAIT_L(0); PG8_BAR; PG8_MMA(1, 0, At, B0); PG8_MMA(1, 1, At, B1); PG8_BAR; PG8_SCHED;
;             } else {
;             PG8_LDB(B0, 0, 0); PG8_SCHED; PG8_LDA(At, 0, 0); PG8_STAGE(PG8_SA(1, 1), a1 + hstep, voffA);
;             PG8_WAIT_L(8); PG8_BAR; PG8_WAIT_L(0); PG8_MMA(0, 0, At, B0); PG8_BAR; PG8_SCHED;
;             PG8_LDB(B1, 0, 1); PG8_STAGE(PG8_SB(0, 0), b2, voffB);
;             PG8_BAR; PG8_WAIT_L(0); PG8_MMA(0, 1, At, B1); PG8_BAR;
;             PG8_LDA(At, 0, 1); PG8_STAGE(PG8_SA(0, 0), a2, voffA);
;             PG8_BAR; PG8_WAIT_L(0); PG8_MMA(1, 0, At, B0); PG8_BAR; PG8_SCHED;
;             PG8_STAGE(PG8_SB(0, 1), b2 + hstep, voffB);
;             PG8_WAIT_V(6); PG8_BAR; PG8_MMA(1, 1, At, B1); PG8_BAR;
;             PG8_LDB(B0, 1, 0); PG8_SCHED; PG8_LDA(At, 1, 0); PG8_STAGE(PG8_SA(0, 1), a2 + hstep, voffA);
;             PG8_WAIT_L(8); PG8_BAR; PG8_WAIT_L(0); PG8_MMA(0, 0, At, B0); PG8_BAR; PG8_SCHED;
;             PG8_LDB(B1, 1, 1); PG8_STAGE(PG8_SB(1, 0), b3, voffB);
;             PG8_BAR; PG8_WAIT_L(0); PG8_MMA(0, 1, At, B1); PG8_BAR;
;             PG8_LDA(At, 1, 1); PG8_STAGE(PG8_SA(1, 0), a3, voffA);
;             PG8_BAR; PG8_WAIT_L(0); PG8_MMA(1, 0, At, B0); PG8_BAR; PG8_SCHED;
;             PG8_STAGE(PG8_SB(1, 1), b3 + hstep, voffB);
;             PG8_WAIT_V(6); PG8_BAR; PG8_MMA(1, 1, At, B1); PG8_BAR;
;             }
;         }
;         if constexpr (ALIGN_EPI) { if (wr == 0) PG8_BAR; }
.Lvw_19:
	s_waitcnt lgkmcnt(0)
	s_barrier
	s_setprio 1
	s_waitcnt lgkmcnt(0)
	v_mfma_f32_16x16x32_bf16 v[60:63], v[150:153], v[182:185], v[60:63]
	v_mfma_f32_16x16x32_bf16 v[56:59], v[158:161], v[182:185], v[56:59]
	v_mfma_f32_16x16x32_bf16 v[48:51], v[158:161], v[194:197], v[48:51]
	v_mfma_f32_16x16x32_bf16 v[52:55], v[150:153], v[194:197], v[52:55]
	v_mfma_f32_16x16x32_bf16 v[36:39], v[150:153], v[202:205], v[36:39]
	v_mfma_f32_16x16x32_bf16 v[32:35], v[158:161], v[202:205], v[32:35]
	v_mfma_f32_16x16x32_bf16 v[16:19], v[158:161], v[210:213], v[16:19]
	v_mfma_f32_16x16x32_bf16 v[20:23], v[150:153], v[210:213], v[20:23]
	v_mfma_f32_16x16x32_bf16 v[60:63], v[154:157], v[186:189], v[60:63]
	v_mfma_f32_16x16x32_bf16 v[56:59], v[162:165], v[186:189], v[56:59]
	v_mfma_f32_16x16x32_bf16 v[48:51], v[162:165], v[198:201], v[48:51]
	v_mfma_f32_16x16x32_bf16 v[52:55], v[154:157], v[198:201], v[52:55]
	v_mfma_f32_16x16x32_bf16 v[36:39], v[154:157], v[206:209], v[36:39]
	v_mfma_f32_16x16x32_bf16 v[32:35], v[162:165], v[206:209], v[32:35]
	v_mfma_f32_16x16x32_bf16 v[16:19], v[162:165], v[214:217], v[16:19]
	v_mfma_f32_16x16x32_bf16 v[20:23], v[154:157], v[214:217], v[20:23]
	s_setprio 0
	s_setprio 1
	v_mfma_f32_16x16x32_bf16 v[44:47], v[166:169], v[182:185], v[44:47]
	v_mfma_f32_16x16x32_bf16 v[40:43], v[174:177], v[182:185], v[40:43]
	v_mfma_f32_16x16x32_bf16 v[24:27], v[174:177], v[194:197], v[24:27]
	v_mfma_f32_16x16x32_bf16 v[28:31], v[166:169], v[194:197], v[28:31]
	v_mfma_f32_16x16x32_bf16 v[12:15], v[166:169], v[202:205], v[12:15]
	v_mfma_f32_16x16x32_bf16 v[8:11], v[174:177], v[202:205], v[8:11]
	v_mfma_f32_16x16x32_bf16 v[0:3], v[174:177], v[210:213], v[0:3]
	v_mfma_f32_16x16x32_bf16 v[4:7], v[166:169], v[210:213], v[4:7]
	v_mfma_f32_16x16x32_bf16 v[44:47], v[170:173], v[186:189], v[44:47]
	v_mfma_f32_16x16x32_bf16 v[40:43], v[178:181], v[186:189], v[40:43]
	v_mfma_f32_16x16x32_bf16 v[24:27], v[178:181], v[198:201], v[24:27]
	v_mfma_f32_16x16x32_bf16 v[28:31], v[170:173], v[198:201], v[28:31]
	v_mfma_f32_16x16x32_bf16 v[12:15], v[170:173], v[206:209], v[12:15]
	v_mfma_f32_16x16x32_bf16 v[8:11], v[178:181], v[206:209], v[8:11]
	v_mfma_f32_16x16x32_bf16 v[0:3], v[178:181], v[214:217], v[0:3]
	v_mfma_f32_16x16x32_bf16 v[4:7], v[170:173], v[214:217], v[4:7]
	s_setprio 0
	s_waitcnt vmcnt(8)
	s_barrier
	s_add_i32 s58, s58, 2
	s_add_u32 s36, s36, 0x100
	s_addc_u32 s37, s37, 0
	s_add_u32 s56, s56, 0x100
	s_addc_u32 s57, s57, 0
	s_cmp_gt_u32 s58, 5
	s_cbranch_scc0 .LBB0_430
	s_and_b64 vcc, exec, s[8:9]
	s_cbranch_vccz .LBB0_433
	s_barrier

; #define PG8_STAGE(bufoff, gbase, voff) do { _Pragma("unroll") for (int _i = 0; _i < 2; ++_i) \
;         __builtin_amdgcn_global_load_lds((const unsigned*)((const char*)(gbase) + (voff)[_i]), (PG8_LAS unsigned*)(lds + (bufoff) + ldsw + _i * 8192), 16, 0, 0); } while (0)
; #define PG8_LDA(dst, b, h) do { _Pragma("unroll") for (int m = 0; m < 4; ++m) _Pragma("unroll") for (int k = 0; k < 2; ++k) dst[m][k] = *(const PG8_LAS bf16x8*)(lds + PG8_SA(b, h) + aoff + m * 2048 + k * 1024); } while (0)
; #define PG8_MMA(ai, bj, At, Bt) do { __builtin_amdgcn_s_setprio(1); _Pragma("unroll") for (int m = 0; m < 4; ++m) _Pragma("unroll") for (int n = 0; n < 2; ++n) _Pragma("unroll") for (int k = 0; k < 2; ++k) \
;         acc[ai][bj][m][n] = __builtin_amdgcn_mfma_f32_16x16x32_bf16(Bt[n][k], At[m][k], acc[ai][bj][m][n], 0, 0, 0); __builtin_amdgcn_s_setprio(0); } while (0)
; #define PG8_WAIT_V(n) asm volatile("s_waitcnt vmcnt(" #n ")" ::: "memory")
; #define PG8_WAIT_L(n) asm volatile("s_waitcnt lgkmcnt(" #n ")" ::: "memory")
; #define PG8_BAR __builtin_amdgcn_s_barrier()
; #define PG8_SCHED __builtin_amdgcn_sched_barrier(0)
; template <class Epi, class Sched, bool ALIGN_EPI = false, bool SP2 = false>
; __device__ __forceinline__ void gemm_phase(PG8_LAS unsigned char* lds, const Gemm g, const Sched& S, const Epi& E) {
;     ...
;             PG8_WAIT_V(8); PG8_WAIT_L(0); PG8_BAR; PG8_MMA(0, 0, At, B0); PG8_MMA(0, 1, At, B1); PG8_BAR; PG8_SCHED;
;             PG8_LDA(At, 0, 1); PG8_STAGE(PG8_SB(0, 0), b2, voffB); PG8_STAGE(PG8_SB(0, 1), b2 + hstep, voffB); PG8_STAGE(PG8_SA(0, 0), a2, voffA);
;             PG8_WAIT_V(8); PG8_WAIT_L(0); PG8_BAR; PG8_MMA(1, 0, At, B0); PG8_MMA(1, 1, At, B1); PG8_BAR; PG8_SCHED;
.Lvw_20:
	s_waitcnt lgkmcnt(0)
	s_barrier
	s_setprio 1
	s_waitcnt lgkmcnt(0)
	v_mfma_f32_16x16x32_bf16 v[132:135], v[96:99], v[188:191], v[132:135]
	v_mfma_f32_16x16x32_bf16 v[128:131], v[154:157], v[188:191], v[128:131]
	v_mfma_f32_16x16x32_bf16 v[120:123], v[154:157], v[198:201], v[120:123]
	v_mfma_f32_16x16x32_bf16 v[124:127], v[96:99], v[198:201], v[124:127]
	v_mfma_f32_16x16x32_bf16 v[116:119], v[96:99], v[206:209], v[116:119]
	v_mfma_f32_16x16x32_bf16 v[112:115], v[154:157], v[206:209], v[112:115]
	v_mfma_f32_16x16x32_bf16 v[104:107], v[154:157], v[214:217], v[104:107]
	v_mfma_f32_16x16x32_bf16 v[108:111], v[96:99], v[214:217], v[108:111]
	v_mfma_f32_16x16x32_bf16 v[132:135], v[100:103], v[194:197], v[132:135]
	v_mfma_f32_16x16x32_bf16 v[128:131], v[168:171], v[194:197], v[128:131]
	v_mfma_f32_16x16x32_bf16 v[120:123], v[168:171], v[202:205], v[120:123]
	v_mfma_f32_16x16x32_bf16 v[124:127], v[100:103], v[202:205], v[124:127]
	v_mfma_f32_16x16x32_bf16 v[116:119], v[100:103], v[210:213], v[116:119]
	v_mfma_f32_16x16x32_bf16 v[112:115], v[168:171], v[210:213], v[112:115]
	v_mfma_f32_16x16x32_bf16 v[104:107], v[168:171], v[218:221], v[104:107]
	v_mfma_f32_16x16x32_bf16 v[108:111], v[100:103], v[218:221], v[108:111]
	s_setprio 0
	s_setprio 1
	v_mfma_f32_16x16x32_bf16 v[60:63], v[172:175], v[188:191], v[60:63]
	v_mfma_f32_16x16x32_bf16 v[56:59], v[180:183], v[188:191], v[56:59]
	v_mfma_f32_16x16x32_bf16 v[48:51], v[180:183], v[198:201], v[48:51]
	v_mfma_f32_16x16x32_bf16 v[52:55], v[172:175], v[198:201], v[52:55]
	v_mfma_f32_16x16x32_bf16 v[44:47], v[172:175], v[206:209], v[44:47]
	v_mfma_f32_16x16x32_bf16 v[40:43], v[180:183], v[206:209], v[40:43]
	v_mfma_f32_16x16x32_bf16 v[32:35], v[180:183], v[214:217], v[32:35]
	v_mfma_f32_16x16x32_bf16 v[36:39], v[172:175], v[214:217], v[36:39]
	v_mfma_f32_16x16x32_bf16 v[60:63], v[176:179], v[194:197], v[60:63]
	v_mfma_f32_16x16x32_bf16 v[56:59], v[184:187], v[194:197], v[56:59]
	v_mfma_f32_16x16x32_bf16 v[48:51], v[184:187], v[202:205], v[48:51]
	v_mfma_f32_16x16x32_bf16 v[52:55], v[176:179], v[202:205], v[52:55]
	v_mfma_f32_16x16x32_bf16 v[44:47], v[176:179], v[210:213], v[44:47]
	v_mfma_f32_16x16x32_bf16 v[40:43], v[184:187], v[210:213], v[40:43]
	v_mfma_f32_16x16x32_bf16 v[32:35], v[184:187], v[218:221], v[32:35]
	v_mfma_f32_16x16x32_bf16 v[36:39], v[176:179], v[218:221], v[36:39]
	s_setprio 0
	s_waitcnt vmcnt(8)
	s_barrier
	s_add_i32 s58, s53, s42
	v_lshl_add_u64 v[158:159], s[38:39], 0, v[138:139]
	s_mov_b32 m0, s58
	ds_read_b128 v[188:191], v165 offset:16384
	ds_read_b128 v[194:197], v165 offset:17408
	ds_read_b128 v[198:201], v165 offset:18432
	ds_read_b128 v[202:205], v165 offset:19456
	ds_read_b128 v[206:209], v165 offset:20480
	ds_read_b128 v[210:213], v165 offset:21504
	ds_read_b128 v[214:217], v165 offset:22528
	ds_read_b128 v[218:221], v165 offset:23552
	global_load_lds_dwordx4 v[158:159], off
	s_add_i32 m0, s58, 0x2000
	s_add_u32 s58, s38, 0x80000
	v_lshl_add_u64 v[222:223], s[38:39], 0, v[142:143]
	s_addc_u32 s59, s39, 0
	s_add_i32 s60, s54, s42
	global_load_lds_dwordx4 v[222:223], off
	v_lshl_add_u64 v[224:225], s[58:59], 0, v[138:139]
	s_mov_b32 m0, s60
	v_lshl_add_u64 v[226:227], s[40:41], 0, v[140:141]
	global_load_lds_dwordx4 v[224:225], off
	v_lshl_add_u64 v[224:225], s[58:59], 0, v[142:143]
	s_add_i32 m0, s60, 0x2000
	s_nop 0
	global_load_lds_dwordx4 v[224:225], off
	v_lshl_add_u64 v[224:225], s[40:41], 0, v[136:137]
	s_mov_b32 m0, s43
	s_nop 0
	global_load_lds_dwordx4 v[224:225], off
	s_mov_b32 m0, s44
	s_nop 0
	global_load_lds_dwordx4 v[226:227], off
	s_mov_b64 vcc, s[98:99]
	s_cbranch_vccnz .Lvw_21
	s_waitcnt vmcnt(8)
.Lvw_21:
	s_waitcnt lgkmcnt(0)
	s_barrier
	s_setprio 1
	s_waitcnt lgkmcnt(0)
	v_mfma_f32_16x16x32_bf16 v[92:95], v[96:99], v[188:191], v[92:95]
	v_mfma_f32_16x16x32_bf16 v[88:91], v[154:157], v[188:191], v[88:91]
	v_mfma_f32_16x16x32_bf16 v[80:83], v[154:157], v[198:201], v[80:83]
	v_mfma_f32_16x16x32_bf16 v[84:87], v[96:99], v[198:201], v[84:87]
	v_mfma_f32_16x16x32_bf16 v[76:79], v[96:99], v[206:209], v[76:79]
	v_mfma_f32_16x16x32_bf16 v[72:75], v[154:157], v[206:209], v[72:75]
	v_mfma_f32_16x16x32_bf16 v[64:67], v[154:157], v[214:217], v[64:67]
	v_mfma_f32_16x16x32_bf16 v[68:71], v[96:99], v[214:217], v[68:71]
	v_mfma_f32_16x16x32_bf16 v[92:95], v[100:103], v[194:197], v[92:95]
	v_mfma_f32_16x16x32_bf16 v[88:91], v[168:171], v[194:197], v[88:91]
	v_mfma_f32_16x16x32_bf16 v[80:83], v[168:171], v[202:205], v[80:83]
	v_mfma_f32_16x16x32_bf16 v[84:87], v[100:103], v[202:205], v[84:87]
	v_mfma_f32_16x16x32_bf16 v[76:79], v[100:103], v[210:213], v[76:79]
	v_mfma_f32_16x16x32_bf16 v[72:75], v[168:171], v[210:213], v[72:75]
	v_mfma_f32_16x16x32_bf16 v[64:67], v[168:171], v[218:221], v[64:67]
	v_mfma_f32_16x16x32_bf16 v[68:71], v[100:103], v[218:221], v[68:71]
	s_setprio 0
	s_setprio 1
	v_mfma_f32_16x16x32_bf16 v[28:31], v[172:175], v[188:191], v[28:31]
	v_mfma_f32_16x16x32_bf16 v[24:27], v[180:183], v[188:191], v[24:27]
	v_mfma_f32_16x16x32_bf16 v[16:19], v[180:183], v[198:201], v[16:19]
	v_mfma_f32_16x16x32_bf16 v[20:23], v[172:175], v[198:201], v[20:23]
	v_mfma_f32_16x16x32_bf16 v[12:15], v[172:175], v[206:209], v[12:15]
	v_mfma_f32_16x16x32_bf16 v[8:11], v[180:183], v[206:209], v[8:11]
	v_mfma_f32_16x16x32_bf16 v[0:3], v[180:183], v[214:217], v[0:3]
	v_mfma_f32_16x16x32_bf16 v[4:7], v[172:175], v[214:217], v[4:7]
	v_mfma_f32_16x16x32_bf16 v[28:31], v[176:179], v[194:197], v[28:31]
	v_mfma_f32_16x16x32_bf16 v[24:27], v[184:187], v[194:197], v[24:27]
	v_mfma_f32_16x16x32_bf16 v[16:19], v[184:187], v[202:205], v[16:19]
	v_mfma_f32_16x16x32_bf16 v[20:23], v[176:179], v[202:205], v[20:23]
	v_mfma_f32_16x16x32_bf16 v[12:15], v[176:179], v[210:213], v[12:15]
	v_mfma_f32_16x16x32_bf16 v[8:11], v[184:187], v[210:213], v[8:11]
	v_mfma_f32_16x16x32_bf16 v[0:3], v[184:187], v[218:221], v[0:3]
	v_mfma_f32_16x16x32_bf16 v[4:7], v[176:179], v[218:221], v[4:7]
	s_setprio 0
	s_waitcnt vmcnt(8)
	s_barrier
; #define PG8_STAGE(bufoff, gbase, voff) do { _Pragma("unroll") for (int _i = 0; _i < 2; ++_i) \
;         __builtin_amdgcn_global_load_lds((const unsigned*)((const char*)(gbase) + (voff)[_i]), (PG8_LAS unsigned*)(lds + (bufoff) + ldsw + _i * 8192), 16, 0, 0); } while (0)
; #define PG8_LDA(dst, b, h) do { _Pragma("unroll") for (int m = 0; m < 4; ++m) _Pragma("unroll") for (int k = 0; k < 2; ++k) dst[m][k] = *(const PG8_LAS bf16x8*)(lds + PG8_SA(b, h) + aoff + m * 2048 + k * 1024); } while (0)
; #define PG8_LDB(dst, b, h) do { _Pragma("unroll") for (int n = 0; n < 2; ++n) _Pragma("unroll") for (int k = 0; k < 2; ++k) dst[n][k] = *(const PG8_LAS bf16x8*)(lds + PG8_SB(b, h) + boff + n * 2048 + k * 1024); } while (0)
; #define PG8_MMA(ai, bj, At, Bt) do { __builtin_amdgcn_s_setprio(1); _Pragma("unroll") for (int m = 0; m < 4; ++m) _Pragma("unroll") for (int n = 0; n < 2; ++n) _Pragma("unroll") for (int k = 0; k < 2; ++k) \
;         acc[ai][bj][m][n] = __builtin_amdgcn_mfma_f32_16x16x32_bf16(Bt[n][k], At[m][k], acc[ai][bj][m][n], 0, 0, 0); __builtin_amdgcn_s_setprio(0); } while (0)
; #define PG8_WAIT_V(n) asm volatile("s_waitcnt vmcnt(" #n ")" ::: "memory")
; #define PG8_WAIT_L(n) asm volatile("s_waitcnt lgkmcnt(" #n ")" ::: "memory")
; #define PG8_BAR __builtin_amdgcn_s_barrier()
; #define PG8_SCHED __builtin_amdgcn_sched_barrier(0)
; template <class Epi, class Sched, bool ALIGN_EPI = false, bool SP2 = false>
; __device__ __forceinline__ void gemm_phase(PG8_LAS unsigned char* lds, const Gemm g, const Sched& S, const Epi& E) {
;     ...
;             PG8_LDB(B0, 1, 0); PG8_LDB(B1, 1, 1); PG8_SCHED; PG8_LDA(At, 1, 0); PG8_STAGE(PG8_SA(0, 1), a2 + hstep, voffA);
;             PG8_WAIT_V(8); PG8_WAIT_L(0); PG8_BAR; PG8_MMA(0, 0, At, B0); PG8_MMA(0, 1, At, B1); PG8_BAR; PG8_SCHED;
;             PG8_LDA(At, 1, 1); PG8_STAGE(PG8_SB(1, 0), b3, voffB); PG8_STAGE(PG8_SB(1, 1), b3 + hstep, voffB); PG8_STAGE(PG8_SA(1, 0), a3, voffA);
	s_add_i32 s58, 0, 0x18000
	v_add_u32_e32 v144, s58, v161
	s_add_i32 s59, 0, 0x1c000
	ds_read_b128 v[96:99], v144
	ds_read_b128 v[100:103], v144 offset:1024
	ds_read_b128 v[154:157], v144 offset:2048
	ds_read_b128 v[168:171], v144 offset:3072
	v_add_u32_e32 v144, s59, v161
	ds_read_b128 v[172:175], v144
	ds_read_b128 v[176:179], v144 offset:1024
	ds_read_b128 v[180:183], v144 offset:2048
	ds_read_b128 v[184:187], v144 offset:3072
	s_add_u32 s40, s40, 0x80000
	s_addc_u32 s41, s41, 0
	s_mov_b32 m0, s45
	v_lshl_add_u64 v[228:229], s[40:41], 0, v[136:137]
	ds_read_b128 v[188:191], v165 offset:32768
	ds_read_b128 v[194:197], v165 offset:33792
	ds_read_b128 v[198:201], v165 offset:34816
	ds_read_b128 v[202:205], v165 offset:35840
	ds_read_b128 v[206:209], v165 offset:36864
	ds_read_b128 v[210:213], v165 offset:37888
	ds_read_b128 v[214:217], v165 offset:38912
	ds_read_b128 v[218:221], v165 offset:39936
	global_load_lds_dwordx4 v[228:229], off
	v_lshl_add_u64 v[228:229], s[40:41], 0, v[140:141]
	s_mov_b32 m0, s46
	s_nop 0
	global_load_lds_dwordx4 v[228:229], off
	s_mov_b64 vcc, s[98:99]
	s_cbranch_vccnz .Lvw_22
	s_waitcnt vmcnt(8)
.Lvw_22:
	s_waitcnt lgkmcnt(0)
	s_barrier
	s_setprio 1
	s_waitcnt lgkmcnt(0)
	v_mfma_f32_16x16x32_bf16 v[132:135], v[96:99], v[188:191], v[132:135]
	v_mfma_f32_16x16x32_bf16 v[128:131], v[154:157], v[188:191], v[128:131]
	v_mfma_f32_16x16x32_bf16 v[120:123], v[154:157], v[198:201], v[120:123]
	v_mfma_f32_16x16x32_bf16 v[124:127], v[96:99], v[198:201], v[124:127]
	v_mfma_f32_16x16x32_bf16 v[116:119], v[96:99], v[206:209], v[116:119]
	v_mfma_f32_16x16x32_bf16 v[112:115], v[154:157], v[206:209], v[112:115]
	v_mfma_f32_16x16x32_bf16 v[104:107], v[154:157], v[214:217], v[104:107]
	v_mfma_f32_16x16x32_bf16 v[108:111], v[96:99], v[214:217], v[108:111]
	v_mfma_f32_16x16x32_bf16 v[132:135], v[100:103], v[194:197], v[132:135]
	v_mfma_f32_16x16x32_bf16 v[128:131], v[168:171], v[194:197], v[128:131]
	v_mfma_f32_16x16x32_bf16 v[120:123], v[168:171], v[202:205], v[120:123]
	v_mfma_f32_16x16x32_bf16 v[124:127], v[100:103], v[202:205], v[124:127]
	v_mfma_f32_16x16x32_bf16 v[116:119], v[100:103], v[210:213], v[116:119]
	v_mfma_f32_16x16x32_bf16 v[112:115], v[168:171], v[210:213], v[112:115]
	v_mfma_f32_16x16x32_bf16 v[104:107], v[168:171], v[218:221], v[104:107]
	v_mfma_f32_16x16x32_bf16 v[108:111], v[100:103], v[218:221], v[108:111]
	s_setprio 0
	s_setprio 1
	v_mfma_f32_16x16x32_bf16 v[60:63], v[172:175], v[188:191], v[60:63]
	v_mfma_f32_16x16x32_bf16 v[56:59], v[180:183], v[188:191], v[56:59]
	v_mfma_f32_16x16x32_bf16 v[48:51], v[180:183], v[198:201], v[48:51]
	v_mfma_f32_16x16x32_bf16 v[52:55], v[172:175], v[198:201], v[52:55]
	v_mfma_f32_16x16x32_bf16 v[44:47], v[172:175], v[206:209], v[44:47]
	v_mfma_f32_16x16x32_bf16 v[40:43], v[180:183], v[206:209], v[40:43]
	v_mfma_f32_16x16x32_bf16 v[32:35], v[180:183], v[214:217], v[32:35]
	v_mfma_f32_16x16x32_bf16 v[36:39], v[172:175], v[214:217], v[36:39]
	v_mfma_f32_16x16x32_bf16 v[60:63], v[176:179], v[194:197], v[60:63]
	v_mfma_f32_16x16x32_bf16 v[56:59], v[184:187], v[194:197], v[56:59]
	v_mfma_f32_16x16x32_bf16 v[48:51], v[184:187], v[202:205], v[48:51]
	v_mfma_f32_16x16x32_bf16 v[52:55], v[176:179], v[202:205], v[52:55]
	v_mfma_f32_16x16x32_bf16 v[44:47], v[176:179], v[210:213], v[44:47]
	v_mfma_f32_16x16x32_bf16 v[40:43], v[184:187], v[210:213], v[40:43]
	v_mfma_f32_16x16x32_bf16 v[32:35], v[184:187], v[218:221], v[32:35]
	v_mfma_f32_16x16x32_bf16 v[36:39], v[176:179], v[218:221], v[36:39]
	s_setprio 0
	s_waitcnt vmcnt(8)
	s_barrier
	s_add_i32 s40, s58, s42
	v_lshl_add_u64 v[158:159], v[158:159], 0, s[16:17]
	s_mov_b32 m0, s40
	ds_read_b128 v[188:191], v165 offset:49152
	ds_read_b128 v[194:197], v165 offset:50176
	ds_read_b128 v[198:201], v165 offset:51200
	ds_read_b128 v[202:205], v165 offset:52224
	ds_read_b128 v[206:209], v165 offset:53248
	ds_read_b128 v[210:213], v165 offset:54272
	ds_read_b128 v[214:217], v165 offset:55296
	ds_read_b128 v[218:221], v165 offset:56320
	global_load_lds_dwordx4 v[158:159], off
	s_add_i32 m0, s40, 0x2000
	s_add_u32 s38, s38, 0x80080
	v_lshl_add_u64 v[158:159], v[222:223], 0, s[16:17]
	s_addc_u32 s39, s39, 0
	s_add_i32 s40, s59, s42
	global_load_lds_dwordx4 v[158:159], off
	v_lshl_add_u64 v[158:159], s[38:39], 0, v[138:139]
	s_mov_b32 m0, s40
	s_nop 0
	global_load_lds_dwordx4 v[158:159], off
	v_lshl_add_u64 v[158:159], s[38:39], 0, v[142:143]
	s_add_i32 m0, s40, 0x2000
	s_nop 0
	global_load_lds_dwordx4 v[158:159], off
	v_lshl_add_u64 v[158:159], v[224:225], 0, s[16:17]
	s_mov_b32 m0, s48
	s_nop 0
	global_load_lds_dwordx4 v[158:159], off
	v_lshl_add_u64 v[158:159], v[226:227], 0, s[16:17]
	s_mov_b32 m0, s49
	s_nop 0
	global_load_lds_dwordx4 v[158:159], off
	s_mov_b64 vcc, s[98:99]
	s_cbranch_vccnz .Lvw_23
	s_waitcnt vmcnt(8)
; #define PG8_STAGE(bufoff, gbase, voff) do { _Pragma("unroll") for (int _i = 0; _i < 2; ++_i) \
;         __builtin_amdgcn_global_load_lds((const unsigned*)((const char*)(gbase) + (voff)[_i]), (PG8_LAS unsigned*)(lds + (bufoff) + ldsw + _i * 8192), 16, 0, 0); } while (0)
; #define PG8_LDA(dst, b, h) do { _Pragma("unroll") for (int m = 0; m < 4; ++m) _Pragma("unroll") for (int k = 0; k < 2; ++k) dst[m][k] = *(const PG8_LAS bf16x8*)(lds + PG8_SA(b, h) + aoff + m * 2048 + k * 1024); } while (0)
; #define PG8_LDB(dst, b, h) do { _Pragma("unroll") for (int n = 0; n < 2; ++n) _Pragma("unroll") for (int k = 0; k < 2; ++k) dst[n][k] = *(const PG8_LAS bf16x8*)(lds + PG8_SB(b, h) + boff + n * 2048 + k * 1024); } while (0)
; template <class Epi, class Sched, bool ALIGN_EPI = false, bool SP2 = false>
; __device__ __forceinline__ void gemm_phase(PG8_LAS unsigned char* lds, const Gemm g, const Sched& S, const Epi& E) {
;     ...
;             PG8_WAIT_V(8); PG8_WAIT_L(0); PG8_BAR; PG8_MMA(1, 0, At, B0); PG8_MMA(1, 1, At, B1); PG8_BAR; PG8_SCHED;
;             } else {
;             PG8_LDB(B0, 0, 0); PG8_SCHED; PG8_LDA(At, 0, 0); PG8_STAGE(PG8_SA(1, 1), a1 + hstep, voffA);
;             PG8_WAIT_L(8); PG8_BAR; PG8_WAIT_L(0); PG8_MMA(0, 0, At, B0); PG8_BAR; PG8_SCHED;
;             PG8_LDB(B1, 0, 1); PG8_STAGE(PG8_SB(0, 0), b2, voffB);
;             PG8_BAR; PG8_WAIT_L(0); PG8_MMA(0, 1, At, B1); PG8_BAR;
;             PG8_LDA(At, 0, 1); PG8_STAGE(PG8_SA(0, 0), a2, voffA);
;             PG8_BAR; PG8_WAIT_L(0); PG8_MMA(1, 0, At, B0); PG8_BAR; PG8_SCHED;
;             PG8_STAGE(PG8_SB(0, 1), b2 + hstep, voffB);
;             PG8_WAIT_V(6); PG8_BAR; PG8_MMA(1, 1, At, B1); PG8_BAR;
;             PG8_LDB(B0, 1, 0); PG8_SCHED; PG8_LDA(At, 1, 0); PG8_STAGE(PG8_SA(0, 1), a2 + hstep, voffA);
;             PG8_WAIT_L(8); PG8_BAR; PG8_WAIT_L(0); PG8_MMA(0, 0, At, B0); PG8_BAR; PG8_SCHED;
;             PG8_LDB(B1, 1, 1); PG8_STAGE(PG8_SB(1, 0), b3, voffB);
;             PG8_BAR; PG8_WAIT_L(0); PG8_MMA(0, 1, At, B1); PG8_BAR;
;             PG8_LDA(At, 1, 1); PG8_STAGE(PG8_SA(1, 0), a3, voffA);
;             PG8_BAR; PG8_WAIT_L(0); PG8_MMA(1, 0, At, B0); PG8_BAR; PG8_SCHED;
;             PG8_STAGE(PG8_SB(1, 1), b3 + hstep, voffB);
;             PG8_WAIT_V(6); PG8_BAR; PG8_MMA(1, 1, At, B1); PG8_BAR;
;             }
;         }
;         if constexpr (ALIGN_EPI) { if (wr == 0) PG8_BAR; }
.Lvw_23:
	s_waitcnt lgkmcnt(0)
	s_barrier
	s_setprio 1
	s_waitcnt lgkmcnt(0)
	v_mfma_f32_16x16x32_bf16 v[92:95], v[96:99], v[188:191], v[92:95]
	v_mfma_f32_16x16x32_bf16 v[88:91], v[154:157], v[188:191], v[88:91]
	v_mfma_f32_16x16x32_bf16 v[80:83], v[154:157], v[198:201], v[80:83]
	v_mfma_f32_16x16x32_bf16 v[84:87], v[96:99], v[198:201], v[84:87]
	v_mfma_f32_16x16x32_bf16 v[76:79], v[96:99], v[206:209], v[76:79]
	v_mfma_f32_16x16x32_bf16 v[72:75], v[154:157], v[206:209], v[72:75]
	v_mfma_f32_16x16x32_bf16 v[64:67], v[154:157], v[214:217], v[64:67]
	v_mfma_f32_16x16x32_bf16 v[68:71], v[96:99], v[214:217], v[68:71]
	v_mfma_f32_16x16x32_bf16 v[92:95], v[100:103], v[194:197], v[92:95]
	v_mfma_f32_16x16x32_bf16 v[88:91], v[168:171], v[194:197], v[88:91]
	v_mfma_f32_16x16x32_bf16 v[80:83], v[168:171], v[202:205], v[80:83]
	v_mfma_f32_16x16x32_bf16 v[84:87], v[100:103], v[202:205], v[84:87]
	v_mfma_f32_16x16x32_bf16 v[76:79], v[100:103], v[210:213], v[76:79]
	v_mfma_f32_16x16x32_bf16 v[72:75], v[168:171], v[210:213], v[72:75]
	v_mfma_f32_16x16x32_bf16 v[64:67], v[168:171], v[218:221], v[64:67]
	v_mfma_f32_16x16x32_bf16 v[68:71], v[100:103], v[218:221], v[68:71]
	s_setprio 0
	s_setprio 1
	v_mfma_f32_16x16x32_bf16 v[28:31], v[172:175], v[188:191], v[28:31]
	v_mfma_f32_16x16x32_bf16 v[24:27], v[180:183], v[188:191], v[24:27]
	v_mfma_f32_16x16x32_bf16 v[16:19], v[180:183], v[198:201], v[16:19]
	v_mfma_f32_16x16x32_bf16 v[20:23], v[172:175], v[198:201], v[20:23]
	v_mfma_f32_16x16x32_bf16 v[12:15], v[172:175], v[206:209], v[12:15]
	v_mfma_f32_16x16x32_bf16 v[8:11], v[180:183], v[206:209], v[8:11]
	v_mfma_f32_16x16x32_bf16 v[0:3], v[180:183], v[214:217], v[0:3]
	v_mfma_f32_16x16x32_bf16 v[4:7], v[172:175], v[214:217], v[4:7]
	v_mfma_f32_16x16x32_bf16 v[28:31], v[176:179], v[194:197], v[28:31]
	v_mfma_f32_16x16x32_bf16 v[24:27], v[184:187], v[194:197], v[24:27]
	v_mfma_f32_16x16x32_bf16 v[16:19], v[184:187], v[202:205], v[16:19]
	v_mfma_f32_16x16x32_bf16 v[20:23], v[176:179], v[202:205], v[20:23]
	v_mfma_f32_16x16x32_bf16 v[12:15], v[176:179], v[210:213], v[12:15]
	v_mfma_f32_16x16x32_bf16 v[8:11], v[184:187], v[210:213], v[8:11]
	v_mfma_f32_16x16x32_bf16 v[0:3], v[184:187], v[218:221], v[0:3]
	v_mfma_f32_16x16x32_bf16 v[4:7], v[176:179], v[218:221], v[4:7]
	s_setprio 0
	s_waitcnt vmcnt(8)
	s_barrier
	s_add_i32 s33, s33, 2
	s_add_u32 s36, s36, 0x100
	s_addc_u32 s37, s37, 0
	s_add_u32 s27, s27, 0x100
	s_addc_u32 s29, s29, 0
	s_cmp_gt_u32 s33, 29
	s_cbranch_scc0 .LBB0_605
	s_and_b64 vcc, exec, s[18:19]
	s_cbranch_vccz .LBB0_608
	s_barrier

; #define PG8_STAGE(bufoff, gbase, voff) do { _Pragma("unroll") for (int _i = 0; _i < 2; ++_i) \
;         __builtin_amdgcn_global_load_lds((const unsigned*)((const char*)(gbase) + (voff)[_i]), (PG8_LAS unsigned*)(lds + (bufoff) + ldsw + _i * 8192), 16, 0, 0); } while (0)
; #define PG8_LDA(dst, b, h) do { _Pragma("unroll") for (int m = 0; m < 4; ++m) _Pragma("unroll") for (int k = 0; k < 2; ++k) dst[m][k] = *(const PG8_LAS bf16x8*)(lds + PG8_SA(b, h) + aoff + m * 2048 + k * 1024); } while (0)
; #define PG8_MMA(ai, bj, At, Bt) do { __builtin_amdgcn_s_setprio(1); _Pragma("unroll") for (int m = 0; m < 4; ++m) _Pragma("unroll") for (int n = 0; n < 2; ++n) _Pragma("unroll") for (int k = 0; k < 2; ++k) \
;         acc[ai][bj][m][n] = __builtin_amdgcn_mfma_f32_16x16x32_bf16(Bt[n][k], At[m][k], acc[ai][bj][m][n], 0, 0, 0); __builtin_amdgcn_s_setprio(0); } while (0)
; #define PG8_WAIT_V(n) asm volatile("s_waitcnt vmcnt(" #n ")" ::: "memory")
; #define PG8_WAIT_L(n) asm volatile("s_waitcnt lgkmcnt(" #n ")" ::: "memory")
; #define PG8_BAR __builtin_amdgcn_s_barrier()
; #define PG8_SCHED __builtin_amdgcn_sched_barrier(0)
; template <class Epi, class Sched, bool ALIGN_EPI = false, bool SP2 = false>
; __device__ __forceinline__ void gemm_phase(PG8_LAS unsigned char* lds, const Gemm g, const Sched& S, const Epi& E) {
;     ...
;             PG8_WAIT_V(8); PG8_WAIT_L(0); PG8_BAR; PG8_MMA(0, 0, At, B0); PG8_MMA(0, 1, At, B1); PG8_BAR; PG8_SCHED;
;             PG8_LDA(At, 0, 1); PG8_STAGE(PG8_SB(0, 0), b2, voffB); PG8_STAGE(PG8_SB(0, 1), b2 + hstep, voffB); PG8_STAGE(PG8_SA(0, 0), a2, voffA);
;             PG8_WAIT_V(8); PG8_WAIT_L(0); PG8_BAR; PG8_MMA(1, 0, At, B0); PG8_MMA(1, 1, At, B1); PG8_BAR; PG8_SCHED;
.Lvw_24:
	s_waitcnt lgkmcnt(0)
	s_barrier
	s_setprio 1
	s_waitcnt lgkmcnt(0)
	v_mfma_f32_16x16x32_bf16 v[132:135], v[64:67], v[188:191], v[132:135]
	v_mfma_f32_16x16x32_bf16 v[128:131], v[136:139], v[188:191], v[128:131]
	v_mfma_f32_16x16x32_bf16 v[112:115], v[136:139], v[198:201], v[112:115]
	v_mfma_f32_16x16x32_bf16 v[116:119], v[64:67], v[198:201], v[116:119]
	v_mfma_f32_16x16x32_bf16 v[100:103], v[64:67], v[206:209], v[100:103]
	v_mfma_f32_16x16x32_bf16 v[96:99], v[136:139], v[206:209], v[96:99]
	v_mfma_f32_16x16x32_bf16 v[80:83], v[136:139], v[214:217], v[80:83]
	v_mfma_f32_16x16x32_bf16 v[84:87], v[64:67], v[214:217], v[84:87]
	v_mfma_f32_16x16x32_bf16 v[132:135], v[68:71], v[194:197], v[132:135]
	v_mfma_f32_16x16x32_bf16 v[128:131], v[162:165], v[194:197], v[128:131]
	v_mfma_f32_16x16x32_bf16 v[112:115], v[162:165], v[202:205], v[112:115]
	v_mfma_f32_16x16x32_bf16 v[116:119], v[68:71], v[202:205], v[116:119]
	v_mfma_f32_16x16x32_bf16 v[100:103], v[68:71], v[210:213], v[100:103]
	v_mfma_f32_16x16x32_bf16 v[96:99], v[162:165], v[210:213], v[96:99]
	v_mfma_f32_16x16x32_bf16 v[80:83], v[162:165], v[218:221], v[80:83]
	v_mfma_f32_16x16x32_bf16 v[84:87], v[68:71], v[218:221], v[84:87]
	s_setprio 0
	s_setprio 1
	v_mfma_f32_16x16x32_bf16 v[124:127], v[172:175], v[188:191], v[124:127]
	v_mfma_f32_16x16x32_bf16 v[120:123], v[180:183], v[188:191], v[120:123]
	v_mfma_f32_16x16x32_bf16 v[104:107], v[180:183], v[198:201], v[104:107]
	v_mfma_f32_16x16x32_bf16 v[108:111], v[172:175], v[198:201], v[108:111]
	v_mfma_f32_16x16x32_bf16 v[92:95], v[172:175], v[206:209], v[92:95]
	v_mfma_f32_16x16x32_bf16 v[88:91], v[180:183], v[206:209], v[88:91]
	v_mfma_f32_16x16x32_bf16 v[72:75], v[180:183], v[214:217], v[72:75]
	v_mfma_f32_16x16x32_bf16 v[76:79], v[172:175], v[214:217], v[76:79]
	v_mfma_f32_16x16x32_bf16 v[124:127], v[176:179], v[194:197], v[124:127]
	v_mfma_f32_16x16x32_bf16 v[120:123], v[184:187], v[194:197], v[120:123]
	v_mfma_f32_16x16x32_bf16 v[104:107], v[184:187], v[202:205], v[104:107]
	v_mfma_f32_16x16x32_bf16 v[108:111], v[176:179], v[202:205], v[108:111]
	v_mfma_f32_16x16x32_bf16 v[92:95], v[176:179], v[210:213], v[92:95]
	v_mfma_f32_16x16x32_bf16 v[88:91], v[184:187], v[210:213], v[88:91]
	v_mfma_f32_16x16x32_bf16 v[72:75], v[184:187], v[218:221], v[72:75]
	v_mfma_f32_16x16x32_bf16 v[76:79], v[176:179], v[218:221], v[76:79]
	s_setprio 0
	s_waitcnt vmcnt(8)
	s_barrier
	s_add_i32 s45, s41, s29
	v_lshl_add_u64 v[222:223], s[22:23], 0, v[142:143]
	s_mov_b32 m0, s45
	ds_read_b128 v[188:191], v170 offset:16384
	ds_read_b128 v[194:197], v170 offset:17408
	ds_read_b128 v[198:201], v170 offset:18432
	ds_read_b128 v[202:205], v170 offset:19456
	ds_read_b128 v[206:209], v170 offset:20480
	ds_read_b128 v[210:213], v170 offset:21504
	ds_read_b128 v[214:217], v170 offset:22528
	ds_read_b128 v[218:221], v170 offset:23552
	global_load_lds_dwordx4 v[222:223], off
	s_add_i32 m0, s45, 0x2000
	s_add_u32 s46, s22, 0x80000
	v_lshl_add_u64 v[224:225], s[22:23], 0, v[146:147]
	s_addc_u32 s47, s23, 0
	s_add_i32 s45, s42, s29
	global_load_lds_dwordx4 v[224:225], off
	v_lshl_add_u64 v[226:227], s[46:47], 0, v[142:143]
	s_mov_b32 m0, s45
	v_lshl_add_u64 v[228:229], s[24:25], 0, v[144:145]
	global_load_lds_dwordx4 v[226:227], off
	v_lshl_add_u64 v[226:227], s[46:47], 0, v[146:147]
	s_add_i32 m0, s45, 0x2000
	s_nop 0
	global_load_lds_dwordx4 v[226:227], off
	v_lshl_add_u64 v[226:227], s[24:25], 0, v[140:141]
	s_mov_b32 m0, s30
	s_nop 0
	global_load_lds_dwordx4 v[226:227], off
	s_mov_b32 m0, s31
	s_nop 0
	global_load_lds_dwordx4 v[228:229], off
	s_mov_b64 vcc, s[98:99]
	s_cbranch_vccnz .Lvw_25
	s_waitcnt vmcnt(8)
.Lvw_25:
	s_waitcnt lgkmcnt(0)
	s_barrier
	s_setprio 1
	s_waitcnt lgkmcnt(0)
	v_mfma_f32_16x16x32_bf16 v[60:63], v[64:67], v[188:191], v[60:63]
	v_mfma_f32_16x16x32_bf16 v[56:59], v[136:139], v[188:191], v[56:59]
	v_mfma_f32_16x16x32_bf16 v[40:43], v[136:139], v[198:201], v[40:43]
	v_mfma_f32_16x16x32_bf16 v[44:47], v[64:67], v[198:201], v[44:47]
	v_mfma_f32_16x16x32_bf16 v[28:31], v[64:67], v[206:209], v[28:31]
	v_mfma_f32_16x16x32_bf16 v[24:27], v[136:139], v[206:209], v[24:27]
	v_mfma_f32_16x16x32_bf16 v[8:11], v[136:139], v[214:217], v[8:11]
	v_mfma_f32_16x16x32_bf16 v[12:15], v[64:67], v[214:217], v[12:15]
	v_mfma_f32_16x16x32_bf16 v[60:63], v[68:71], v[194:197], v[60:63]
	v_mfma_f32_16x16x32_bf16 v[56:59], v[162:165], v[194:197], v[56:59]
	v_mfma_f32_16x16x32_bf16 v[40:43], v[162:165], v[202:205], v[40:43]
	v_mfma_f32_16x16x32_bf16 v[44:47], v[68:71], v[202:205], v[44:47]
	v_mfma_f32_16x16x32_bf16 v[28:31], v[68:71], v[210:213], v[28:31]
	v_mfma_f32_16x16x32_bf16 v[24:27], v[162:165], v[210:213], v[24:27]
	v_mfma_f32_16x16x32_bf16 v[8:11], v[162:165], v[218:221], v[8:11]
	v_mfma_f32_16x16x32_bf16 v[12:15], v[68:71], v[218:221], v[12:15]
	s_setprio 0
	s_setprio 1
	v_mfma_f32_16x16x32_bf16 v[52:55], v[172:175], v[188:191], v[52:55]
	v_mfma_f32_16x16x32_bf16 v[48:51], v[180:183], v[188:191], v[48:51]
	v_mfma_f32_16x16x32_bf16 v[32:35], v[180:183], v[198:201], v[32:35]
	v_mfma_f32_16x16x32_bf16 v[36:39], v[172:175], v[198:201], v[36:39]
	v_mfma_f32_16x16x32_bf16 v[20:23], v[172:175], v[206:209], v[20:23]
	v_mfma_f32_16x16x32_bf16 v[16:19], v[180:183], v[206:209], v[16:19]
	v_mfma_f32_16x16x32_bf16 v[0:3], v[180:183], v[214:217], v[0:3]
	v_mfma_f32_16x16x32_bf16 v[4:7], v[172:175], v[214:217], v[4:7]
	v_mfma_f32_16x16x32_bf16 v[52:55], v[176:179], v[194:197], v[52:55]
	v_mfma_f32_16x16x32_bf16 v[48:51], v[184:187], v[194:197], v[48:51]
	v_mfma_f32_16x16x32_bf16 v[32:35], v[184:187], v[202:205], v[32:35]
	v_mfma_f32_16x16x32_bf16 v[36:39], v[176:179], v[202:205], v[36:39]
	v_mfma_f32_16x16x32_bf16 v[20:23], v[176:179], v[210:213], v[20:23]
	v_mfma_f32_16x16x32_bf16 v[16:19], v[184:187], v[210:213], v[16:19]
	v_mfma_f32_16x16x32_bf16 v[0:3], v[184:187], v[218:221], v[0:3]
	v_mfma_f32_16x16x32_bf16 v[4:7], v[176:179], v[218:221], v[4:7]
	s_setprio 0
	s_waitcnt vmcnt(8)
	s_barrier
; #define PG8_STAGE(bufoff, gbase, voff) do { _Pragma("unroll") for (int _i = 0; _i < 2; ++_i) \
;         __builtin_amdgcn_global_load_lds((const unsigned*)((const char*)(gbase) + (voff)[_i]), (PG8_LAS unsigned*)(lds + (bufoff) + ldsw + _i * 8192), 16, 0, 0); } while (0)
; #define PG8_LDA(dst, b, h) do { _Pragma("unroll") for (int m = 0; m < 4; ++m) _Pragma("unroll") for (int k = 0; k < 2; ++k) dst[m][k] = *(const PG8_LAS bf16x8*)(lds + PG8_SA(b, h) + aoff + m * 2048 + k * 1024); } while (0)
; #define PG8_LDB(dst, b, h) do { _Pragma("unroll") for (int n = 0; n < 2; ++n) _Pragma("unroll") for (int k = 0; k < 2; ++k) dst[n][k] = *(const PG8_LAS bf16x8*)(lds + PG8_SB(b, h) + boff + n * 2048 + k * 1024); } while (0)
; #define PG8_MMA(ai, bj, At, Bt) do { __builtin_amdgcn_s_setprio(1); _Pragma("unroll") for (int m = 0; m < 4; ++m) _Pragma("unroll") for (int n = 0; n < 2; ++n) _Pragma("unroll") for (int k = 0; k < 2; ++k) \
;         acc[ai][bj][m][n] = __builtin_amdgcn_mfma_f32_16x16x32_bf16(Bt[n][k], At[m][k], acc[ai][bj][m][n], 0, 0, 0); __builtin_amdgcn_s_setprio(0); } while (0)
; #define PG8_WAIT_V(n) asm volatile("s_waitcnt vmcnt(" #n ")" ::: "memory")
; #define PG8_WAIT_L(n) asm volatile("s_waitcnt lgkmcnt(" #n ")" ::: "memory")
; #define PG8_BAR __builtin_amdgcn_s_barrier()
; #define PG8_SCHED __builtin_amdgcn_sched_barrier(0)
; template <class Epi, class Sched, bool ALIGN_EPI = false, bool SP2 = false>
; __device__ __forceinline__ void gemm_phase(PG8_LAS unsigned char* lds, const Gemm g, const Sched& S, const Epi& E) {
;     ...
;             PG8_LDB(B0, 1, 0); PG8_LDB(B1, 1, 1); PG8_SCHED; PG8_LDA(At, 1, 0); PG8_STAGE(PG8_SA(0, 1), a2 + hstep, voffA);
;             PG8_WAIT_V(8); PG8_WAIT_L(0); PG8_BAR; PG8_MMA(0, 0, At, B0); PG8_MMA(0, 1, At, B1); PG8_BAR; PG8_SCHED;
;             PG8_LDA(At, 1, 1); PG8_STAGE(PG8_SB(1, 0), b3, voffB); PG8_STAGE(PG8_SB(1, 1), b3 + hstep, voffB); PG8_STAGE(PG8_SA(1, 0), a3, voffA);
	s_add_i32 s45, 0, 0x18000
	s_add_i32 s46, 0, 0x1c000
	v_add_u32_e32 v162, s45, v167
	v_add_u32_e32 v184, s46, v167
	ds_read_b128 v[64:67], v162
	ds_read_b128 v[68:71], v162 offset:1024
	ds_read_b128 v[136:139], v162 offset:2048
	ds_read_b128 v[162:165], v162 offset:3072
	ds_read_b128 v[172:175], v184
	ds_read_b128 v[176:179], v184 offset:1024
	ds_read_b128 v[180:183], v184 offset:2048
	ds_read_b128 v[184:187], v184 offset:3072
	s_add_u32 s24, s24, 0x80000
	s_addc_u32 s25, s25, 0
	s_mov_b32 m0, s34
	v_lshl_add_u64 v[230:231], s[24:25], 0, v[140:141]
	ds_read_b128 v[188:191], v170 offset:32768
	ds_read_b128 v[194:197], v170 offset:33792
	ds_read_b128 v[198:201], v170 offset:34816
	ds_read_b128 v[202:205], v170 offset:35840
	ds_read_b128 v[206:209], v170 offset:36864
	ds_read_b128 v[210:213], v170 offset:37888
	ds_read_b128 v[214:217], v170 offset:38912
	ds_read_b128 v[218:221], v170 offset:39936
	global_load_lds_dwordx4 v[230:231], off
	v_lshl_add_u64 v[230:231], s[24:25], 0, v[144:145]
	s_mov_b32 m0, s35
	s_nop 0
	global_load_lds_dwordx4 v[230:231], off
	s_mov_b64 vcc, s[98:99]
	s_cbranch_vccnz .Lvw_26
	s_waitcnt vmcnt(8)
.Lvw_26:
	s_waitcnt lgkmcnt(0)
	s_barrier
	s_setprio 1
	s_waitcnt lgkmcnt(0)
	v_mfma_f32_16x16x32_bf16 v[132:135], v[64:67], v[188:191], v[132:135]
	v_mfma_f32_16x16x32_bf16 v[128:131], v[136:139], v[188:191], v[128:131]
	v_mfma_f32_16x16x32_bf16 v[112:115], v[136:139], v[198:201], v[112:115]
	v_mfma_f32_16x16x32_bf16 v[116:119], v[64:67], v[198:201], v[116:119]
	v_mfma_f32_16x16x32_bf16 v[100:103], v[64:67], v[206:209], v[100:103]
	v_mfma_f32_16x16x32_bf16 v[96:99], v[136:139], v[206:209], v[96:99]
	v_mfma_f32_16x16x32_bf16 v[80:83], v[136:139], v[214:217], v[80:83]
	v_mfma_f32_16x16x32_bf16 v[84:87], v[64:67], v[214:217], v[84:87]
	v_mfma_f32_16x16x32_bf16 v[132:135], v[68:71], v[194:197], v[132:135]
	v_mfma_f32_16x16x32_bf16 v[128:131], v[162:165], v[194:197], v[128:131]
	v_mfma_f32_16x16x32_bf16 v[112:115], v[162:165], v[202:205], v[112:115]
	v_mfma_f32_16x16x32_bf16 v[116:119], v[68:71], v[202:205], v[116:119]
	v_mfma_f32_16x16x32_bf16 v[100:103], v[68:71], v[210:213], v[100:103]
	v_mfma_f32_16x16x32_bf16 v[96:99], v[162:165], v[210:213], v[96:99]
	v_mfma_f32_16x16x32_bf16 v[80:83], v[162:165], v[218:221], v[80:83]
	v_mfma_f32_16x16x32_bf16 v[84:87], v[68:71], v[218:221], v[84:87]
	s_setprio 0
	s_setprio 1
	v_mfma_f32_16x16x32_bf16 v[124:127], v[172:175], v[188:191], v[124:127]
	v_mfma_f32_16x16x32_bf16 v[120:123], v[180:183], v[188:191], v[120:123]
	v_mfma_f32_16x16x32_bf16 v[104:107], v[180:183], v[198:201], v[104:107]
	v_mfma_f32_16x16x32_bf16 v[108:111], v[172:175], v[198:201], v[108:111]
	v_mfma_f32_16x16x32_bf16 v[92:95], v[172:175], v[206:209], v[92:95]
	v_mfma_f32_16x16x32_bf16 v[88:91], v[180:183], v[206:209], v[88:91]
	v_mfma_f32_16x16x32_bf16 v[72:75], v[180:183], v[214:217], v[72:75]
	v_mfma_f32_16x16x32_bf16 v[76:79], v[172:175], v[214:217], v[76:79]
	v_mfma_f32_16x16x32_bf16 v[124:127], v[176:179], v[194:197], v[124:127]
	v_mfma_f32_16x16x32_bf16 v[120:123], v[184:187], v[194:197], v[120:123]
	v_mfma_f32_16x16x32_bf16 v[104:107], v[184:187], v[202:205], v[104:107]
	v_mfma_f32_16x16x32_bf16 v[108:111], v[176:179], v[202:205], v[108:111]
	v_mfma_f32_16x16x32_bf16 v[92:95], v[176:179], v[210:213], v[92:95]
	v_mfma_f32_16x16x32_bf16 v[88:91], v[184:187], v[210:213], v[88:91]
	v_mfma_f32_16x16x32_bf16 v[72:75], v[184:187], v[218:221], v[72:75]
	v_mfma_f32_16x16x32_bf16 v[76:79], v[176:179], v[218:221], v[76:79]
	s_setprio 0
	s_waitcnt vmcnt(8)
	s_barrier
	s_add_i32 s24, s45, s29
	v_lshl_add_u64 v[222:223], v[222:223], 0, s[8:9]
	s_mov_b32 m0, s24
	ds_read_b128 v[188:191], v170 offset:49152
	ds_read_b128 v[194:197], v170 offset:50176
	ds_read_b128 v[198:201], v170 offset:51200
	ds_read_b128 v[202:205], v170 offset:52224
	ds_read_b128 v[206:209], v170 offset:53248
	ds_read_b128 v[210:213], v170 offset:54272
	ds_read_b128 v[214:217], v170 offset:55296
	ds_read_b128 v[218:221], v170 offset:56320
	global_load_lds_dwordx4 v[222:223], off
	s_add_i32 m0, s24, 0x2000
	s_add_u32 s22, s22, 0x80080
	v_lshl_add_u64 v[222:223], v[224:225], 0, s[8:9]
	s_addc_u32 s23, s23, 0
	s_add_i32 s24, s46, s29
	global_load_lds_dwordx4 v[222:223], off
	v_lshl_add_u64 v[222:223], s[22:23], 0, v[142:143]
	s_mov_b32 m0, s24
	s_nop 0
	global_load_lds_dwordx4 v[222:223], off
	v_lshl_add_u64 v[222:223], s[22:23], 0, v[146:147]
	s_add_i32 m0, s24, 0x2000
	s_nop 0
	global_load_lds_dwordx4 v[222:223], off
	v_lshl_add_u64 v[222:223], v[226:227], 0, s[8:9]
	s_mov_b32 m0, s37
	s_nop 0
	global_load_lds_dwordx4 v[222:223], off
	v_lshl_add_u64 v[222:223], v[228:229], 0, s[8:9]
	s_mov_b32 m0, s38
	s_nop 0
	global_load_lds_dwordx4 v[222:223], off
	s_mov_b64 vcc, s[98:99]
	s_cbranch_vccnz .Lvw_27
	s_waitcnt vmcnt(8)
; #define PG8_STAGE(bufoff, gbase, voff) do { _Pragma("unroll") for (int _i = 0; _i < 2; ++_i) \
;         __builtin_amdgcn_global_load_lds((const unsigned*)((const char*)(gbase) + (voff)[_i]), (PG8_LAS unsigned*)(lds + (bufoff) + ldsw + _i * 8192), 16, 0, 0); } while (0)
; #define PG8_LDA(dst, b, h) do { _Pragma("unroll") for (int m = 0; m < 4; ++m) _Pragma("unroll") for (int k = 0; k < 2; ++k) dst[m][k] = *(const PG8_LAS bf16x8*)(lds + PG8_SA(b, h) + aoff + m * 2048 + k * 1024); } while (0)
; #define PG8_LDB(dst, b, h) do { _Pragma("unroll") for (int n = 0; n < 2; ++n) _Pragma("unroll") for (int k = 0; k < 2; ++k) dst[n][k] = *(const PG8_LAS bf16x8*)(lds + PG8_SB(b, h) + boff + n * 2048 + k * 1024); } while (0)
; template <class Epi, class Sched, bool ALIGN_EPI = false, bool SP2 = false>
; __device__ __forceinline__ void gemm_phase(PG8_LAS unsigned char* lds, const Gemm g, const Sched& S, const Epi& E) {
;     ...
;             PG8_WAIT_V(8); PG8_WAIT_L(0); PG8_BAR; PG8_MMA(1, 0, At, B0); PG8_MMA(1, 1, At, B1); PG8_BAR; PG8_SCHED;
;             } else {
;             PG8_LDB(B0, 0, 0); PG8_SCHED; PG8_LDA(At, 0, 0); PG8_STAGE(PG8_SA(1, 1), a1 + hstep, voffA);
;             PG8_WAIT_L(8); PG8_BAR; PG8_WAIT_L(0); PG8_MMA(0, 0, At, B0); PG8_BAR; PG8_SCHED;
;             PG8_LDB(B1, 0, 1); PG8_STAGE(PG8_SB(0, 0), b2, voffB);
;             PG8_BAR; PG8_WAIT_L(0); PG8_MMA(0, 1, At, B1); PG8_BAR;
;             PG8_LDA(At, 0, 1); PG8_STAGE(PG8_SA(0, 0), a2, voffA);
;             PG8_BAR; PG8_WAIT_L(0); PG8_MMA(1, 0, At, B0); PG8_BAR; PG8_SCHED;
;             PG8_STAGE(PG8_SB(0, 1), b2 + hstep, voffB);
;             PG8_WAIT_V(6); PG8_BAR; PG8_MMA(1, 1, At, B1); PG8_BAR;
;             PG8_LDB(B0, 1, 0); PG8_SCHED; PG8_LDA(At, 1, 0); PG8_STAGE(PG8_SA(0, 1), a2 + hstep, voffA);
;             PG8_WAIT_L(8); PG8_BAR; PG8_WAIT_L(0); PG8_MMA(0, 0, At, B0); PG8_BAR; PG8_SCHED;
;             PG8_LDB(B1, 1, 1); PG8_STAGE(PG8_SB(1, 0), b3, voffB);
;             PG8_BAR; PG8_WAIT_L(0); PG8_MMA(0, 1, At, B1); PG8_BAR;
;             PG8_LDA(At, 1, 1); PG8_STAGE(PG8_SA(1, 0), a3, voffA);
;             PG8_BAR; PG8_WAIT_L(0); PG8_MMA(1, 0, At, B0); PG8_BAR; PG8_SCHED;
;             PG8_STAGE(PG8_SB(1, 1), b3 + hstep, voffB);
;             PG8_WAIT_V(6); PG8_BAR; PG8_MMA(1, 1, At, B1); PG8_BAR;
;             }
;         }
;         if constexpr (ALIGN_EPI) { if (wr == 0) PG8_BAR; }
.Lvw_27:
	s_waitcnt lgkmcnt(0)
	s_barrier
	s_setprio 1
	s_waitcnt lgkmcnt(0)
	v_mfma_f32_16x16x32_bf16 v[60:63], v[64:67], v[188:191], v[60:63]
	v_mfma_f32_16x16x32_bf16 v[56:59], v[136:139], v[188:191], v[56:59]
	v_mfma_f32_16x16x32_bf16 v[40:43], v[136:139], v[198:201], v[40:43]
	v_mfma_f32_16x16x32_bf16 v[44:47], v[64:67], v[198:201], v[44:47]
	v_mfma_f32_16x16x32_bf16 v[28:31], v[64:67], v[206:209], v[28:31]
	v_mfma_f32_16x16x32_bf16 v[24:27], v[136:139], v[206:209], v[24:27]
	v_mfma_f32_16x16x32_bf16 v[8:11], v[136:139], v[214:217], v[8:11]
	v_mfma_f32_16x16x32_bf16 v[12:15], v[64:67], v[214:217], v[12:15]
	v_mfma_f32_16x16x32_bf16 v[60:63], v[68:71], v[194:197], v[60:63]
	v_mfma_f32_16x16x32_bf16 v[56:59], v[162:165], v[194:197], v[56:59]
	v_mfma_f32_16x16x32_bf16 v[40:43], v[162:165], v[202:205], v[40:43]
	v_mfma_f32_16x16x32_bf16 v[44:47], v[68:71], v[202:205], v[44:47]
	v_mfma_f32_16x16x32_bf16 v[28:31], v[68:71], v[210:213], v[28:31]
	v_mfma_f32_16x16x32_bf16 v[24:27], v[162:165], v[210:213], v[24:27]
	v_mfma_f32_16x16x32_bf16 v[8:11], v[162:165], v[218:221], v[8:11]
	v_mfma_f32_16x16x32_bf16 v[12:15], v[68:71], v[218:221], v[12:15]
	s_setprio 0
	s_setprio 1
	v_mfma_f32_16x16x32_bf16 v[52:55], v[172:175], v[188:191], v[52:55]
	v_mfma_f32_16x16x32_bf16 v[48:51], v[180:183], v[188:191], v[48:51]
	v_mfma_f32_16x16x32_bf16 v[32:35], v[180:183], v[198:201], v[32:35]
	v_mfma_f32_16x16x32_bf16 v[36:39], v[172:175], v[198:201], v[36:39]
	v_mfma_f32_16x16x32_bf16 v[20:23], v[172:175], v[206:209], v[20:23]
	v_mfma_f32_16x16x32_bf16 v[16:19], v[180:183], v[206:209], v[16:19]
	v_mfma_f32_16x16x32_bf16 v[0:3], v[180:183], v[214:217], v[0:3]
	v_mfma_f32_16x16x32_bf16 v[4:7], v[172:175], v[214:217], v[4:7]
	v_mfma_f32_16x16x32_bf16 v[52:55], v[176:179], v[194:197], v[52:55]
	v_mfma_f32_16x16x32_bf16 v[48:51], v[184:187], v[194:197], v[48:51]
	v_mfma_f32_16x16x32_bf16 v[32:35], v[184:187], v[202:205], v[32:35]
	v_mfma_f32_16x16x32_bf16 v[36:39], v[176:179], v[202:205], v[36:39]
	v_mfma_f32_16x16x32_bf16 v[20:23], v[176:179], v[210:213], v[20:23]
	v_mfma_f32_16x16x32_bf16 v[16:19], v[184:187], v[210:213], v[16:19]
	v_mfma_f32_16x16x32_bf16 v[0:3], v[184:187], v[218:221], v[0:3]
	v_mfma_f32_16x16x32_bf16 v[4:7], v[176:179], v[218:221], v[4:7]
	s_setprio 0
	s_waitcnt vmcnt(8)
	s_barrier
	s_add_i32 s44, s44, 2
	s_add_u32 s20, s20, 0x100
	s_addc_u32 s21, s21, 0
	s_add_u32 s33, s33, 0x100
	s_addc_u32 s43, s43, 0
	s_cmp_gt_u32 s44, 29
	s_cbranch_scc0 .LBB0_797
	s_and_b64 vcc, exec, s[10:11]
	s_cbranch_vccz .LBB0_800
	s_barrier

; #define PG8_STAGE(bufoff, gbase, voff) do { _Pragma("unroll") for (int _i = 0; _i < 2; ++_i) \
;         __builtin_amdgcn_global_load_lds((const unsigned*)((const char*)(gbase) + (voff)[_i]), (PG8_LAS unsigned*)(lds + (bufoff) + ldsw + _i * 8192), 16, 0, 0); } while (0)
; #define PG8_LDA(dst, b, h) do { _Pragma("unroll") for (int m = 0; m < 4; ++m) _Pragma("unroll") for (int k = 0; k < 2; ++k) dst[m][k] = *(const PG8_LAS bf16x8*)(lds + PG8_SA(b, h) + aoff + m * 2048 + k * 1024); } while (0)
; #define PG8_MMA(ai, bj, At, Bt) do { __builtin_amdgcn_s_setprio(1); _Pragma("unroll") for (int m = 0; m < 4; ++m) _Pragma("unroll") for (int n = 0; n < 2; ++n) _Pragma("unroll") for (int k = 0; k < 2; ++k) \
;         acc[ai][bj][m][n] = __builtin_amdgcn_mfma_f32_16x16x32_bf16(Bt[n][k], At[m][k], acc[ai][bj][m][n], 0, 0, 0); __builtin_amdgcn_s_setprio(0); } while (0)
; #define PG8_WAIT_V(n) asm volatile("s_waitcnt vmcnt(" #n ")" ::: "memory")
; #define PG8_WAIT_L(n) asm volatile("s_waitcnt lgkmcnt(" #n ")" ::: "memory")
; #define PG8_BAR __builtin_amdgcn_s_barrier()
; #define PG8_SCHED __builtin_amdgcn_sched_barrier(0)
; template <class Epi, class Sched, bool ALIGN_EPI = false, bool SP2 = false>
; __device__ __forceinline__ void gemm_phase(PG8_LAS unsigned char* lds, const Gemm g, const Sched& S, const Epi& E) {
;     ...
;             PG8_WAIT_V(8); PG8_WAIT_L(0); PG8_BAR; PG8_MMA(0, 0, At, B0); PG8_MMA(0, 1, At, B1); PG8_BAR; PG8_SCHED;
;             PG8_LDA(At, 0, 1); PG8_STAGE(PG8_SB(0, 0), b2, voffB); PG8_STAGE(PG8_SB(0, 1), b2 + hstep, voffB); PG8_STAGE(PG8_SA(0, 0), a2, voffA);
;             PG8_WAIT_V(8); PG8_WAIT_L(0); PG8_BAR; PG8_MMA(1, 0, At, B0); PG8_MMA(1, 1, At, B1); PG8_BAR; PG8_SCHED;
.Lvw_28:
	s_waitcnt lgkmcnt(0)
	s_barrier
	s_setprio 1
	s_waitcnt lgkmcnt(0)
	v_mfma_f32_16x16x32_bf16 v[124:127], v[146:149], v[186:189], v[124:127]
	v_mfma_f32_16x16x32_bf16 v[120:123], v[162:165], v[186:189], v[120:123]
	v_mfma_f32_16x16x32_bf16 v[104:107], v[162:165], v[198:201], v[104:107]
	v_mfma_f32_16x16x32_bf16 v[108:111], v[146:149], v[198:201], v[108:111]
	v_mfma_f32_16x16x32_bf16 v[92:95], v[146:149], v[206:209], v[92:95]
	v_mfma_f32_16x16x32_bf16 v[88:91], v[162:165], v[206:209], v[88:91]
	v_mfma_f32_16x16x32_bf16 v[72:75], v[162:165], v[214:217], v[72:75]
	v_mfma_f32_16x16x32_bf16 v[76:79], v[146:149], v[214:217], v[76:79]
	v_mfma_f32_16x16x32_bf16 v[124:127], v[158:161], v[194:197], v[124:127]
	v_mfma_f32_16x16x32_bf16 v[120:123], v[166:169], v[194:197], v[120:123]
	v_mfma_f32_16x16x32_bf16 v[104:107], v[166:169], v[202:205], v[104:107]
	v_mfma_f32_16x16x32_bf16 v[108:111], v[158:161], v[202:205], v[108:111]
	v_mfma_f32_16x16x32_bf16 v[92:95], v[158:161], v[210:213], v[92:95]
	v_mfma_f32_16x16x32_bf16 v[88:91], v[166:169], v[210:213], v[88:91]
	v_mfma_f32_16x16x32_bf16 v[72:75], v[166:169], v[218:221], v[72:75]
	v_mfma_f32_16x16x32_bf16 v[76:79], v[158:161], v[218:221], v[76:79]
	s_setprio 0
	s_setprio 1
	v_mfma_f32_16x16x32_bf16 v[116:119], v[170:173], v[186:189], v[116:119]
	v_mfma_f32_16x16x32_bf16 v[112:115], v[178:181], v[186:189], v[112:115]
	v_mfma_f32_16x16x32_bf16 v[96:99], v[178:181], v[198:201], v[96:99]
	v_mfma_f32_16x16x32_bf16 v[100:103], v[170:173], v[198:201], v[100:103]
	v_mfma_f32_16x16x32_bf16 v[84:87], v[170:173], v[206:209], v[84:87]
	v_mfma_f32_16x16x32_bf16 v[80:83], v[178:181], v[206:209], v[80:83]
	v_mfma_f32_16x16x32_bf16 v[64:67], v[178:181], v[214:217], v[64:67]
	v_mfma_f32_16x16x32_bf16 v[68:71], v[170:173], v[214:217], v[68:71]
	v_mfma_f32_16x16x32_bf16 v[116:119], v[174:177], v[194:197], v[116:119]
	v_mfma_f32_16x16x32_bf16 v[112:115], v[182:185], v[194:197], v[112:115]
	v_mfma_f32_16x16x32_bf16 v[96:99], v[182:185], v[202:205], v[96:99]
	v_mfma_f32_16x16x32_bf16 v[100:103], v[174:177], v[202:205], v[100:103]
	v_mfma_f32_16x16x32_bf16 v[84:87], v[174:177], v[210:213], v[84:87]
	v_mfma_f32_16x16x32_bf16 v[80:83], v[182:185], v[210:213], v[80:83]
	v_mfma_f32_16x16x32_bf16 v[64:67], v[182:185], v[218:221], v[64:67]
	v_mfma_f32_16x16x32_bf16 v[68:71], v[174:177], v[218:221], v[68:71]
	s_setprio 0
	s_waitcnt vmcnt(8)
	s_barrier
	s_add_i32 s55, s46, s37
	v_lshl_add_u64 v[150:151], s[28:29], 0, v[130:131]
	s_mov_b32 m0, s55
	ds_read_b128 v[186:189], v157 offset:16384
	ds_read_b128 v[194:197], v157 offset:17408
	ds_read_b128 v[198:201], v157 offset:18432
	ds_read_b128 v[202:205], v157 offset:19456
	ds_read_b128 v[206:209], v157 offset:20480
	ds_read_b128 v[210:213], v157 offset:21504
	ds_read_b128 v[214:217], v157 offset:22528
	ds_read_b128 v[218:221], v157 offset:23552
	global_load_lds_dwordx4 v[150:151], off
	s_add_i32 m0, s55, 0x2000
	s_add_u32 s56, s28, 0x80000
	v_lshl_add_u64 v[190:191], s[28:29], 0, v[134:135]
	s_addc_u32 s57, s29, 0
	s_add_i32 s55, s47, s37
	global_load_lds_dwordx4 v[190:191], off
	v_lshl_add_u64 v[222:223], s[56:57], 0, v[130:131]
	s_mov_b32 m0, s55
	v_lshl_add_u64 v[224:225], s[30:31], 0, v[132:133]
	global_load_lds_dwordx4 v[222:223], off
	v_lshl_add_u64 v[222:223], s[56:57], 0, v[134:135]
	s_add_i32 m0, s55, 0x2000
	s_nop 0
	global_load_lds_dwordx4 v[222:223], off
	v_lshl_add_u64 v[222:223], s[30:31], 0, v[128:129]
	s_mov_b32 m0, s25
	s_nop 0
	global_load_lds_dwordx4 v[222:223], off
	s_mov_b32 m0, s38
	s_nop 0
	global_load_lds_dwordx4 v[224:225], off
	s_mov_b64 vcc, s[98:99]
	s_cbranch_vccnz .Lvw_29
	s_waitcnt vmcnt(8)
.Lvw_29:
	s_waitcnt lgkmcnt(0)
	s_barrier
	s_setprio 1
	s_waitcnt lgkmcnt(0)
	v_mfma_f32_16x16x32_bf16 v[60:63], v[146:149], v[186:189], v[60:63]
	v_mfma_f32_16x16x32_bf16 v[56:59], v[162:165], v[186:189], v[56:59]
	v_mfma_f32_16x16x32_bf16 v[40:43], v[162:165], v[198:201], v[40:43]
	v_mfma_f32_16x16x32_bf16 v[44:47], v[146:149], v[198:201], v[44:47]
	v_mfma_f32_16x16x32_bf16 v[28:31], v[146:149], v[206:209], v[28:31]
	v_mfma_f32_16x16x32_bf16 v[24:27], v[162:165], v[206:209], v[24:27]
	v_mfma_f32_16x16x32_bf16 v[8:11], v[162:165], v[214:217], v[8:11]
	v_mfma_f32_16x16x32_bf16 v[12:15], v[146:149], v[214:217], v[12:15]
	v_mfma_f32_16x16x32_bf16 v[60:63], v[158:161], v[194:197], v[60:63]
	v_mfma_f32_16x16x32_bf16 v[56:59], v[166:169], v[194:197], v[56:59]
	v_mfma_f32_16x16x32_bf16 v[40:43], v[166:169], v[202:205], v[40:43]
	v_mfma_f32_16x16x32_bf16 v[44:47], v[158:161], v[202:205], v[44:47]
	v_mfma_f32_16x16x32_bf16 v[28:31], v[158:161], v[210:213], v[28:31]
	v_mfma_f32_16x16x32_bf16 v[24:27], v[166:169], v[210:213], v[24:27]
	v_mfma_f32_16x16x32_bf16 v[8:11], v[166:169], v[218:221], v[8:11]
	v_mfma_f32_16x16x32_bf16 v[12:15], v[158:161], v[218:221], v[12:15]
	s_setprio 0
	s_setprio 1
	v_mfma_f32_16x16x32_bf16 v[52:55], v[170:173], v[186:189], v[52:55]
	v_mfma_f32_16x16x32_bf16 v[48:51], v[178:181], v[186:189], v[48:51]
	v_mfma_f32_16x16x32_bf16 v[32:35], v[178:181], v[198:201], v[32:35]
	v_mfma_f32_16x16x32_bf16 v[36:39], v[170:173], v[198:201], v[36:39]
	v_mfma_f32_16x16x32_bf16 v[20:23], v[170:173], v[206:209], v[20:23]
	v_mfma_f32_16x16x32_bf16 v[16:19], v[178:181], v[206:209], v[16:19]
	v_mfma_f32_16x16x32_bf16 v[0:3], v[178:181], v[214:217], v[0:3]
	v_mfma_f32_16x16x32_bf16 v[4:7], v[170:173], v[214:217], v[4:7]
	v_mfma_f32_16x16x32_bf16 v[52:55], v[174:177], v[194:197], v[52:55]
	v_mfma_f32_16x16x32_bf16 v[48:51], v[182:185], v[194:197], v[48:51]
	v_mfma_f32_16x16x32_bf16 v[32:35], v[182:185], v[202:205], v[32:35]
	v_mfma_f32_16x16x32_bf16 v[36:39], v[174:177], v[202:205], v[36:39]
	v_mfma_f32_16x16x32_bf16 v[20:23], v[174:177], v[210:213], v[20:23]
	v_mfma_f32_16x16x32_bf16 v[16:19], v[182:185], v[210:213], v[16:19]
	v_mfma_f32_16x16x32_bf16 v[0:3], v[182:185], v[218:221], v[0:3]
	v_mfma_f32_16x16x32_bf16 v[4:7], v[174:177], v[218:221], v[4:7]
	s_setprio 0
	s_waitcnt vmcnt(8)
	s_barrier
; #define PG8_STAGE(bufoff, gbase, voff) do { _Pragma("unroll") for (int _i = 0; _i < 2; ++_i) \
;         __builtin_amdgcn_global_load_lds((const unsigned*)((const char*)(gbase) + (voff)[_i]), (PG8_LAS unsigned*)(lds + (bufoff) + ldsw + _i * 8192), 16, 0, 0); } while (0)
; #define PG8_LDA(dst, b, h) do { _Pragma("unroll") for (int m = 0; m < 4; ++m) _Pragma("unroll") for (int k = 0; k < 2; ++k) dst[m][k] = *(const PG8_LAS bf16x8*)(lds + PG8_SA(b, h) + aoff + m * 2048 + k * 1024); } while (0)
; #define PG8_LDB(dst, b, h) do { _Pragma("unroll") for (int n = 0; n < 2; ++n) _Pragma("unroll") for (int k = 0; k < 2; ++k) dst[n][k] = *(const PG8_LAS bf16x8*)(lds + PG8_SB(b, h) + boff + n * 2048 + k * 1024); } while (0)
; #define PG8_MMA(ai, bj, At, Bt) do { __builtin_amdgcn_s_setprio(1); _Pragma("unroll") for (int m = 0; m < 4; ++m) _Pragma("unroll") for (int n = 0; n < 2; ++n) _Pragma("unroll") for (int k = 0; k < 2; ++k) \
;         acc[ai][bj][m][n] = __builtin_amdgcn_mfma_f32_16x16x32_bf16(Bt[n][k], At[m][k], acc[ai][bj][m][n], 0, 0, 0); __builtin_amdgcn_s_setprio(0); } while (0)
; #define PG8_WAIT_V(n) asm volatile("s_waitcnt vmcnt(" #n ")" ::: "memory")
; #define PG8_WAIT_L(n) asm volatile("s_waitcnt lgkmcnt(" #n ")" ::: "memory")
; #define PG8_BAR __builtin_amdgcn_s_barrier()
; #define PG8_SCHED __builtin_amdgcn_sched_barrier(0)
; template <class Epi, class Sched, bool ALIGN_EPI = false, bool SP2 = false>
; __device__ __forceinline__ void gemm_phase(PG8_LAS unsigned char* lds, const Gemm g, const Sched& S, const Epi& E) {
;     ...
;             PG8_LDB(B0, 1, 0); PG8_LDB(B1, 1, 1); PG8_SCHED; PG8_LDA(At, 1, 0); PG8_STAGE(PG8_SA(0, 1), a2 + hstep, voffA);
;             PG8_WAIT_V(8); PG8_WAIT_L(0); PG8_BAR; PG8_MMA(0, 0, At, B0); PG8_MMA(0, 1, At, B1); PG8_BAR; PG8_SCHED;
;             PG8_LDA(At, 1, 1); PG8_STAGE(PG8_SB(1, 0), b3, voffB); PG8_STAGE(PG8_SB(1, 1), b3 + hstep, voffB); PG8_STAGE(PG8_SA(1, 0), a3, voffA);
	s_add_i32 s55, 0, 0x18000
	v_add_u32_e32 v136, s55, v153
	s_add_i32 s56, 0, 0x1c000
	ds_read_b128 v[146:149], v136
	ds_read_b128 v[158:161], v136 offset:1024
	ds_read_b128 v[162:165], v136 offset:2048
	ds_read_b128 v[166:169], v136 offset:3072
	v_add_u32_e32 v136, s56, v153
	ds_read_b128 v[170:173], v136
	ds_read_b128 v[174:177], v136 offset:1024
	ds_read_b128 v[178:181], v136 offset:2048
	ds_read_b128 v[182:185], v136 offset:3072
	s_add_u32 s30, s30, 0x80000
	s_addc_u32 s31, s31, 0
	s_mov_b32 m0, s39
	v_lshl_add_u64 v[226:227], s[30:31], 0, v[128:129]
	ds_read_b128 v[186:189], v157 offset:32768
	ds_read_b128 v[194:197], v157 offset:33792
	ds_read_b128 v[198:201], v157 offset:34816
	ds_read_b128 v[202:205], v157 offset:35840
	ds_read_b128 v[206:209], v157 offset:36864
	ds_read_b128 v[210:213], v157 offset:37888
	ds_read_b128 v[214:217], v157 offset:38912
	ds_read_b128 v[218:221], v157 offset:39936
	global_load_lds_dwordx4 v[226:227], off
	v_lshl_add_u64 v[226:227], s[30:31], 0, v[132:133]
	s_mov_b32 m0, s40
	s_nop 0
	global_load_lds_dwordx4 v[226:227], off
	s_mov_b64 vcc, s[98:99]
	s_cbranch_vccnz .Lvw_30
	s_waitcnt vmcnt(8)
.Lvw_30:
	s_waitcnt lgkmcnt(0)
	s_barrier
	s_setprio 1
	s_waitcnt lgkmcnt(0)
	v_mfma_f32_16x16x32_bf16 v[124:127], v[146:149], v[186:189], v[124:127]
	v_mfma_f32_16x16x32_bf16 v[120:123], v[162:165], v[186:189], v[120:123]
	v_mfma_f32_16x16x32_bf16 v[104:107], v[162:165], v[198:201], v[104:107]
	v_mfma_f32_16x16x32_bf16 v[108:111], v[146:149], v[198:201], v[108:111]
	v_mfma_f32_16x16x32_bf16 v[92:95], v[146:149], v[206:209], v[92:95]
	v_mfma_f32_16x16x32_bf16 v[88:91], v[162:165], v[206:209], v[88:91]
	v_mfma_f32_16x16x32_bf16 v[72:75], v[162:165], v[214:217], v[72:75]
	v_mfma_f32_16x16x32_bf16 v[76:79], v[146:149], v[214:217], v[76:79]
	v_mfma_f32_16x16x32_bf16 v[124:127], v[158:161], v[194:197], v[124:127]
	v_mfma_f32_16x16x32_bf16 v[120:123], v[166:169], v[194:197], v[120:123]
	v_mfma_f32_16x16x32_bf16 v[104:107], v[166:169], v[202:205], v[104:107]
	v_mfma_f32_16x16x32_bf16 v[108:111], v[158:161], v[202:205], v[108:111]
	v_mfma_f32_16x16x32_bf16 v[92:95], v[158:161], v[210:213], v[92:95]
	v_mfma_f32_16x16x32_bf16 v[88:91], v[166:169], v[210:213], v[88:91]
	v_mfma_f32_16x16x32_bf16 v[72:75], v[166:169], v[218:221], v[72:75]
	v_mfma_f32_16x16x32_bf16 v[76:79], v[158:161], v[218:221], v[76:79]
	s_setprio 0
	s_setprio 1
	v_mfma_f32_16x16x32_bf16 v[116:119], v[170:173], v[186:189], v[116:119]
	v_mfma_f32_16x16x32_bf16 v[112:115], v[178:181], v[186:189], v[112:115]
	v_mfma_f32_16x16x32_bf16 v[96:99], v[178:181], v[198:201], v[96:99]
	v_mfma_f32_16x16x32_bf16 v[100:103], v[170:173], v[198:201], v[100:103]
	v_mfma_f32_16x16x32_bf16 v[84:87], v[170:173], v[206:209], v[84:87]
	v_mfma_f32_16x16x32_bf16 v[80:83], v[178:181], v[206:209], v[80:83]
	v_mfma_f32_16x16x32_bf16 v[64:67], v[178:181], v[214:217], v[64:67]
	v_mfma_f32_16x16x32_bf16 v[68:71], v[170:173], v[214:217], v[68:71]
	v_mfma_f32_16x16x32_bf16 v[116:119], v[174:177], v[194:197], v[116:119]
	v_mfma_f32_16x16x32_bf16 v[112:115], v[182:185], v[194:197], v[112:115]
	v_mfma_f32_16x16x32_bf16 v[96:99], v[182:185], v[202:205], v[96:99]
	v_mfma_f32_16x16x32_bf16 v[100:103], v[174:177], v[202:205], v[100:103]
	v_mfma_f32_16x16x32_bf16 v[84:87], v[174:177], v[210:213], v[84:87]
	v_mfma_f32_16x16x32_bf16 v[80:83], v[182:185], v[210:213], v[80:83]
	v_mfma_f32_16x16x32_bf16 v[64:67], v[182:185], v[218:221], v[64:67]
	v_mfma_f32_16x16x32_bf16 v[68:71], v[174:177], v[218:221], v[68:71]
	s_setprio 0
	s_waitcnt vmcnt(8)
	s_barrier
	s_add_i32 s30, s55, s37
	v_lshl_add_u64 v[150:151], v[150:151], 0, s[8:9]
	s_mov_b32 m0, s30
	ds_read_b128 v[186:189], v157 offset:49152
	ds_read_b128 v[194:197], v157 offset:50176
	ds_read_b128 v[198:201], v157 offset:51200
	ds_read_b128 v[202:205], v157 offset:52224
	ds_read_b128 v[206:209], v157 offset:53248
	ds_read_b128 v[210:213], v157 offset:54272
	ds_read_b128 v[214:217], v157 offset:55296
	ds_read_b128 v[218:221], v157 offset:56320
	global_load_lds_dwordx4 v[150:151], off
	s_add_i32 m0, s30, 0x2000
	s_add_u32 s28, s28, 0x80080
	v_lshl_add_u64 v[150:151], v[190:191], 0, s[8:9]
	s_addc_u32 s29, s29, 0
	s_add_i32 s30, s56, s37
	global_load_lds_dwordx4 v[150:151], off
	v_lshl_add_u64 v[150:151], s[28:29], 0, v[130:131]
	s_mov_b32 m0, s30
	s_nop 0
	global_load_lds_dwordx4 v[150:151], off
	v_lshl_add_u64 v[150:151], s[28:29], 0, v[134:135]
	s_add_i32 m0, s30, 0x2000
	s_nop 0
	global_load_lds_dwordx4 v[150:151], off
	v_lshl_add_u64 v[150:151], v[222:223], 0, s[8:9]
	s_mov_b32 m0, s42
	s_nop 0
	global_load_lds_dwordx4 v[150:151], off
	v_lshl_add_u64 v[150:151], v[224:225], 0, s[8:9]
	s_mov_b32 m0, s43
	s_nop 0
	global_load_lds_dwordx4 v[150:151], off
	s_mov_b64 vcc, s[98:99]
	s_cbranch_vccnz .Lvw_31
	s_waitcnt vmcnt(8)
; #define PG8_MMA(ai, bj, At, Bt) do { __builtin_amdgcn_s_setprio(1); _Pragma("unroll") for (int m = 0; m < 4; ++m) _Pragma("unroll") for (int n = 0; n < 2; ++n) _Pragma("unroll") for (int k = 0; k < 2; ++k) \
;         acc[ai][bj][m][n] = __builtin_amdgcn_mfma_f32_16x16x32_bf16(Bt[n][k], At[m][k], acc[ai][bj][m][n], 0, 0, 0); __builtin_amdgcn_s_setprio(0); } while (0)
; #define PG8_WAIT_V(n) asm volatile("s_waitcnt vmcnt(" #n ")" ::: "memory")
; #define PG8_WAIT_L(n) asm volatile("s_waitcnt lgkmcnt(" #n ")" ::: "memory")
; #define PG8_BAR __builtin_amdgcn_s_barrier()
; #define PG8_SCHED __builtin_amdgcn_sched_barrier(0)
; template <class Epi, class Sched, bool ALIGN_EPI = false, bool SP2 = false>
; __device__ __forceinline__ void gemm_phase(PG8_LAS unsigned char* lds, const Gemm g, const Sched& S, const Epi& E) {
;     ...
;             PG8_WAIT_V(8); PG8_WAIT_L(0); PG8_BAR; PG8_MMA(1, 0, At, B0); PG8_MMA(1, 1, At, B1); PG8_BAR; PG8_SCHED;
;     ...
;         if constexpr (ALIGN_EPI) { if (wr == 0) PG8_BAR; }
.Lvw_31:
	s_waitcnt lgkmcnt(0)
	s_barrier
	s_setprio 1
	s_waitcnt lgkmcnt(0)
	v_mfma_f32_16x16x32_bf16 v[60:63], v[146:149], v[186:189], v[60:63]
	v_mfma_f32_16x16x32_bf16 v[56:59], v[162:165], v[186:189], v[56:59]
	v_mfma_f32_16x16x32_bf16 v[40:43], v[162:165], v[198:201], v[40:43]
	v_mfma_f32_16x16x32_bf16 v[44:47], v[146:149], v[198:201], v[44:47]
	v_mfma_f32_16x16x32_bf16 v[28:31], v[146:149], v[206:209], v[28:31]
	v_mfma_f32_16x16x32_bf16 v[24:27], v[162:165], v[206:209], v[24:27]
	v_mfma_f32_16x16x32_bf16 v[8:11], v[162:165], v[214:217], v[8:11]
	v_mfma_f32_16x16x32_bf16 v[12:15], v[146:149], v[214:217], v[12:15]
	v_mfma_f32_16x16x32_bf16 v[60:63], v[158:161], v[194:197], v[60:63]
	v_mfma_f32_16x16x32_bf16 v[56:59], v[166:169], v[194:197], v[56:59]
	v_mfma_f32_16x16x32_bf16 v[40:43], v[166:169], v[202:205], v[40:43]
	v_mfma_f32_16x16x32_bf16 v[44:47], v[158:161], v[202:205], v[44:47]
	v_mfma_f32_16x16x32_bf16 v[28:31], v[158:161], v[210:213], v[28:31]
	v_mfma_f32_16x16x32_bf16 v[24:27], v[166:169], v[210:213], v[24:27]
	v_mfma_f32_16x16x32_bf16 v[8:11], v[166:169], v[218:221], v[8:11]
	v_mfma_f32_16x16x32_bf16 v[12:15], v[158:161], v[218:221], v[12:15]
	s_setprio 0
	s_setprio 1
	v_mfma_f32_16x16x32_bf16 v[52:55], v[170:173], v[186:189], v[52:55]
	v_mfma_f32_16x16x32_bf16 v[48:51], v[178:181], v[186:189], v[48:51]
	v_mfma_f32_16x16x32_bf16 v[32:35], v[178:181], v[198:201], v[32:35]
	v_mfma_f32_16x16x32_bf16 v[36:39], v[170:173], v[198:201], v[36:39]
	v_mfma_f32_16x16x32_bf16 v[20:23], v[170:173], v[206:209], v[20:23]
	v_mfma_f32_16x16x32_bf16 v[16:19], v[178:181], v[206:209], v[16:19]
	v_mfma_f32_16x16x32_bf16 v[0:3], v[178:181], v[214:217], v[0:3]
	v_mfma_f32_16x16x32_bf16 v[4:7], v[170:173], v[214:217], v[4:7]
	v_mfma_f32_16x16x32_bf16 v[52:55], v[174:177], v[194:197], v[52:55]
	v_mfma_f32_16x16x32_bf16 v[48:51], v[182:185], v[194:197], v[48:51]
	v_mfma_f32_16x16x32_bf16 v[32:35], v[182:185], v[202:205], v[32:35]
	v_mfma_f32_16x16x32_bf16 v[36:39], v[174:177], v[202:205], v[36:39]
	v_mfma_f32_16x16x32_bf16 v[20:23], v[174:177], v[210:213], v[20:23]
	v_mfma_f32_16x16x32_bf16 v[16:19], v[182:185], v[210:213], v[16:19]
	v_mfma_f32_16x16x32_bf16 v[0:3], v[182:185], v[218:221], v[0:3]
	v_mfma_f32_16x16x32_bf16 v[4:7], v[174:177], v[218:221], v[4:7]
	s_setprio 0
	s_waitcnt vmcnt(8)
	s_barrier
	s_add_i32 s54, s54, 2
	s_add_u32 s26, s26, 0x100
	s_addc_u32 s27, s27, 0
	s_add_u32 s52, s52, 0x100
	s_addc_u32 s53, s53, 0
	s_cmp_gt_u32 s54, 29
	s_cbranch_scc0 .LBB0_821
	s_and_b64 vcc, exec, s[10:11]
	s_cbranch_vccz .LBB0_824
	s_barrier

; #define PG8_STAGE(bufoff, gbase, voff) do { _Pragma("unroll") for (int _i = 0; _i < 2; ++_i) \
;         __builtin_amdgcn_global_load_lds((const unsigned*)((const char*)(gbase) + (voff)[_i]), (PG8_LAS unsigned*)(lds + (bufoff) + ldsw + _i * 8192), 16, 0, 0); } while (0)
; #define PG8_LDA(dst, b, h) do { _Pragma("unroll") for (int m = 0; m < 4; ++m) _Pragma("unroll") for (int k = 0; k < 2; ++k) dst[m][k] = *(const PG8_LAS bf16x8*)(lds + PG8_SA(b, h) + aoff + m * 2048 + k * 1024); } while (0)
; #define PG8_MMA(ai, bj, At, Bt) do { __builtin_amdgcn_s_setprio(1); _Pragma("unroll") for (int m = 0; m < 4; ++m) _Pragma("unroll") for (int n = 0; n < 2; ++n) _Pragma("unroll") for (int k = 0; k < 2; ++k) \
;         acc[ai][bj][m][n] = __builtin_amdgcn_mfma_f32_16x16x32_bf16(Bt[n][k], At[m][k], acc[ai][bj][m][n], 0, 0, 0); __builtin_amdgcn_s_setprio(0); } while (0)
; #define PG8_WAIT_V(n) asm volatile("s_waitcnt vmcnt(" #n ")" ::: "memory")
; #define PG8_WAIT_L(n) asm volatile("s_waitcnt lgkmcnt(" #n ")" ::: "memory")
; #define PG8_BAR __builtin_amdgcn_s_barrier()
; #define PG8_SCHED __builtin_amdgcn_sched_barrier(0)
; template <class Epi, class Sched, bool ALIGN_EPI = false, bool SP2 = false>
; __device__ __forceinline__ void gemm_phase(PG8_LAS unsigned char* lds, const Gemm g, const Sched& S, const Epi& E) {
;     ...
;             PG8_WAIT_V(8); PG8_WAIT_L(0); PG8_BAR; PG8_MMA(0, 0, At, B0); PG8_MMA(0, 1, At, B1); PG8_BAR; PG8_SCHED;
;             PG8_LDA(At, 0, 1); PG8_STAGE(PG8_SB(0, 0), b2, voffB); PG8_STAGE(PG8_SB(0, 1), b2 + hstep, voffB); PG8_STAGE(PG8_SA(0, 0), a2, voffA);
;             PG8_WAIT_V(8); PG8_WAIT_L(0); PG8_BAR; PG8_MMA(1, 0, At, B0); PG8_MMA(1, 1, At, B1); PG8_BAR; PG8_SCHED;
.Lvw_32:
	s_waitcnt lgkmcnt(0)
	s_barrier
	s_setprio 1
	s_waitcnt lgkmcnt(0)
	v_mfma_f32_16x16x32_bf16 v[124:127], v[128:131], v[182:185], v[124:127]
	v_mfma_f32_16x16x32_bf16 v[120:123], v[152:155], v[182:185], v[120:123]
	v_mfma_f32_16x16x32_bf16 v[112:115], v[152:155], v[194:197], v[112:115]
	v_mfma_f32_16x16x32_bf16 v[116:119], v[128:131], v[194:197], v[116:119]
	v_mfma_f32_16x16x32_bf16 v[92:95], v[128:131], v[202:205], v[92:95]
	v_mfma_f32_16x16x32_bf16 v[88:91], v[152:155], v[202:205], v[88:91]
	v_mfma_f32_16x16x32_bf16 v[76:79], v[152:155], v[210:213], v[76:79]
	v_mfma_f32_16x16x32_bf16 v[84:87], v[128:131], v[210:213], v[84:87]
	v_mfma_f32_16x16x32_bf16 v[124:127], v[132:135], v[186:189], v[124:127]
	v_mfma_f32_16x16x32_bf16 v[120:123], v[156:159], v[186:189], v[120:123]
	v_mfma_f32_16x16x32_bf16 v[112:115], v[156:159], v[198:201], v[112:115]
	v_mfma_f32_16x16x32_bf16 v[116:119], v[132:135], v[198:201], v[116:119]
	v_mfma_f32_16x16x32_bf16 v[92:95], v[132:135], v[206:209], v[92:95]
	v_mfma_f32_16x16x32_bf16 v[88:91], v[156:159], v[206:209], v[88:91]
	v_mfma_f32_16x16x32_bf16 v[76:79], v[156:159], v[214:217], v[76:79]
	v_mfma_f32_16x16x32_bf16 v[84:87], v[132:135], v[214:217], v[84:87]
	s_setprio 0
	s_setprio 1
	v_mfma_f32_16x16x32_bf16 v[108:111], v[166:169], v[182:185], v[108:111]
	v_mfma_f32_16x16x32_bf16 v[104:107], v[174:177], v[182:185], v[104:107]
	v_mfma_f32_16x16x32_bf16 v[96:99], v[174:177], v[194:197], v[96:99]
	v_mfma_f32_16x16x32_bf16 v[100:103], v[166:169], v[194:197], v[100:103]
	v_mfma_f32_16x16x32_bf16 v[80:83], v[166:169], v[202:205], v[80:83]
	v_mfma_f32_16x16x32_bf16 v[72:75], v[174:177], v[202:205], v[72:75]
	v_mfma_f32_16x16x32_bf16 v[64:67], v[174:177], v[210:213], v[64:67]
	v_mfma_f32_16x16x32_bf16 v[68:71], v[166:169], v[210:213], v[68:71]
	v_mfma_f32_16x16x32_bf16 v[108:111], v[170:173], v[186:189], v[108:111]
	v_mfma_f32_16x16x32_bf16 v[104:107], v[178:181], v[186:189], v[104:107]
	v_mfma_f32_16x16x32_bf16 v[96:99], v[178:181], v[198:201], v[96:99]
	v_mfma_f32_16x16x32_bf16 v[100:103], v[170:173], v[198:201], v[100:103]
	v_mfma_f32_16x16x32_bf16 v[80:83], v[170:173], v[206:209], v[80:83]
	v_mfma_f32_16x16x32_bf16 v[72:75], v[178:181], v[206:209], v[72:75]
	v_mfma_f32_16x16x32_bf16 v[64:67], v[178:181], v[214:217], v[64:67]
	v_mfma_f32_16x16x32_bf16 v[68:71], v[170:173], v[214:217], v[68:71]
	s_setprio 0
	s_waitcnt vmcnt(8)
	s_barrier
	s_add_i32 s51, s43, s37
	v_lshl_add_u64 v[190:191], s[30:31], 0, v[138:139]
	s_mov_b32 m0, s51
	ds_read_b128 v[182:185], v165 offset:16384
	ds_read_b128 v[186:189], v165 offset:17408
	ds_read_b128 v[194:197], v165 offset:18432
	ds_read_b128 v[198:201], v165 offset:19456
	ds_read_b128 v[202:205], v165 offset:20480
	ds_read_b128 v[206:209], v165 offset:21504
	ds_read_b128 v[210:213], v165 offset:22528
	ds_read_b128 v[214:217], v165 offset:23552
	global_load_lds_dwordx4 v[190:191], off
	s_add_i32 m0, s51, 0x2000
	s_add_u32 s52, s30, 0x80000
	v_lshl_add_u64 v[218:219], s[30:31], 0, v[142:143]
	s_addc_u32 s53, s31, 0
	s_add_i32 s51, s44, s37
	global_load_lds_dwordx4 v[218:219], off
	v_lshl_add_u64 v[220:221], s[52:53], 0, v[138:139]
	s_mov_b32 m0, s51
	v_lshl_add_u64 v[222:223], s[34:35], 0, v[140:141]
	global_load_lds_dwordx4 v[220:221], off
	v_lshl_add_u64 v[220:221], s[52:53], 0, v[142:143]
	s_add_i32 m0, s51, 0x2000
	s_nop 0
	global_load_lds_dwordx4 v[220:221], off
	v_lshl_add_u64 v[220:221], s[34:35], 0, v[136:137]
	s_mov_b32 m0, s27
	s_nop 0
	global_load_lds_dwordx4 v[220:221], off
	s_mov_b32 m0, s38
	s_nop 0
	global_load_lds_dwordx4 v[222:223], off
	s_mov_b64 vcc, s[98:99]
	s_cbranch_vccnz .Lvw_33
	s_waitcnt vmcnt(8)
.Lvw_33:
	s_waitcnt lgkmcnt(0)
	s_barrier
	s_setprio 1
	s_waitcnt lgkmcnt(0)
	v_mfma_f32_16x16x32_bf16 v[60:63], v[128:131], v[182:185], v[60:63]
	v_mfma_f32_16x16x32_bf16 v[56:59], v[152:155], v[182:185], v[56:59]
	v_mfma_f32_16x16x32_bf16 v[44:47], v[152:155], v[194:197], v[44:47]
	v_mfma_f32_16x16x32_bf16 v[52:55], v[128:131], v[194:197], v[52:55]
	v_mfma_f32_16x16x32_bf16 v[36:39], v[128:131], v[202:205], v[36:39]
	v_mfma_f32_16x16x32_bf16 v[24:27], v[152:155], v[202:205], v[24:27]
	v_mfma_f32_16x16x32_bf16 v[8:11], v[152:155], v[210:213], v[8:11]
	v_mfma_f32_16x16x32_bf16 v[16:19], v[128:131], v[210:213], v[16:19]
	v_mfma_f32_16x16x32_bf16 v[60:63], v[132:135], v[186:189], v[60:63]
	v_mfma_f32_16x16x32_bf16 v[56:59], v[156:159], v[186:189], v[56:59]
	v_mfma_f32_16x16x32_bf16 v[44:47], v[156:159], v[198:201], v[44:47]
	v_mfma_f32_16x16x32_bf16 v[52:55], v[132:135], v[198:201], v[52:55]
	v_mfma_f32_16x16x32_bf16 v[36:39], v[132:135], v[206:209], v[36:39]
	v_mfma_f32_16x16x32_bf16 v[24:27], v[156:159], v[206:209], v[24:27]
	v_mfma_f32_16x16x32_bf16 v[8:11], v[156:159], v[214:217], v[8:11]
	v_mfma_f32_16x16x32_bf16 v[16:19], v[132:135], v[214:217], v[16:19]
	s_setprio 0
	s_setprio 1
	v_mfma_f32_16x16x32_bf16 v[48:51], v[166:169], v[182:185], v[48:51]
	v_mfma_f32_16x16x32_bf16 v[40:43], v[174:177], v[182:185], v[40:43]
	v_mfma_f32_16x16x32_bf16 v[28:31], v[174:177], v[194:197], v[28:31]
	v_mfma_f32_16x16x32_bf16 v[32:35], v[166:169], v[194:197], v[32:35]
	v_mfma_f32_16x16x32_bf16 v[20:23], v[166:169], v[202:205], v[20:23]
	v_mfma_f32_16x16x32_bf16 v[12:15], v[174:177], v[202:205], v[12:15]
	v_mfma_f32_16x16x32_bf16 v[0:3], v[174:177], v[210:213], v[0:3]
	v_mfma_f32_16x16x32_bf16 v[4:7], v[166:169], v[210:213], v[4:7]
	v_mfma_f32_16x16x32_bf16 v[48:51], v[170:173], v[186:189], v[48:51]
	v_mfma_f32_16x16x32_bf16 v[40:43], v[178:181], v[186:189], v[40:43]
	v_mfma_f32_16x16x32_bf16 v[28:31], v[178:181], v[198:201], v[28:31]
	v_mfma_f32_16x16x32_bf16 v[32:35], v[170:173], v[198:201], v[32:35]
	v_mfma_f32_16x16x32_bf16 v[20:23], v[170:173], v[206:209], v[20:23]
	v_mfma_f32_16x16x32_bf16 v[12:15], v[178:181], v[206:209], v[12:15]
	v_mfma_f32_16x16x32_bf16 v[0:3], v[178:181], v[214:217], v[0:3]
	v_mfma_f32_16x16x32_bf16 v[4:7], v[170:173], v[214:217], v[4:7]
	s_setprio 0
	s_waitcnt vmcnt(8)
	s_barrier
; #define PG8_STAGE(bufoff, gbase, voff) do { _Pragma("unroll") for (int _i = 0; _i < 2; ++_i) \
;         __builtin_amdgcn_global_load_lds((const unsigned*)((const char*)(gbase) + (voff)[_i]), (PG8_LAS unsigned*)(lds + (bufoff) + ldsw + _i * 8192), 16, 0, 0); } while (0)
; #define PG8_LDA(dst, b, h) do { _Pragma("unroll") for (int m = 0; m < 4; ++m) _Pragma("unroll") for (int k = 0; k < 2; ++k) dst[m][k] = *(const PG8_LAS bf16x8*)(lds + PG8_SA(b, h) + aoff + m * 2048 + k * 1024); } while (0)
; #define PG8_LDB(dst, b, h) do { _Pragma("unroll") for (int n = 0; n < 2; ++n) _Pragma("unroll") for (int k = 0; k < 2; ++k) dst[n][k] = *(const PG8_LAS bf16x8*)(lds + PG8_SB(b, h) + boff + n * 2048 + k * 1024); } while (0)
; #define PG8_MMA(ai, bj, At, Bt) do { __builtin_amdgcn_s_setprio(1); _Pragma("unroll") for (int m = 0; m < 4; ++m) _Pragma("unroll") for (int n = 0; n < 2; ++n) _Pragma("unroll") for (int k = 0; k < 2; ++k) \
;         acc[ai][bj][m][n] = __builtin_amdgcn_mfma_f32_16x16x32_bf16(Bt[n][k], At[m][k], acc[ai][bj][m][n], 0, 0, 0); __builtin_amdgcn_s_setprio(0); } while (0)
; #define PG8_WAIT_V(n) asm volatile("s_waitcnt vmcnt(" #n ")" ::: "memory")
; #define PG8_WAIT_L(n) asm volatile("s_waitcnt lgkmcnt(" #n ")" ::: "memory")
; #define PG8_BAR __builtin_amdgcn_s_barrier()
; #define PG8_SCHED __builtin_amdgcn_sched_barrier(0)
; template <class Epi, class Sched, bool ALIGN_EPI = false, bool SP2 = false>
; __device__ __forceinline__ void gemm_phase(PG8_LAS unsigned char* lds, const Gemm g, const Sched& S, const Epi& E) {
;     ...
;             PG8_LDB(B0, 1, 0); PG8_LDB(B1, 1, 1); PG8_SCHED; PG8_LDA(At, 1, 0); PG8_STAGE(PG8_SA(0, 1), a2 + hstep, voffA);
;             PG8_WAIT_V(8); PG8_WAIT_L(0); PG8_BAR; PG8_MMA(0, 0, At, B0); PG8_MMA(0, 1, At, B1); PG8_BAR; PG8_SCHED;
;             PG8_LDA(At, 1, 1); PG8_STAGE(PG8_SB(1, 0), b3, voffB); PG8_STAGE(PG8_SB(1, 1), b3 + hstep, voffB); PG8_STAGE(PG8_SA(1, 0), a3, voffA);
	s_add_i32 s51, 0, 0x18000
	s_add_i32 s52, 0, 0x1c000
	v_add_u32_e32 v156, s51, v161
	v_add_u32_e32 v178, s52, v161
	ds_read_b128 v[128:131], v156
	ds_read_b128 v[132:135], v156 offset:1024
	ds_read_b128 v[152:155], v156 offset:2048
	ds_read_b128 v[156:159], v156 offset:3072
	ds_read_b128 v[166:169], v178
	ds_read_b128 v[170:173], v178 offset:1024
	ds_read_b128 v[174:177], v178 offset:2048
	ds_read_b128 v[178:181], v178 offset:3072
	s_add_u32 s34, s34, 0x80000
	s_addc_u32 s35, s35, 0
	s_mov_b32 m0, s39
	v_lshl_add_u64 v[224:225], s[34:35], 0, v[136:137]
	ds_read_b128 v[182:185], v165 offset:32768
	ds_read_b128 v[186:189], v165 offset:33792
	ds_read_b128 v[194:197], v165 offset:34816
	ds_read_b128 v[198:201], v165 offset:35840
	ds_read_b128 v[202:205], v165 offset:36864
	ds_read_b128 v[206:209], v165 offset:37888
	ds_read_b128 v[210:213], v165 offset:38912
	ds_read_b128 v[214:217], v165 offset:39936
	global_load_lds_dwordx4 v[224:225], off
	v_lshl_add_u64 v[224:225], s[34:35], 0, v[140:141]
	s_mov_b32 m0, s40
	s_nop 0
	global_load_lds_dwordx4 v[224:225], off
	s_mov_b64 vcc, s[98:99]
	s_cbranch_vccnz .Lvw_34
	s_waitcnt vmcnt(8)
.Lvw_34:
	s_waitcnt lgkmcnt(0)
	s_barrier
	s_setprio 1
	s_waitcnt lgkmcnt(0)
	v_mfma_f32_16x16x32_bf16 v[124:127], v[128:131], v[182:185], v[124:127]
	v_mfma_f32_16x16x32_bf16 v[120:123], v[152:155], v[182:185], v[120:123]
	v_mfma_f32_16x16x32_bf16 v[112:115], v[152:155], v[194:197], v[112:115]
	v_mfma_f32_16x16x32_bf16 v[116:119], v[128:131], v[194:197], v[116:119]
	v_mfma_f32_16x16x32_bf16 v[92:95], v[128:131], v[202:205], v[92:95]
	v_mfma_f32_16x16x32_bf16 v[88:91], v[152:155], v[202:205], v[88:91]
	v_mfma_f32_16x16x32_bf16 v[76:79], v[152:155], v[210:213], v[76:79]
	v_mfma_f32_16x16x32_bf16 v[84:87], v[128:131], v[210:213], v[84:87]
	v_mfma_f32_16x16x32_bf16 v[124:127], v[132:135], v[186:189], v[124:127]
	v_mfma_f32_16x16x32_bf16 v[120:123], v[156:159], v[186:189], v[120:123]
	v_mfma_f32_16x16x32_bf16 v[112:115], v[156:159], v[198:201], v[112:115]
	v_mfma_f32_16x16x32_bf16 v[116:119], v[132:135], v[198:201], v[116:119]
	v_mfma_f32_16x16x32_bf16 v[92:95], v[132:135], v[206:209], v[92:95]
	v_mfma_f32_16x16x32_bf16 v[88:91], v[156:159], v[206:209], v[88:91]
	v_mfma_f32_16x16x32_bf16 v[76:79], v[156:159], v[214:217], v[76:79]
	v_mfma_f32_16x16x32_bf16 v[84:87], v[132:135], v[214:217], v[84:87]
	s_setprio 0
	s_setprio 1
	v_mfma_f32_16x16x32_bf16 v[108:111], v[166:169], v[182:185], v[108:111]
	v_mfma_f32_16x16x32_bf16 v[104:107], v[174:177], v[182:185], v[104:107]
	v_mfma_f32_16x16x32_bf16 v[96:99], v[174:177], v[194:197], v[96:99]
	v_mfma_f32_16x16x32_bf16 v[100:103], v[166:169], v[194:197], v[100:103]
	v_mfma_f32_16x16x32_bf16 v[80:83], v[166:169], v[202:205], v[80:83]
	v_mfma_f32_16x16x32_bf16 v[72:75], v[174:177], v[202:205], v[72:75]
	v_mfma_f32_16x16x32_bf16 v[64:67], v[174:177], v[210:213], v[64:67]
	v_mfma_f32_16x16x32_bf16 v[68:71], v[166:169], v[210:213], v[68:71]
	v_mfma_f32_16x16x32_bf16 v[108:111], v[170:173], v[186:189], v[108:111]
	v_mfma_f32_16x16x32_bf16 v[104:107], v[178:181], v[186:189], v[104:107]
	v_mfma_f32_16x16x32_bf16 v[96:99], v[178:181], v[198:201], v[96:99]
	v_mfma_f32_16x16x32_bf16 v[100:103], v[170:173], v[198:201], v[100:103]
	v_mfma_f32_16x16x32_bf16 v[80:83], v[170:173], v[206:209], v[80:83]
	v_mfma_f32_16x16x32_bf16 v[72:75], v[178:181], v[206:209], v[72:75]
	v_mfma_f32_16x16x32_bf16 v[64:67], v[178:181], v[214:217], v[64:67]
	v_mfma_f32_16x16x32_bf16 v[68:71], v[170:173], v[214:217], v[68:71]
	s_setprio 0
	s_waitcnt vmcnt(8)
	s_barrier
	s_add_i32 s34, s51, s37
	v_lshl_add_u64 v[190:191], v[190:191], 0, s[0:1]
	s_mov_b32 m0, s34
	ds_read_b128 v[182:185], v165 offset:49152
	ds_read_b128 v[186:189], v165 offset:50176
	ds_read_b128 v[194:197], v165 offset:51200
	ds_read_b128 v[198:201], v165 offset:52224
	ds_read_b128 v[202:205], v165 offset:53248
	ds_read_b128 v[206:209], v165 offset:54272
	ds_read_b128 v[210:213], v165 offset:55296
	ds_read_b128 v[214:217], v165 offset:56320
	global_load_lds_dwordx4 v[190:191], off
	s_add_i32 m0, s34, 0x2000
	s_add_u32 s30, s30, 0x80080
	v_lshl_add_u64 v[190:191], v[218:219], 0, s[0:1]
	s_addc_u32 s31, s31, 0
	s_add_i32 s34, s52, s37
	global_load_lds_dwordx4 v[190:191], off
	v_lshl_add_u64 v[190:191], s[30:31], 0, v[138:139]
	s_mov_b32 m0, s34
	s_nop 0
	global_load_lds_dwordx4 v[190:191], off
	v_lshl_add_u64 v[190:191], s[30:31], 0, v[142:143]
	s_add_i32 m0, s34, 0x2000
	s_nop 0
	global_load_lds_dwordx4 v[190:191], off
	v_lshl_add_u64 v[190:191], v[220:221], 0, s[0:1]
	s_mov_b32 m0, s2
	s_nop 0
	global_load_lds_dwordx4 v[190:191], off
	v_lshl_add_u64 v[190:191], v[222:223], 0, s[0:1]
	s_mov_b32 m0, s3
	s_nop 0
	global_load_lds_dwordx4 v[190:191], off
	s_mov_b64 vcc, s[98:99]
	s_cbranch_vccnz .Lvw_35
	s_waitcnt vmcnt(8)
; #define PG8_MMA(ai, bj, At, Bt) do { __builtin_amdgcn_s_setprio(1); _Pragma("unroll") for (int m = 0; m < 4; ++m) _Pragma("unroll") for (int n = 0; n < 2; ++n) _Pragma("unroll") for (int k = 0; k < 2; ++k) \
;         acc[ai][bj][m][n] = __builtin_amdgcn_mfma_f32_16x16x32_bf16(Bt[n][k], At[m][k], acc[ai][bj][m][n], 0, 0, 0); __builtin_amdgcn_s_setprio(0); } while (0)
; #define PG8_WAIT_V(n) asm volatile("s_waitcnt vmcnt(" #n ")" ::: "memory")
; #define PG8_WAIT_L(n) asm volatile("s_waitcnt lgkmcnt(" #n ")" ::: "memory")
; #define PG8_BAR __builtin_amdgcn_s_barrier()
; #define PG8_SCHED __builtin_amdgcn_sched_barrier(0)
; template <class Epi, class Sched, bool ALIGN_EPI = false, bool SP2 = false>
; __device__ __forceinline__ void gemm_phase(PG8_LAS unsigned char* lds, const Gemm g, const Sched& S, const Epi& E) {
;     ...
;             PG8_WAIT_V(8); PG8_WAIT_L(0); PG8_BAR; PG8_MMA(1, 0, At, B0); PG8_MMA(1, 1, At, B1); PG8_BAR; PG8_SCHED;
;     ...
;         if constexpr (ALIGN_EPI) { if (wr == 0) PG8_BAR; }
.Lvw_35:
	s_waitcnt lgkmcnt(0)
	s_barrier
	s_setprio 1
	s_waitcnt lgkmcnt(0)
	v_mfma_f32_16x16x32_bf16 v[60:63], v[128:131], v[182:185], v[60:63]
	v_mfma_f32_16x16x32_bf16 v[56:59], v[152:155], v[182:185], v[56:59]
	v_mfma_f32_16x16x32_bf16 v[44:47], v[152:155], v[194:197], v[44:47]
	v_mfma_f32_16x16x32_bf16 v[52:55], v[128:131], v[194:197], v[52:55]
	v_mfma_f32_16x16x32_bf16 v[36:39], v[128:131], v[202:205], v[36:39]
	v_mfma_f32_16x16x32_bf16 v[24:27], v[152:155], v[202:205], v[24:27]
	v_mfma_f32_16x16x32_bf16 v[8:11], v[152:155], v[210:213], v[8:11]
	v_mfma_f32_16x16x32_bf16 v[16:19], v[128:131], v[210:213], v[16:19]
	v_mfma_f32_16x16x32_bf16 v[60:63], v[132:135], v[186:189], v[60:63]
	v_mfma_f32_16x16x32_bf16 v[56:59], v[156:159], v[186:189], v[56:59]
	v_mfma_f32_16x16x32_bf16 v[44:47], v[156:159], v[198:201], v[44:47]
	v_mfma_f32_16x16x32_bf16 v[52:55], v[132:135], v[198:201], v[52:55]
	v_mfma_f32_16x16x32_bf16 v[36:39], v[132:135], v[206:209], v[36:39]
	v_mfma_f32_16x16x32_bf16 v[24:27], v[156:159], v[206:209], v[24:27]
	v_mfma_f32_16x16x32_bf16 v[8:11], v[156:159], v[214:217], v[8:11]
	v_mfma_f32_16x16x32_bf16 v[16:19], v[132:135], v[214:217], v[16:19]
	s_setprio 0
	s_setprio 1
	v_mfma_f32_16x16x32_bf16 v[48:51], v[166:169], v[182:185], v[48:51]
	v_mfma_f32_16x16x32_bf16 v[40:43], v[174:177], v[182:185], v[40:43]
	v_mfma_f32_16x16x32_bf16 v[28:31], v[174:177], v[194:197], v[28:31]
	v_mfma_f32_16x16x32_bf16 v[32:35], v[166:169], v[194:197], v[32:35]
	v_mfma_f32_16x16x32_bf16 v[20:23], v[166:169], v[202:205], v[20:23]
	v_mfma_f32_16x16x32_bf16 v[12:15], v[174:177], v[202:205], v[12:15]
	v_mfma_f32_16x16x32_bf16 v[0:3], v[174:177], v[210:213], v[0:3]
	v_mfma_f32_16x16x32_bf16 v[4:7], v[166:169], v[210:213], v[4:7]
	v_mfma_f32_16x16x32_bf16 v[48:51], v[170:173], v[186:189], v[48:51]
	v_mfma_f32_16x16x32_bf16 v[40:43], v[178:181], v[186:189], v[40:43]
	v_mfma_f32_16x16x32_bf16 v[28:31], v[178:181], v[198:201], v[28:31]
	v_mfma_f32_16x16x32_bf16 v[32:35], v[170:173], v[198:201], v[32:35]
	v_mfma_f32_16x16x32_bf16 v[20:23], v[170:173], v[206:209], v[20:23]
	v_mfma_f32_16x16x32_bf16 v[12:15], v[178:181], v[206:209], v[12:15]
	v_mfma_f32_16x16x32_bf16 v[0:3], v[178:181], v[214:217], v[0:3]
	v_mfma_f32_16x16x32_bf16 v[4:7], v[170:173], v[214:217], v[4:7]
	s_setprio 0
	s_waitcnt vmcnt(8)
	s_barrier
	s_add_i32 s50, s50, 2
	s_add_u32 s28, s28, 0x100
	s_addc_u32 s29, s29, 0
	s_add_u32 s48, s48, 0x100
	s_addc_u32 s49, s49, 0
	s_cmp_gt_u32 s50, 29
	s_cbranch_scc0 .LBB0_845
	s_and_b64 vcc, exec, s[10:11]
	s_cbranch_vccz .LBB0_848
	s_barrier

; #define PG8_STAGE(bufoff, gbase, voff) do { _Pragma("unroll") for (int _i = 0; _i < 2; ++_i) \
;         __builtin_amdgcn_global_load_lds((const unsigned*)((const char*)(gbase) + (voff)[_i]), (PG8_LAS unsigned*)(lds + (bufoff) + ldsw + _i * 8192), 16, 0, 0); } while (0)
; #define PG8_LDA(dst, b, h) do { _Pragma("unroll") for (int m = 0; m < 4; ++m) _Pragma("unroll") for (int k = 0; k < 2; ++k) dst[m][k] = *(const PG8_LAS bf16x8*)(lds + PG8_SA(b, h) + aoff + m * 2048 + k * 1024); } while (0)
; #define PG8_MMA(ai, bj, At, Bt) do { __builtin_amdgcn_s_setprio(1); _Pragma("unroll") for (int m = 0; m < 4; ++m) _Pragma("unroll") for (int n = 0; n < 2; ++n) _Pragma("unroll") for (int k = 0; k < 2; ++k) \
;         acc[ai][bj][m][n] = __builtin_amdgcn_mfma_f32_16x16x32_bf16(Bt[n][k], At[m][k], acc[ai][bj][m][n], 0, 0, 0); __builtin_amdgcn_s_setprio(0); } while (0)
; #define PG8_WAIT_V(n) asm volatile("s_waitcnt vmcnt(" #n ")" ::: "memory")
; #define PG8_WAIT_L(n) asm volatile("s_waitcnt lgkmcnt(" #n ")" ::: "memory")
; #define PG8_BAR __builtin_amdgcn_s_barrier()
; #define PG8_SCHED __builtin_amdgcn_sched_barrier(0)
; template <class Epi, class Sched, bool ALIGN_EPI = false, bool SP2 = false>
; __device__ __forceinline__ void gemm_phase(PG8_LAS unsigned char* lds, const Gemm g, const Sched& S, const Epi& E) {
;     ...
;             PG8_WAIT_V(8); PG8_WAIT_L(0); PG8_BAR; PG8_MMA(0, 0, At, B0); PG8_MMA(0, 1, At, B1); PG8_BAR; PG8_SCHED;
;             PG8_LDA(At, 0, 1); PG8_STAGE(PG8_SB(0, 0), b2, voffB); PG8_STAGE(PG8_SB(0, 1), b2 + hstep, voffB); PG8_STAGE(PG8_SA(0, 0), a2, voffA);
;             PG8_WAIT_V(8); PG8_WAIT_L(0); PG8_BAR; PG8_MMA(1, 0, At, B0); PG8_MMA(1, 1, At, B1); PG8_BAR; PG8_SCHED;
.Lvw_36:
	s_waitcnt lgkmcnt(0)
	s_barrier
	s_setprio 1
	s_waitcnt lgkmcnt(0)
	v_mfma_f32_16x16x32_bf16 v[124:127], v[146:149], v[186:189], v[124:127]
	v_mfma_f32_16x16x32_bf16 v[120:123], v[162:165], v[186:189], v[120:123]
	v_mfma_f32_16x16x32_bf16 v[104:107], v[162:165], v[198:201], v[104:107]
	v_mfma_f32_16x16x32_bf16 v[108:111], v[146:149], v[198:201], v[108:111]
	v_mfma_f32_16x16x32_bf16 v[92:95], v[146:149], v[206:209], v[92:95]
	v_mfma_f32_16x16x32_bf16 v[88:91], v[162:165], v[206:209], v[88:91]
	v_mfma_f32_16x16x32_bf16 v[72:75], v[162:165], v[214:217], v[72:75]
	v_mfma_f32_16x16x32_bf16 v[76:79], v[146:149], v[214:217], v[76:79]
	v_mfma_f32_16x16x32_bf16 v[124:127], v[158:161], v[194:197], v[124:127]
	v_mfma_f32_16x16x32_bf16 v[120:123], v[166:169], v[194:197], v[120:123]
	v_mfma_f32_16x16x32_bf16 v[104:107], v[166:169], v[202:205], v[104:107]
	v_mfma_f32_16x16x32_bf16 v[108:111], v[158:161], v[202:205], v[108:111]
	v_mfma_f32_16x16x32_bf16 v[92:95], v[158:161], v[210:213], v[92:95]
	v_mfma_f32_16x16x32_bf16 v[88:91], v[166:169], v[210:213], v[88:91]
	v_mfma_f32_16x16x32_bf16 v[72:75], v[166:169], v[218:221], v[72:75]
	v_mfma_f32_16x16x32_bf16 v[76:79], v[158:161], v[218:221], v[76:79]
	s_setprio 0
	s_setprio 1
	v_mfma_f32_16x16x32_bf16 v[116:119], v[170:173], v[186:189], v[116:119]
	v_mfma_f32_16x16x32_bf16 v[112:115], v[178:181], v[186:189], v[112:115]
	v_mfma_f32_16x16x32_bf16 v[96:99], v[178:181], v[198:201], v[96:99]
	v_mfma_f32_16x16x32_bf16 v[100:103], v[170:173], v[198:201], v[100:103]
	v_mfma_f32_16x16x32_bf16 v[84:87], v[170:173], v[206:209], v[84:87]
	v_mfma_f32_16x16x32_bf16 v[80:83], v[178:181], v[206:209], v[80:83]
	v_mfma_f32_16x16x32_bf16 v[64:67], v[178:181], v[214:217], v[64:67]
	v_mfma_f32_16x16x32_bf16 v[68:71], v[170:173], v[214:217], v[68:71]
	v_mfma_f32_16x16x32_bf16 v[116:119], v[174:177], v[194:197], v[116:119]
	v_mfma_f32_16x16x32_bf16 v[112:115], v[182:185], v[194:197], v[112:115]
	v_mfma_f32_16x16x32_bf16 v[96:99], v[182:185], v[202:205], v[96:99]
	v_mfma_f32_16x16x32_bf16 v[100:103], v[174:177], v[202:205], v[100:103]
	v_mfma_f32_16x16x32_bf16 v[84:87], v[174:177], v[210:213], v[84:87]
	v_mfma_f32_16x16x32_bf16 v[80:83], v[182:185], v[210:213], v[80:83]
	v_mfma_f32_16x16x32_bf16 v[64:67], v[182:185], v[218:221], v[64:67]
	v_mfma_f32_16x16x32_bf16 v[68:71], v[174:177], v[218:221], v[68:71]
	s_setprio 0
	s_waitcnt vmcnt(8)
	s_barrier
	s_add_i32 s57, s47, s38
	v_lshl_add_u64 v[150:151], s[30:31], 0, v[130:131]
	s_mov_b32 m0, s57
	ds_read_b128 v[186:189], v157 offset:16384
	ds_read_b128 v[194:197], v157 offset:17408
	ds_read_b128 v[198:201], v157 offset:18432
	ds_read_b128 v[202:205], v157 offset:19456
	ds_read_b128 v[206:209], v157 offset:20480
	ds_read_b128 v[210:213], v157 offset:21504
	ds_read_b128 v[214:217], v157 offset:22528
	ds_read_b128 v[218:221], v157 offset:23552
	global_load_lds_dwordx4 v[150:151], off
	s_add_i32 m0, s57, 0x2000
	s_add_u32 s58, s30, 0x80000
	v_lshl_add_u64 v[190:191], s[30:31], 0, v[134:135]
	s_addc_u32 s59, s31, 0
	s_add_i32 s57, s48, s38
	global_load_lds_dwordx4 v[190:191], off
	v_lshl_add_u64 v[222:223], s[58:59], 0, v[130:131]
	s_mov_b32 m0, s57
	v_lshl_add_u64 v[224:225], s[34:35], 0, v[132:133]
	global_load_lds_dwordx4 v[222:223], off
	v_lshl_add_u64 v[222:223], s[58:59], 0, v[134:135]
	s_add_i32 m0, s57, 0x2000
	s_nop 0
	global_load_lds_dwordx4 v[222:223], off
	v_lshl_add_u64 v[222:223], s[34:35], 0, v[128:129]
	s_mov_b32 m0, s27
	s_nop 0
	global_load_lds_dwordx4 v[222:223], off
	s_mov_b32 m0, s39
	s_nop 0
	global_load_lds_dwordx4 v[224:225], off
	s_mov_b64 vcc, s[98:99]
	s_cbranch_vccnz .Lvw_37
	s_waitcnt vmcnt(8)
.Lvw_37:
	s_waitcnt lgkmcnt(0)
	s_barrier
	s_setprio 1
	s_waitcnt lgkmcnt(0)
	v_mfma_f32_16x16x32_bf16 v[60:63], v[146:149], v[186:189], v[60:63]
	v_mfma_f32_16x16x32_bf16 v[56:59], v[162:165], v[186:189], v[56:59]
	v_mfma_f32_16x16x32_bf16 v[40:43], v[162:165], v[198:201], v[40:43]
	v_mfma_f32_16x16x32_bf16 v[44:47], v[146:149], v[198:201], v[44:47]
	v_mfma_f32_16x16x32_bf16 v[28:31], v[146:149], v[206:209], v[28:31]
	v_mfma_f32_16x16x32_bf16 v[24:27], v[162:165], v[206:209], v[24:27]
	v_mfma_f32_16x16x32_bf16 v[8:11], v[162:165], v[214:217], v[8:11]
	v_mfma_f32_16x16x32_bf16 v[12:15], v[146:149], v[214:217], v[12:15]
	v_mfma_f32_16x16x32_bf16 v[60:63], v[158:161], v[194:197], v[60:63]
	v_mfma_f32_16x16x32_bf16 v[56:59], v[166:169], v[194:197], v[56:59]
	v_mfma_f32_16x16x32_bf16 v[40:43], v[166:169], v[202:205], v[40:43]
	v_mfma_f32_16x16x32_bf16 v[44:47], v[158:161], v[202:205], v[44:47]
	v_mfma_f32_16x16x32_bf16 v[28:31], v[158:161], v[210:213], v[28:31]
	v_mfma_f32_16x16x32_bf16 v[24:27], v[166:169], v[210:213], v[24:27]
	v_mfma_f32_16x16x32_bf16 v[8:11], v[166:169], v[218:221], v[8:11]
	v_mfma_f32_16x16x32_bf16 v[12:15], v[158:161], v[218:221], v[12:15]
	s_setprio 0
	s_setprio 1
	v_mfma_f32_16x16x32_bf16 v[52:55], v[170:173], v[186:189], v[52:55]
	v_mfma_f32_16x16x32_bf16 v[48:51], v[178:181], v[186:189], v[48:51]
	v_mfma_f32_16x16x32_bf16 v[32:35], v[178:181], v[198:201], v[32:35]
	v_mfma_f32_16x16x32_bf16 v[36:39], v[170:173], v[198:201], v[36:39]
	v_mfma_f32_16x16x32_bf16 v[20:23], v[170:173], v[206:209], v[20:23]
	v_mfma_f32_16x16x32_bf16 v[16:19], v[178:181], v[206:209], v[16:19]
	v_mfma_f32_16x16x32_bf16 v[0:3], v[178:181], v[214:217], v[0:3]
	v_mfma_f32_16x16x32_bf16 v[4:7], v[170:173], v[214:217], v[4:7]
	v_mfma_f32_16x16x32_bf16 v[52:55], v[174:177], v[194:197], v[52:55]
	v_mfma_f32_16x16x32_bf16 v[48:51], v[182:185], v[194:197], v[48:51]
	v_mfma_f32_16x16x32_bf16 v[32:35], v[182:185], v[202:205], v[32:35]
	v_mfma_f32_16x16x32_bf16 v[36:39], v[174:177], v[202:205], v[36:39]
	v_mfma_f32_16x16x32_bf16 v[20:23], v[174:177], v[210:213], v[20:23]
	v_mfma_f32_16x16x32_bf16 v[16:19], v[182:185], v[210:213], v[16:19]
	v_mfma_f32_16x16x32_bf16 v[0:3], v[182:185], v[218:221], v[0:3]
	v_mfma_f32_16x16x32_bf16 v[4:7], v[174:177], v[218:221], v[4:7]
	s_setprio 0
	s_waitcnt vmcnt(8)
	s_barrier
; #define PG8_STAGE(bufoff, gbase, voff) do { _Pragma("unroll") for (int _i = 0; _i < 2; ++_i) \
;         __builtin_amdgcn_global_load_lds((const unsigned*)((const char*)(gbase) + (voff)[_i]), (PG8_LAS unsigned*)(lds + (bufoff) + ldsw + _i * 8192), 16, 0, 0); } while (0)
; #define PG8_LDA(dst, b, h) do { _Pragma("unroll") for (int m = 0; m < 4; ++m) _Pragma("unroll") for (int k = 0; k < 2; ++k) dst[m][k] = *(const PG8_LAS bf16x8*)(lds + PG8_SA(b, h) + aoff + m * 2048 + k * 1024); } while (0)
; #define PG8_LDB(dst, b, h) do { _Pragma("unroll") for (int n = 0; n < 2; ++n) _Pragma("unroll") for (int k = 0; k < 2; ++k) dst[n][k] = *(const PG8_LAS bf16x8*)(lds + PG8_SB(b, h) + boff + n * 2048 + k * 1024); } while (0)
; #define PG8_MMA(ai, bj, At, Bt) do { __builtin_amdgcn_s_setprio(1); _Pragma("unroll") for (int m = 0; m < 4; ++m) _Pragma("unroll") for (int n = 0; n < 2; ++n) _Pragma("unroll") for (int k = 0; k < 2; ++k) \
;         acc[ai][bj][m][n] = __builtin_amdgcn_mfma_f32_16x16x32_bf16(Bt[n][k], At[m][k], acc[ai][bj][m][n], 0, 0, 0); __builtin_amdgcn_s_setprio(0); } while (0)
; #define PG8_WAIT_V(n) asm volatile("s_waitcnt vmcnt(" #n ")" ::: "memory")
; #define PG8_WAIT_L(n) asm volatile("s_waitcnt lgkmcnt(" #n ")" ::: "memory")
; #define PG8_BAR __builtin_amdgcn_s_barrier()
; #define PG8_SCHED __builtin_amdgcn_sched_barrier(0)
; template <class Epi, class Sched, bool ALIGN_EPI = false, bool SP2 = false>
; __device__ __forceinline__ void gemm_phase(PG8_LAS unsigned char* lds, const Gemm g, const Sched& S, const Epi& E) {
;     ...
;             PG8_LDB(B0, 1, 0); PG8_LDB(B1, 1, 1); PG8_SCHED; PG8_LDA(At, 1, 0); PG8_STAGE(PG8_SA(0, 1), a2 + hstep, voffA);
;             PG8_WAIT_V(8); PG8_WAIT_L(0); PG8_BAR; PG8_MMA(0, 0, At, B0); PG8_MMA(0, 1, At, B1); PG8_BAR; PG8_SCHED;
;             PG8_LDA(At, 1, 1); PG8_STAGE(PG8_SB(1, 0), b3, voffB); PG8_STAGE(PG8_SB(1, 1), b3 + hstep, voffB); PG8_STAGE(PG8_SA(1, 0), a3, voffA);
	s_add_i32 s57, 0, 0x18000
	v_add_u32_e32 v136, s57, v153
	s_add_i32 s58, 0, 0x1c000
	ds_read_b128 v[146:149], v136
	ds_read_b128 v[158:161], v136 offset:1024
	ds_read_b128 v[162:165], v136 offset:2048
	ds_read_b128 v[166:169], v136 offset:3072
	v_add_u32_e32 v136, s58, v153
	ds_read_b128 v[170:173], v136
	ds_read_b128 v[174:177], v136 offset:1024
	ds_read_b128 v[178:181], v136 offset:2048
	ds_read_b128 v[182:185], v136 offset:3072
	s_add_u32 s34, s34, 0x80000
	s_addc_u32 s35, s35, 0
	s_mov_b32 m0, s40
	v_lshl_add_u64 v[226:227], s[34:35], 0, v[128:129]
	ds_read_b128 v[186:189], v157 offset:32768
	ds_read_b128 v[194:197], v157 offset:33792
	ds_read_b128 v[198:201], v157 offset:34816
	ds_read_b128 v[202:205], v157 offset:35840
	ds_read_b128 v[206:209], v157 offset:36864
	ds_read_b128 v[210:213], v157 offset:37888
	ds_read_b128 v[214:217], v157 offset:38912
	ds_read_b128 v[218:221], v157 offset:39936
	global_load_lds_dwordx4 v[226:227], off
	v_lshl_add_u64 v[226:227], s[34:35], 0, v[132:133]
	s_mov_b32 m0, s41
	s_nop 0
	global_load_lds_dwordx4 v[226:227], off
	s_mov_b64 vcc, s[98:99]
	s_cbranch_vccnz .Lvw_38
	s_waitcnt vmcnt(8)
.Lvw_38:
	s_waitcnt lgkmcnt(0)
	s_barrier
	s_setprio 1
	s_waitcnt lgkmcnt(0)
	v_mfma_f32_16x16x32_bf16 v[124:127], v[146:149], v[186:189], v[124:127]
	v_mfma_f32_16x16x32_bf16 v[120:123], v[162:165], v[186:189], v[120:123]
	v_mfma_f32_16x16x32_bf16 v[104:107], v[162:165], v[198:201], v[104:107]
	v_mfma_f32_16x16x32_bf16 v[108:111], v[146:149], v[198:201], v[108:111]
	v_mfma_f32_16x16x32_bf16 v[92:95], v[146:149], v[206:209], v[92:95]
	v_mfma_f32_16x16x32_bf16 v[88:91], v[162:165], v[206:209], v[88:91]
	v_mfma_f32_16x16x32_bf16 v[72:75], v[162:165], v[214:217], v[72:75]
	v_mfma_f32_16x16x32_bf16 v[76:79], v[146:149], v[214:217], v[76:79]
	v_mfma_f32_16x16x32_bf16 v[124:127], v[158:161], v[194:197], v[124:127]
	v_mfma_f32_16x16x32_bf16 v[120:123], v[166:169], v[194:197], v[120:123]
	v_mfma_f32_16x16x32_bf16 v[104:107], v[166:169], v[202:205], v[104:107]
	v_mfma_f32_16x16x32_bf16 v[108:111], v[158:161], v[202:205], v[108:111]
	v_mfma_f32_16x16x32_bf16 v[92:95], v[158:161], v[210:213], v[92:95]
	v_mfma_f32_16x16x32_bf16 v[88:91], v[166:169], v[210:213], v[88:91]
	v_mfma_f32_16x16x32_bf16 v[72:75], v[166:169], v[218:221], v[72:75]
	v_mfma_f32_16x16x32_bf16 v[76:79], v[158:161], v[218:221], v[76:79]
	s_setprio 0
	s_setprio 1
	v_mfma_f32_16x16x32_bf16 v[116:119], v[170:173], v[186:189], v[116:119]
	v_mfma_f32_16x16x32_bf16 v[112:115], v[178:181], v[186:189], v[112:115]
	v_mfma_f32_16x16x32_bf16 v[96:99], v[178:181], v[198:201], v[96:99]
	v_mfma_f32_16x16x32_bf16 v[100:103], v[170:173], v[198:201], v[100:103]
	v_mfma_f32_16x16x32_bf16 v[84:87], v[170:173], v[206:209], v[84:87]
	v_mfma_f32_16x16x32_bf16 v[80:83], v[178:181], v[206:209], v[80:83]
	v_mfma_f32_16x16x32_bf16 v[64:67], v[178:181], v[214:217], v[64:67]
	v_mfma_f32_16x16x32_bf16 v[68:71], v[170:173], v[214:217], v[68:71]
	v_mfma_f32_16x16x32_bf16 v[116:119], v[174:177], v[194:197], v[116:119]
	v_mfma_f32_16x16x32_bf16 v[112:115], v[182:185], v[194:197], v[112:115]
	v_mfma_f32_16x16x32_bf16 v[96:99], v[182:185], v[202:205], v[96:99]
	v_mfma_f32_16x16x32_bf16 v[100:103], v[174:177], v[202:205], v[100:103]
	v_mfma_f32_16x16x32_bf16 v[84:87], v[174:177], v[210:213], v[84:87]
	v_mfma_f32_16x16x32_bf16 v[80:83], v[182:185], v[210:213], v[80:83]
	v_mfma_f32_16x16x32_bf16 v[64:67], v[182:185], v[218:221], v[64:67]
	v_mfma_f32_16x16x32_bf16 v[68:71], v[174:177], v[218:221], v[68:71]
	s_setprio 0
	s_waitcnt vmcnt(8)
	s_barrier
	s_add_i32 s34, s57, s38
	v_lshl_add_u64 v[150:151], v[150:151], 0, s[10:11]
	s_mov_b32 m0, s34
	ds_read_b128 v[186:189], v157 offset:49152
	ds_read_b128 v[194:197], v157 offset:50176
	ds_read_b128 v[198:201], v157 offset:51200
	ds_read_b128 v[202:205], v157 offset:52224
	ds_read_b128 v[206:209], v157 offset:53248
	ds_read_b128 v[210:213], v157 offset:54272
	ds_read_b128 v[214:217], v157 offset:55296
	ds_read_b128 v[218:221], v157 offset:56320
	global_load_lds_dwordx4 v[150:151], off
	s_add_i32 m0, s34, 0x2000
	s_add_u32 s30, s30, 0x80080
	v_lshl_add_u64 v[150:151], v[190:191], 0, s[10:11]
	s_addc_u32 s31, s31, 0
	s_add_i32 s34, s58, s38
	global_load_lds_dwordx4 v[150:151], off
	v_lshl_add_u64 v[150:151], s[30:31], 0, v[130:131]
	s_mov_b32 m0, s34
	s_nop 0
	global_load_lds_dwordx4 v[150:151], off
	v_lshl_add_u64 v[150:151], s[30:31], 0, v[134:135]
	s_add_i32 m0, s34, 0x2000
	s_nop 0
	global_load_lds_dwordx4 v[150:151], off
	v_lshl_add_u64 v[150:151], v[222:223], 0, s[10:11]
	s_mov_b32 m0, s43
	s_nop 0
	global_load_lds_dwordx4 v[150:151], off
	v_lshl_add_u64 v[150:151], v[224:225], 0, s[10:11]
	s_mov_b32 m0, s44
	s_nop 0
	global_load_lds_dwordx4 v[150:151], off
	s_mov_b64 vcc, s[98:99]
	s_cbranch_vccnz .Lvw_39
	s_waitcnt vmcnt(8)
; #define PG8_MMA(ai, bj, At, Bt) do { __builtin_amdgcn_s_setprio(1); _Pragma("unroll") for (int m = 0; m < 4; ++m) _Pragma("unroll") for (int n = 0; n < 2; ++n) _Pragma("unroll") for (int k = 0; k < 2; ++k) \
;         acc[ai][bj][m][n] = __builtin_amdgcn_mfma_f32_16x16x32_bf16(Bt[n][k], At[m][k], acc[ai][bj][m][n], 0, 0, 0); __builtin_amdgcn_s_setprio(0); } while (0)
; #define PG8_WAIT_V(n) asm volatile("s_waitcnt vmcnt(" #n ")" ::: "memory")
; #define PG8_WAIT_L(n) asm volatile("s_waitcnt lgkmcnt(" #n ")" ::: "memory")
; #define PG8_BAR __builtin_amdgcn_s_barrier()
; #define PG8_SCHED __builtin_amdgcn_sched_barrier(0)
; template <class Epi, class Sched, bool ALIGN_EPI = false, bool SP2 = false>
; __device__ __forceinline__ void gemm_phase(PG8_LAS unsigned char* lds, const Gemm g, const Sched& S, const Epi& E) {
;     ...
;             PG8_WAIT_V(8); PG8_WAIT_L(0); PG8_BAR; PG8_MMA(1, 0, At, B0); PG8_MMA(1, 1, At, B1); PG8_BAR; PG8_SCHED;
;     ...
;         if constexpr (ALIGN_EPI) { if (wr == 0) PG8_BAR; }
.Lvw_39:
	s_waitcnt lgkmcnt(0)
	s_barrier
	s_setprio 1
	s_waitcnt lgkmcnt(0)
	v_mfma_f32_16x16x32_bf16 v[60:63], v[146:149], v[186:189], v[60:63]
	v_mfma_f32_16x16x32_bf16 v[56:59], v[162:165], v[186:189], v[56:59]
	v_mfma_f32_16x16x32_bf16 v[40:43], v[162:165], v[198:201], v[40:43]
	v_mfma_f32_16x16x32_bf16 v[44:47], v[146:149], v[198:201], v[44:47]
	v_mfma_f32_16x16x32_bf16 v[28:31], v[146:149], v[206:209], v[28:31]
	v_mfma_f32_16x16x32_bf16 v[24:27], v[162:165], v[206:209], v[24:27]
	v_mfma_f32_16x16x32_bf16 v[8:11], v[162:165], v[214:217], v[8:11]
	v_mfma_f32_16x16x32_bf16 v[12:15], v[146:149], v[214:217], v[12:15]
	v_mfma_f32_16x16x32_bf16 v[60:63], v[158:161], v[194:197], v[60:63]
	v_mfma_f32_16x16x32_bf16 v[56:59], v[166:169], v[194:197], v[56:59]
	v_mfma_f32_16x16x32_bf16 v[40:43], v[166:169], v[202:205], v[40:43]
	v_mfma_f32_16x16x32_bf16 v[44:47], v[158:161], v[202:205], v[44:47]
	v_mfma_f32_16x16x32_bf16 v[28:31], v[158:161], v[210:213], v[28:31]
	v_mfma_f32_16x16x32_bf16 v[24:27], v[166:169], v[210:213], v[24:27]
	v_mfma_f32_16x16x32_bf16 v[8:11], v[166:169], v[218:221], v[8:11]
	v_mfma_f32_16x16x32_bf16 v[12:15], v[158:161], v[218:221], v[12:15]
	s_setprio 0
	s_setprio 1
	v_mfma_f32_16x16x32_bf16 v[52:55], v[170:173], v[186:189], v[52:55]
	v_mfma_f32_16x16x32_bf16 v[48:51], v[178:181], v[186:189], v[48:51]
	v_mfma_f32_16x16x32_bf16 v[32:35], v[178:181], v[198:201], v[32:35]
	v_mfma_f32_16x16x32_bf16 v[36:39], v[170:173], v[198:201], v[36:39]
	v_mfma_f32_16x16x32_bf16 v[20:23], v[170:173], v[206:209], v[20:23]
	v_mfma_f32_16x16x32_bf16 v[16:19], v[178:181], v[206:209], v[16:19]
	v_mfma_f32_16x16x32_bf16 v[0:3], v[178:181], v[214:217], v[0:3]
	v_mfma_f32_16x16x32_bf16 v[4:7], v[170:173], v[214:217], v[4:7]
	v_mfma_f32_16x16x32_bf16 v[52:55], v[174:177], v[194:197], v[52:55]
	v_mfma_f32_16x16x32_bf16 v[48:51], v[182:185], v[194:197], v[48:51]
	v_mfma_f32_16x16x32_bf16 v[32:35], v[182:185], v[202:205], v[32:35]
	v_mfma_f32_16x16x32_bf16 v[36:39], v[174:177], v[202:205], v[36:39]
	v_mfma_f32_16x16x32_bf16 v[20:23], v[174:177], v[210:213], v[20:23]
	v_mfma_f32_16x16x32_bf16 v[16:19], v[182:185], v[210:213], v[16:19]
	v_mfma_f32_16x16x32_bf16 v[0:3], v[182:185], v[218:221], v[0:3]
	v_mfma_f32_16x16x32_bf16 v[4:7], v[174:177], v[218:221], v[4:7]
	s_setprio 0
	s_waitcnt vmcnt(8)
	s_barrier
	s_add_i32 s56, s56, 2
	s_add_u32 s28, s28, 0x100
	s_addc_u32 s29, s29, 0
	s_add_u32 s54, s54, 0x100
	s_addc_u32 s55, s55, 0
	s_cmp_gt_u32 s56, 29
	s_cbranch_scc0 .LBB0_869
	s_and_b64 vcc, exec, s[12:13]
	s_cbranch_vccz .LBB0_872
	s_barrier

; #define PG8_STAGE(bufoff, gbase, voff) do { _Pragma("unroll") for (int _i = 0; _i < 2; ++_i) \
;         __builtin_amdgcn_global_load_lds((const unsigned*)((const char*)(gbase) + (voff)[_i]), (PG8_LAS unsigned*)(lds + (bufoff) + ldsw + _i * 8192), 16, 0, 0); } while (0)
; #define PG8_LDA(dst, b, h) do { _Pragma("unroll") for (int m = 0; m < 4; ++m) _Pragma("unroll") for (int k = 0; k < 2; ++k) dst[m][k] = *(const PG8_LAS bf16x8*)(lds + PG8_SA(b, h) + aoff + m * 2048 + k * 1024); } while (0)
; #define PG8_MMA(ai, bj, At, Bt) do { __builtin_amdgcn_s_setprio(1); _Pragma("unroll") for (int m = 0; m < 4; ++m) _Pragma("unroll") for (int n = 0; n < 2; ++n) _Pragma("unroll") for (int k = 0; k < 2; ++k) \
;         acc[ai][bj][m][n] = __builtin_amdgcn_mfma_f32_16x16x32_bf16(Bt[n][k], At[m][k], acc[ai][bj][m][n], 0, 0, 0); __builtin_amdgcn_s_setprio(0); } while (0)
; #define PG8_WAIT_V(n) asm volatile("s_waitcnt vmcnt(" #n ")" ::: "memory")
; #define PG8_WAIT_L(n) asm volatile("s_waitcnt lgkmcnt(" #n ")" ::: "memory")
; #define PG8_BAR __builtin_amdgcn_s_barrier()
; #define PG8_SCHED __builtin_amdgcn_sched_barrier(0)
; template <class Epi, class Sched, bool ALIGN_EPI = false, bool SP2 = false>
; __device__ __forceinline__ void gemm_phase(PG8_LAS unsigned char* lds, const Gemm g, const Sched& S, const Epi& E) {
;     ...
;             PG8_WAIT_V(8); PG8_WAIT_L(0); PG8_BAR; PG8_MMA(0, 0, At, B0); PG8_MMA(0, 1, At, B1); PG8_BAR; PG8_SCHED;
;             PG8_LDA(At, 0, 1); PG8_STAGE(PG8_SB(0, 0), b2, voffB); PG8_STAGE(PG8_SB(0, 1), b2 + hstep, voffB); PG8_STAGE(PG8_SA(0, 0), a2, voffA);
;             PG8_WAIT_V(8); PG8_WAIT_L(0); PG8_BAR; PG8_MMA(1, 0, At, B0); PG8_MMA(1, 1, At, B1); PG8_BAR; PG8_SCHED;
.Lvw_40:
	s_waitcnt lgkmcnt(0)
	s_barrier
	s_setprio 1
	s_waitcnt lgkmcnt(0)
	v_mfma_f32_16x16x32_bf16 v[124:127], v[144:147], v[184:187], v[124:127]
	v_mfma_f32_16x16x32_bf16 v[120:123], v[160:163], v[184:187], v[120:123]
	v_mfma_f32_16x16x32_bf16 v[104:107], v[160:163], v[194:197], v[104:107]
	v_mfma_f32_16x16x32_bf16 v[112:115], v[144:147], v[194:197], v[112:115]
	v_mfma_f32_16x16x32_bf16 v[92:95], v[144:147], v[202:205], v[92:95]
	v_mfma_f32_16x16x32_bf16 v[88:91], v[160:163], v[202:205], v[88:91]
	v_mfma_f32_16x16x32_bf16 v[72:75], v[160:163], v[210:213], v[72:75]
	v_mfma_f32_16x16x32_bf16 v[76:79], v[144:147], v[210:213], v[76:79]
	v_mfma_f32_16x16x32_bf16 v[124:127], v[156:159], v[188:191], v[124:127]
	v_mfma_f32_16x16x32_bf16 v[120:123], v[164:167], v[188:191], v[120:123]
	v_mfma_f32_16x16x32_bf16 v[104:107], v[164:167], v[198:201], v[104:107]
	v_mfma_f32_16x16x32_bf16 v[112:115], v[156:159], v[198:201], v[112:115]
	v_mfma_f32_16x16x32_bf16 v[92:95], v[156:159], v[206:209], v[92:95]
	v_mfma_f32_16x16x32_bf16 v[88:91], v[164:167], v[206:209], v[88:91]
	v_mfma_f32_16x16x32_bf16 v[72:75], v[164:167], v[214:217], v[72:75]
	v_mfma_f32_16x16x32_bf16 v[76:79], v[156:159], v[214:217], v[76:79]
	s_setprio 0
	s_setprio 1
	v_mfma_f32_16x16x32_bf16 v[116:119], v[168:171], v[184:187], v[116:119]
	v_mfma_f32_16x16x32_bf16 v[108:111], v[176:179], v[184:187], v[108:111]
	v_mfma_f32_16x16x32_bf16 v[96:99], v[176:179], v[194:197], v[96:99]
	v_mfma_f32_16x16x32_bf16 v[100:103], v[168:171], v[194:197], v[100:103]
	v_mfma_f32_16x16x32_bf16 v[84:87], v[168:171], v[202:205], v[84:87]
	v_mfma_f32_16x16x32_bf16 v[80:83], v[176:179], v[202:205], v[80:83]
	v_mfma_f32_16x16x32_bf16 v[64:67], v[176:179], v[210:213], v[64:67]
	v_mfma_f32_16x16x32_bf16 v[68:71], v[168:171], v[210:213], v[68:71]
	v_mfma_f32_16x16x32_bf16 v[116:119], v[172:175], v[188:191], v[116:119]
	v_mfma_f32_16x16x32_bf16 v[108:111], v[180:183], v[188:191], v[108:111]
	v_mfma_f32_16x16x32_bf16 v[96:99], v[180:183], v[198:201], v[96:99]
	v_mfma_f32_16x16x32_bf16 v[100:103], v[172:175], v[198:201], v[100:103]
	v_mfma_f32_16x16x32_bf16 v[84:87], v[172:175], v[206:209], v[84:87]
	v_mfma_f32_16x16x32_bf16 v[80:83], v[180:183], v[206:209], v[80:83]
	v_mfma_f32_16x16x32_bf16 v[64:67], v[180:183], v[214:217], v[64:67]
	v_mfma_f32_16x16x32_bf16 v[68:71], v[172:175], v[214:217], v[68:71]
	s_setprio 0
	s_waitcnt vmcnt(8)
	s_barrier
	s_add_i32 s43, s37, s26
	v_lshl_add_u64 v[148:149], s[22:23], 0, v[130:131]
	s_mov_b32 m0, s43
	ds_read_b128 v[184:187], v155 offset:16384
	ds_read_b128 v[188:191], v155 offset:17408
	ds_read_b128 v[194:197], v155 offset:18432
	ds_read_b128 v[198:201], v155 offset:19456
	ds_read_b128 v[202:205], v155 offset:20480
	ds_read_b128 v[206:209], v155 offset:21504
	ds_read_b128 v[210:213], v155 offset:22528
	ds_read_b128 v[214:217], v155 offset:23552
	global_load_lds_dwordx4 v[148:149], off
	s_add_i32 m0, s43, 0x2000
	s_add_u32 s44, s22, 0x80000
	v_lshl_add_u64 v[218:219], s[22:23], 0, v[134:135]
	s_addc_u32 s45, s23, 0
	s_add_i32 s43, s38, s26
	global_load_lds_dwordx4 v[218:219], off
	v_lshl_add_u64 v[220:221], s[44:45], 0, v[130:131]
	s_mov_b32 m0, s43
	v_lshl_add_u64 v[222:223], s[24:25], 0, v[132:133]
	global_load_lds_dwordx4 v[220:221], off
	v_lshl_add_u64 v[220:221], s[44:45], 0, v[134:135]
	s_add_i32 m0, s43, 0x2000
	s_nop 0
	global_load_lds_dwordx4 v[220:221], off
	v_lshl_add_u64 v[220:221], s[24:25], 0, v[128:129]
	s_mov_b32 m0, s19
	s_nop 0
	global_load_lds_dwordx4 v[220:221], off
	s_mov_b32 m0, s27
	s_nop 0
	global_load_lds_dwordx4 v[222:223], off
	s_mov_b64 vcc, s[98:99]
	s_cbranch_vccnz .Lvw_41
	s_waitcnt vmcnt(8)
.Lvw_41:
	s_waitcnt lgkmcnt(0)
	s_barrier
	s_setprio 1
	s_waitcnt lgkmcnt(0)
	v_mfma_f32_16x16x32_bf16 v[60:63], v[144:147], v[184:187], v[60:63]
	v_mfma_f32_16x16x32_bf16 v[56:59], v[160:163], v[184:187], v[56:59]
	v_mfma_f32_16x16x32_bf16 v[40:43], v[160:163], v[194:197], v[40:43]
	v_mfma_f32_16x16x32_bf16 v[44:47], v[144:147], v[194:197], v[44:47]
	v_mfma_f32_16x16x32_bf16 v[28:31], v[144:147], v[202:205], v[28:31]
	v_mfma_f32_16x16x32_bf16 v[24:27], v[160:163], v[202:205], v[24:27]
	v_mfma_f32_16x16x32_bf16 v[8:11], v[160:163], v[210:213], v[8:11]
	v_mfma_f32_16x16x32_bf16 v[12:15], v[144:147], v[210:213], v[12:15]
	v_mfma_f32_16x16x32_bf16 v[60:63], v[156:159], v[188:191], v[60:63]
	v_mfma_f32_16x16x32_bf16 v[56:59], v[164:167], v[188:191], v[56:59]
	v_mfma_f32_16x16x32_bf16 v[40:43], v[164:167], v[198:201], v[40:43]
	v_mfma_f32_16x16x32_bf16 v[44:47], v[156:159], v[198:201], v[44:47]
	v_mfma_f32_16x16x32_bf16 v[28:31], v[156:159], v[206:209], v[28:31]
	v_mfma_f32_16x16x32_bf16 v[24:27], v[164:167], v[206:209], v[24:27]
	v_mfma_f32_16x16x32_bf16 v[8:11], v[164:167], v[214:217], v[8:11]
	v_mfma_f32_16x16x32_bf16 v[12:15], v[156:159], v[214:217], v[12:15]
	s_setprio 0
	s_setprio 1
	v_mfma_f32_16x16x32_bf16 v[52:55], v[168:171], v[184:187], v[52:55]
	v_mfma_f32_16x16x32_bf16 v[48:51], v[176:179], v[184:187], v[48:51]
	v_mfma_f32_16x16x32_bf16 v[32:35], v[176:179], v[194:197], v[32:35]
	v_mfma_f32_16x16x32_bf16 v[36:39], v[168:171], v[194:197], v[36:39]
	v_mfma_f32_16x16x32_bf16 v[20:23], v[168:171], v[202:205], v[20:23]
	v_mfma_f32_16x16x32_bf16 v[16:19], v[176:179], v[202:205], v[16:19]
	v_mfma_f32_16x16x32_bf16 v[0:3], v[176:179], v[210:213], v[0:3]
	v_mfma_f32_16x16x32_bf16 v[4:7], v[168:171], v[210:213], v[4:7]
	v_mfma_f32_16x16x32_bf16 v[52:55], v[172:175], v[188:191], v[52:55]
	v_mfma_f32_16x16x32_bf16 v[48:51], v[180:183], v[188:191], v[48:51]
	v_mfma_f32_16x16x32_bf16 v[32:35], v[180:183], v[198:201], v[32:35]
	v_mfma_f32_16x16x32_bf16 v[36:39], v[172:175], v[198:201], v[36:39]
	v_mfma_f32_16x16x32_bf16 v[20:23], v[172:175], v[206:209], v[20:23]
	v_mfma_f32_16x16x32_bf16 v[16:19], v[180:183], v[206:209], v[16:19]
	v_mfma_f32_16x16x32_bf16 v[0:3], v[180:183], v[214:217], v[0:3]
	v_mfma_f32_16x16x32_bf16 v[4:7], v[172:175], v[214:217], v[4:7]
	s_setprio 0
	s_waitcnt vmcnt(8)
	s_barrier
; #define PG8_STAGE(bufoff, gbase, voff) do { _Pragma("unroll") for (int _i = 0; _i < 2; ++_i) \
;         __builtin_amdgcn_global_load_lds((const unsigned*)((const char*)(gbase) + (voff)[_i]), (PG8_LAS unsigned*)(lds + (bufoff) + ldsw + _i * 8192), 16, 0, 0); } while (0)
; #define PG8_LDA(dst, b, h) do { _Pragma("unroll") for (int m = 0; m < 4; ++m) _Pragma("unroll") for (int k = 0; k < 2; ++k) dst[m][k] = *(const PG8_LAS bf16x8*)(lds + PG8_SA(b, h) + aoff + m * 2048 + k * 1024); } while (0)
; #define PG8_LDB(dst, b, h) do { _Pragma("unroll") for (int n = 0; n < 2; ++n) _Pragma("unroll") for (int k = 0; k < 2; ++k) dst[n][k] = *(const PG8_LAS bf16x8*)(lds + PG8_SB(b, h) + boff + n * 2048 + k * 1024); } while (0)
; #define PG8_MMA(ai, bj, At, Bt) do { __builtin_amdgcn_s_setprio(1); _Pragma("unroll") for (int m = 0; m < 4; ++m) _Pragma("unroll") for (int n = 0; n < 2; ++n) _Pragma("unroll") for (int k = 0; k < 2; ++k) \
;         acc[ai][bj][m][n] = __builtin_amdgcn_mfma_f32_16x16x32_bf16(Bt[n][k], At[m][k], acc[ai][bj][m][n], 0, 0, 0); __builtin_amdgcn_s_setprio(0); } while (0)
; #define PG8_WAIT_V(n) asm volatile("s_waitcnt vmcnt(" #n ")" ::: "memory")
; #define PG8_WAIT_L(n) asm volatile("s_waitcnt lgkmcnt(" #n ")" ::: "memory")
; #define PG8_BAR __builtin_amdgcn_s_barrier()
; #define PG8_SCHED __builtin_amdgcn_sched_barrier(0)
; template <class Epi, class Sched, bool ALIGN_EPI = false, bool SP2 = false>
; __device__ __forceinline__ void gemm_phase(PG8_LAS unsigned char* lds, const Gemm g, const Sched& S, const Epi& E) {
;     ...
;             PG8_LDB(B0, 1, 0); PG8_LDB(B1, 1, 1); PG8_SCHED; PG8_LDA(At, 1, 0); PG8_STAGE(PG8_SA(0, 1), a2 + hstep, voffA);
;             PG8_WAIT_V(8); PG8_WAIT_L(0); PG8_BAR; PG8_MMA(0, 0, At, B0); PG8_MMA(0, 1, At, B1); PG8_BAR; PG8_SCHED;
;             PG8_LDA(At, 1, 1); PG8_STAGE(PG8_SB(1, 0), b3, voffB); PG8_STAGE(PG8_SB(1, 1), b3 + hstep, voffB); PG8_STAGE(PG8_SA(1, 0), a3, voffA);
	s_add_i32 s43, 0, 0x18000
	s_add_i32 s44, 0, 0x1c000
	v_add_u32_e32 v164, s43, v151
	v_add_u32_e32 v180, s44, v151
	ds_read_b128 v[144:147], v164
	ds_read_b128 v[156:159], v164 offset:1024
	ds_read_b128 v[160:163], v164 offset:2048
	ds_read_b128 v[164:167], v164 offset:3072
	ds_read_b128 v[168:171], v180
	ds_read_b128 v[172:175], v180 offset:1024
	ds_read_b128 v[176:179], v180 offset:2048
	ds_read_b128 v[180:183], v180 offset:3072
	s_add_u32 s24, s24, 0x80000
	s_addc_u32 s25, s25, 0
	s_mov_b32 m0, s28
	v_lshl_add_u64 v[224:225], s[24:25], 0, v[128:129]
	ds_read_b128 v[184:187], v155 offset:32768
	ds_read_b128 v[188:191], v155 offset:33792
	ds_read_b128 v[194:197], v155 offset:34816
	ds_read_b128 v[198:201], v155 offset:35840
	ds_read_b128 v[202:205], v155 offset:36864
	ds_read_b128 v[206:209], v155 offset:37888
	ds_read_b128 v[210:213], v155 offset:38912
	ds_read_b128 v[214:217], v155 offset:39936
	global_load_lds_dwordx4 v[224:225], off
	v_lshl_add_u64 v[224:225], s[24:25], 0, v[132:133]
	s_mov_b32 m0, s29
	s_nop 0
	global_load_lds_dwordx4 v[224:225], off
	s_mov_b64 vcc, s[98:99]
	s_cbranch_vccnz .Lvw_42
	s_waitcnt vmcnt(8)
.Lvw_42:
	s_waitcnt lgkmcnt(0)
	s_barrier
	s_setprio 1
	s_waitcnt lgkmcnt(0)
	v_mfma_f32_16x16x32_bf16 v[124:127], v[144:147], v[184:187], v[124:127]
	v_mfma_f32_16x16x32_bf16 v[120:123], v[160:163], v[184:187], v[120:123]
	v_mfma_f32_16x16x32_bf16 v[104:107], v[160:163], v[194:197], v[104:107]
	v_mfma_f32_16x16x32_bf16 v[112:115], v[144:147], v[194:197], v[112:115]
	v_mfma_f32_16x16x32_bf16 v[92:95], v[144:147], v[202:205], v[92:95]
	v_mfma_f32_16x16x32_bf16 v[88:91], v[160:163], v[202:205], v[88:91]
	v_mfma_f32_16x16x32_bf16 v[72:75], v[160:163], v[210:213], v[72:75]
	v_mfma_f32_16x16x32_bf16 v[76:79], v[144:147], v[210:213], v[76:79]
	v_mfma_f32_16x16x32_bf16 v[124:127], v[156:159], v[188:191], v[124:127]
	v_mfma_f32_16x16x32_bf16 v[120:123], v[164:167], v[188:191], v[120:123]
	v_mfma_f32_16x16x32_bf16 v[104:107], v[164:167], v[198:201], v[104:107]
	v_mfma_f32_16x16x32_bf16 v[112:115], v[156:159], v[198:201], v[112:115]
	v_mfma_f32_16x16x32_bf16 v[92:95], v[156:159], v[206:209], v[92:95]
	v_mfma_f32_16x16x32_bf16 v[88:91], v[164:167], v[206:209], v[88:91]
	v_mfma_f32_16x16x32_bf16 v[72:75], v[164:167], v[214:217], v[72:75]
	v_mfma_f32_16x16x32_bf16 v[76:79], v[156:159], v[214:217], v[76:79]
	s_setprio 0
	s_setprio 1
	v_mfma_f32_16x16x32_bf16 v[116:119], v[168:171], v[184:187], v[116:119]
	v_mfma_f32_16x16x32_bf16 v[108:111], v[176:179], v[184:187], v[108:111]
	v_mfma_f32_16x16x32_bf16 v[96:99], v[176:179], v[194:197], v[96:99]
	v_mfma_f32_16x16x32_bf16 v[100:103], v[168:171], v[194:197], v[100:103]
	v_mfma_f32_16x16x32_bf16 v[84:87], v[168:171], v[202:205], v[84:87]
	v_mfma_f32_16x16x32_bf16 v[80:83], v[176:179], v[202:205], v[80:83]
	v_mfma_f32_16x16x32_bf16 v[64:67], v[176:179], v[210:213], v[64:67]
	v_mfma_f32_16x16x32_bf16 v[68:71], v[168:171], v[210:213], v[68:71]
	v_mfma_f32_16x16x32_bf16 v[116:119], v[172:175], v[188:191], v[116:119]
	v_mfma_f32_16x16x32_bf16 v[108:111], v[180:183], v[188:191], v[108:111]
	v_mfma_f32_16x16x32_bf16 v[96:99], v[180:183], v[198:201], v[96:99]
	v_mfma_f32_16x16x32_bf16 v[100:103], v[172:175], v[198:201], v[100:103]
	v_mfma_f32_16x16x32_bf16 v[84:87], v[172:175], v[206:209], v[84:87]
	v_mfma_f32_16x16x32_bf16 v[80:83], v[180:183], v[206:209], v[80:83]
	v_mfma_f32_16x16x32_bf16 v[64:67], v[180:183], v[214:217], v[64:67]
	v_mfma_f32_16x16x32_bf16 v[68:71], v[172:175], v[214:217], v[68:71]
	s_setprio 0
	s_waitcnt vmcnt(8)
	s_barrier
	s_add_i32 s24, s43, s26
	v_lshl_add_u64 v[148:149], v[148:149], 0, s[8:9]
	s_mov_b32 m0, s24
	ds_read_b128 v[184:187], v155 offset:49152
	ds_read_b128 v[188:191], v155 offset:50176
	ds_read_b128 v[194:197], v155 offset:51200
	ds_read_b128 v[198:201], v155 offset:52224
	ds_read_b128 v[202:205], v155 offset:53248
	ds_read_b128 v[206:209], v155 offset:54272
	ds_read_b128 v[210:213], v155 offset:55296
	ds_read_b128 v[214:217], v155 offset:56320
	global_load_lds_dwordx4 v[148:149], off
	s_add_i32 m0, s24, 0x2000
	s_add_u32 s22, s22, 0x80080
	v_lshl_add_u64 v[148:149], v[218:219], 0, s[8:9]
	s_addc_u32 s23, s23, 0
	s_add_i32 s24, s44, s26
	global_load_lds_dwordx4 v[148:149], off
	v_lshl_add_u64 v[148:149], s[22:23], 0, v[130:131]
	s_mov_b32 m0, s24
	s_nop 0
	global_load_lds_dwordx4 v[148:149], off
	v_lshl_add_u64 v[148:149], s[22:23], 0, v[134:135]
	s_add_i32 m0, s24, 0x2000
	s_nop 0
	global_load_lds_dwordx4 v[148:149], off
	v_lshl_add_u64 v[148:149], v[220:221], 0, s[8:9]
	s_mov_b32 m0, s31
	s_nop 0
	global_load_lds_dwordx4 v[148:149], off
	v_lshl_add_u64 v[148:149], v[222:223], 0, s[8:9]
	s_mov_b32 m0, s34
	s_nop 0
	global_load_lds_dwordx4 v[148:149], off
	s_mov_b64 vcc, s[98:99]
	s_cbranch_vccnz .Lvw_43
	s_waitcnt vmcnt(8)
; #define PG8_MMA(ai, bj, At, Bt) do { __builtin_amdgcn_s_setprio(1); _Pragma("unroll") for (int m = 0; m < 4; ++m) _Pragma("unroll") for (int n = 0; n < 2; ++n) _Pragma("unroll") for (int k = 0; k < 2; ++k) \
;         acc[ai][bj][m][n] = __builtin_amdgcn_mfma_f32_16x16x32_bf16(Bt[n][k], At[m][k], acc[ai][bj][m][n], 0, 0, 0); __builtin_amdgcn_s_setprio(0); } while (0)
; #define PG8_WAIT_V(n) asm volatile("s_waitcnt vmcnt(" #n ")" ::: "memory")
; #define PG8_WAIT_L(n) asm volatile("s_waitcnt lgkmcnt(" #n ")" ::: "memory")
; #define PG8_BAR __builtin_amdgcn_s_barrier()
; #define PG8_SCHED __builtin_amdgcn_sched_barrier(0)
; template <class Epi, class Sched, bool ALIGN_EPI = false, bool SP2 = false>
; __device__ __forceinline__ void gemm_phase(PG8_LAS unsigned char* lds, const Gemm g, const Sched& S, const Epi& E) {
;     ...
;             PG8_WAIT_V(8); PG8_WAIT_L(0); PG8_BAR; PG8_MMA(1, 0, At, B0); PG8_MMA(1, 1, At, B1); PG8_BAR; PG8_SCHED;
;     ...
;         if constexpr (ALIGN_EPI) { if (wr == 0) PG8_BAR; }
.Lvw_43:
	s_waitcnt lgkmcnt(0)
	s_barrier
	s_setprio 1
	s_waitcnt lgkmcnt(0)
	v_mfma_f32_16x16x32_bf16 v[60:63], v[144:147], v[184:187], v[60:63]
	v_mfma_f32_16x16x32_bf16 v[56:59], v[160:163], v[184:187], v[56:59]
	v_mfma_f32_16x16x32_bf16 v[40:43], v[160:163], v[194:197], v[40:43]
	v_mfma_f32_16x16x32_bf16 v[44:47], v[144:147], v[194:197], v[44:47]
	v_mfma_f32_16x16x32_bf16 v[28:31], v[144:147], v[202:205], v[28:31]
	v_mfma_f32_16x16x32_bf16 v[24:27], v[160:163], v[202:205], v[24:27]
	v_mfma_f32_16x16x32_bf16 v[8:11], v[160:163], v[210:213], v[8:11]
	v_mfma_f32_16x16x32_bf16 v[12:15], v[144:147], v[210:213], v[12:15]
	v_mfma_f32_16x16x32_bf16 v[60:63], v[156:159], v[188:191], v[60:63]
	v_mfma_f32_16x16x32_bf16 v[56:59], v[164:167], v[188:191], v[56:59]
	v_mfma_f32_16x16x32_bf16 v[40:43], v[164:167], v[198:201], v[40:43]
	v_mfma_f32_16x16x32_bf16 v[44:47], v[156:159], v[198:201], v[44:47]
	v_mfma_f32_16x16x32_bf16 v[28:31], v[156:159], v[206:209], v[28:31]
	v_mfma_f32_16x16x32_bf16 v[24:27], v[164:167], v[206:209], v[24:27]
	v_mfma_f32_16x16x32_bf16 v[8:11], v[164:167], v[214:217], v[8:11]
	v_mfma_f32_16x16x32_bf16 v[12:15], v[156:159], v[214:217], v[12:15]
	s_setprio 0
	s_setprio 1
	v_mfma_f32_16x16x32_bf16 v[52:55], v[168:171], v[184:187], v[52:55]
	v_mfma_f32_16x16x32_bf16 v[48:51], v[176:179], v[184:187], v[48:51]
	v_mfma_f32_16x16x32_bf16 v[32:35], v[176:179], v[194:197], v[32:35]
	v_mfma_f32_16x16x32_bf16 v[36:39], v[168:171], v[194:197], v[36:39]
	v_mfma_f32_16x16x32_bf16 v[20:23], v[168:171], v[202:205], v[20:23]
	v_mfma_f32_16x16x32_bf16 v[16:19], v[176:179], v[202:205], v[16:19]
	v_mfma_f32_16x16x32_bf16 v[0:3], v[176:179], v[210:213], v[0:3]
	v_mfma_f32_16x16x32_bf16 v[4:7], v[168:171], v[210:213], v[4:7]
	v_mfma_f32_16x16x32_bf16 v[52:55], v[172:175], v[188:191], v[52:55]
	v_mfma_f32_16x16x32_bf16 v[48:51], v[180:183], v[188:191], v[48:51]
	v_mfma_f32_16x16x32_bf16 v[32:35], v[180:183], v[198:201], v[32:35]
	v_mfma_f32_16x16x32_bf16 v[36:39], v[172:175], v[198:201], v[36:39]
	v_mfma_f32_16x16x32_bf16 v[20:23], v[172:175], v[206:209], v[20:23]
	v_mfma_f32_16x16x32_bf16 v[16:19], v[180:183], v[206:209], v[16:19]
	v_mfma_f32_16x16x32_bf16 v[0:3], v[180:183], v[214:217], v[0:3]
	v_mfma_f32_16x16x32_bf16 v[4:7], v[172:175], v[214:217], v[4:7]
	s_setprio 0
	s_waitcnt vmcnt(8)
	s_barrier
	s_add_i32 s42, s42, 2
	s_add_u32 s20, s20, 0x100
	s_addc_u32 s21, s21, 0
	s_add_u32 s40, s40, 0x100
	s_addc_u32 s41, s41, 0
	s_cmp_gt_u32 s42, 29
	s_cbranch_scc0 .LBB0_945
	s_and_b64 vcc, exec, s[10:11]
	s_cbranch_vccz .LBB0_948
	s_barrier

; #define PG8_STAGE(bufoff, gbase, voff) do { _Pragma("unroll") for (int _i = 0; _i < 2; ++_i) \
;         __builtin_amdgcn_global_load_lds((const unsigned*)((const char*)(gbase) + (voff)[_i]), (PG8_LAS unsigned*)(lds + (bufoff) + ldsw + _i * 8192), 16, 0, 0); } while (0)
; #define PG8_LDA(dst, b, h) do { _Pragma("unroll") for (int m = 0; m < 4; ++m) _Pragma("unroll") for (int k = 0; k < 2; ++k) dst[m][k] = *(const PG8_LAS bf16x8*)(lds + PG8_SA(b, h) + aoff + m * 2048 + k * 1024); } while (0)
; #define PG8_MMA(ai, bj, At, Bt) do { __builtin_amdgcn_s_setprio(1); _Pragma("unroll") for (int m = 0; m < 4; ++m) _Pragma("unroll") for (int n = 0; n < 2; ++n) _Pragma("unroll") for (int k = 0; k < 2; ++k) \
;         acc[ai][bj][m][n] = __builtin_amdgcn_mfma_f32_16x16x32_bf16(Bt[n][k], At[m][k], acc[ai][bj][m][n], 0, 0, 0); __builtin_amdgcn_s_setprio(0); } while (0)
; #define PG8_WAIT_V(n) asm volatile("s_waitcnt vmcnt(" #n ")" ::: "memory")
; #define PG8_WAIT_L(n) asm volatile("s_waitcnt lgkmcnt(" #n ")" ::: "memory")
; #define PG8_BAR __builtin_amdgcn_s_barrier()
; #define PG8_SCHED __builtin_amdgcn_sched_barrier(0)
; template <class Epi, class Sched, bool ALIGN_EPI = false, bool SP2 = false>
; __device__ __forceinline__ void gemm_phase(PG8_LAS unsigned char* lds, const Gemm g, const Sched& S, const Epi& E) {
;     ...
;             PG8_WAIT_V(8); PG8_WAIT_L(0); PG8_BAR; PG8_MMA(0, 0, At, B0); PG8_MMA(0, 1, At, B1); PG8_BAR; PG8_SCHED;
;             PG8_LDA(At, 0, 1); PG8_STAGE(PG8_SB(0, 0), b2, voffB); PG8_STAGE(PG8_SB(0, 1), b2 + hstep, voffB); PG8_STAGE(PG8_SA(0, 0), a2, voffA);
;             PG8_WAIT_V(8); PG8_WAIT_L(0); PG8_BAR; PG8_MMA(1, 0, At, B0); PG8_MMA(1, 1, At, B1); PG8_BAR; PG8_SCHED;
.Lvw_44:
	s_waitcnt lgkmcnt(0)
	s_barrier
	s_setprio 1
	s_waitcnt lgkmcnt(0)
	v_mfma_f32_16x16x32_bf16 v[124:127], v[150:153], v[182:185], v[124:127]
	v_mfma_f32_16x16x32_bf16 v[120:123], v[158:161], v[182:185], v[120:123]
	v_mfma_f32_16x16x32_bf16 v[112:115], v[158:161], v[194:197], v[112:115]
	v_mfma_f32_16x16x32_bf16 v[116:119], v[150:153], v[194:197], v[116:119]
	v_mfma_f32_16x16x32_bf16 v[100:103], v[150:153], v[202:205], v[100:103]
	v_mfma_f32_16x16x32_bf16 v[96:99], v[158:161], v[202:205], v[96:99]
	v_mfma_f32_16x16x32_bf16 v[80:83], v[158:161], v[210:213], v[80:83]
	v_mfma_f32_16x16x32_bf16 v[84:87], v[150:153], v[210:213], v[84:87]
	v_mfma_f32_16x16x32_bf16 v[124:127], v[154:157], v[186:189], v[124:127]
	v_mfma_f32_16x16x32_bf16 v[120:123], v[162:165], v[186:189], v[120:123]
	v_mfma_f32_16x16x32_bf16 v[112:115], v[162:165], v[198:201], v[112:115]
	v_mfma_f32_16x16x32_bf16 v[116:119], v[154:157], v[198:201], v[116:119]
	v_mfma_f32_16x16x32_bf16 v[100:103], v[154:157], v[206:209], v[100:103]
	v_mfma_f32_16x16x32_bf16 v[96:99], v[162:165], v[206:209], v[96:99]
	v_mfma_f32_16x16x32_bf16 v[80:83], v[162:165], v[214:217], v[80:83]
	v_mfma_f32_16x16x32_bf16 v[84:87], v[154:157], v[214:217], v[84:87]
	s_setprio 0
	s_setprio 1
	v_mfma_f32_16x16x32_bf16 v[108:111], v[166:169], v[182:185], v[108:111]
	v_mfma_f32_16x16x32_bf16 v[104:107], v[174:177], v[182:185], v[104:107]
	v_mfma_f32_16x16x32_bf16 v[88:91], v[174:177], v[194:197], v[88:91]
	v_mfma_f32_16x16x32_bf16 v[92:95], v[166:169], v[194:197], v[92:95]
	v_mfma_f32_16x16x32_bf16 v[76:79], v[166:169], v[202:205], v[76:79]
	v_mfma_f32_16x16x32_bf16 v[72:75], v[174:177], v[202:205], v[72:75]
	v_mfma_f32_16x16x32_bf16 v[64:67], v[174:177], v[210:213], v[64:67]
	v_mfma_f32_16x16x32_bf16 v[68:71], v[166:169], v[210:213], v[68:71]
	v_mfma_f32_16x16x32_bf16 v[108:111], v[170:173], v[186:189], v[108:111]
	v_mfma_f32_16x16x32_bf16 v[104:107], v[178:181], v[186:189], v[104:107]
	v_mfma_f32_16x16x32_bf16 v[88:91], v[178:181], v[198:201], v[88:91]
	v_mfma_f32_16x16x32_bf16 v[92:95], v[170:173], v[198:201], v[92:95]
	v_mfma_f32_16x16x32_bf16 v[76:79], v[170:173], v[206:209], v[76:79]
	v_mfma_f32_16x16x32_bf16 v[72:75], v[178:181], v[206:209], v[72:75]
	v_mfma_f32_16x16x32_bf16 v[64:67], v[178:181], v[214:217], v[64:67]
	v_mfma_f32_16x16x32_bf16 v[68:71], v[170:173], v[214:217], v[68:71]
	s_setprio 0
	s_waitcnt vmcnt(8)
	s_barrier
	s_add_i32 s55, s43, s2
	v_lshl_add_u64 v[190:191], s[30:31], 0, v[132:133]
	s_mov_b32 m0, s55
	ds_read_b128 v[182:185], v149 offset:16384
	ds_read_b128 v[186:189], v149 offset:17408
	ds_read_b128 v[194:197], v149 offset:18432
	ds_read_b128 v[198:201], v149 offset:19456
	ds_read_b128 v[202:205], v149 offset:20480
	ds_read_b128 v[206:209], v149 offset:21504
	ds_read_b128 v[210:213], v149 offset:22528
	ds_read_b128 v[214:217], v149 offset:23552
	global_load_lds_dwordx4 v[190:191], off
	s_add_i32 m0, s55, 0x2000
	s_add_u32 s56, s30, 0x80000
	v_lshl_add_u64 v[218:219], s[30:31], 0, v[128:129]
	s_addc_u32 s57, s31, 0
	s_add_i32 s55, s44, s2
	global_load_lds_dwordx4 v[218:219], off
	v_lshl_add_u64 v[220:221], s[56:57], 0, v[132:133]
	s_mov_b32 m0, s55
	v_lshl_add_u64 v[222:223], s[34:35], 0, v[130:131]
	global_load_lds_dwordx4 v[220:221], off
	v_lshl_add_u64 v[220:221], s[56:57], 0, v[128:129]
	s_add_i32 m0, s55, 0x2000
	s_nop 0
	global_load_lds_dwordx4 v[220:221], off
	v_lshl_add_u64 v[220:221], s[34:35], 0, v[134:135]
	s_mov_b32 m0, s19
	s_nop 0
	global_load_lds_dwordx4 v[220:221], off
	s_mov_b32 m0, s33
	s_nop 0
	global_load_lds_dwordx4 v[222:223], off
	s_mov_b64 vcc, s[98:99]
	s_cbranch_vccnz .Lvw_45
	s_waitcnt vmcnt(8)
.Lvw_45:
	s_waitcnt lgkmcnt(0)
	s_barrier
	s_setprio 1
	s_waitcnt lgkmcnt(0)
	v_mfma_f32_16x16x32_bf16 v[60:63], v[150:153], v[182:185], v[60:63]
	v_mfma_f32_16x16x32_bf16 v[56:59], v[158:161], v[182:185], v[56:59]
	v_mfma_f32_16x16x32_bf16 v[48:51], v[158:161], v[194:197], v[48:51]
	v_mfma_f32_16x16x32_bf16 v[52:55], v[150:153], v[194:197], v[52:55]
	v_mfma_f32_16x16x32_bf16 v[36:39], v[150:153], v[202:205], v[36:39]
	v_mfma_f32_16x16x32_bf16 v[32:35], v[158:161], v[202:205], v[32:35]
	v_mfma_f32_16x16x32_bf16 v[16:19], v[158:161], v[210:213], v[16:19]
	v_mfma_f32_16x16x32_bf16 v[20:23], v[150:153], v[210:213], v[20:23]
	v_mfma_f32_16x16x32_bf16 v[60:63], v[154:157], v[186:189], v[60:63]
	v_mfma_f32_16x16x32_bf16 v[56:59], v[162:165], v[186:189], v[56:59]
	v_mfma_f32_16x16x32_bf16 v[48:51], v[162:165], v[198:201], v[48:51]
	v_mfma_f32_16x16x32_bf16 v[52:55], v[154:157], v[198:201], v[52:55]
	v_mfma_f32_16x16x32_bf16 v[36:39], v[154:157], v[206:209], v[36:39]
	v_mfma_f32_16x16x32_bf16 v[32:35], v[162:165], v[206:209], v[32:35]
	v_mfma_f32_16x16x32_bf16 v[16:19], v[162:165], v[214:217], v[16:19]
	v_mfma_f32_16x16x32_bf16 v[20:23], v[154:157], v[214:217], v[20:23]
	s_setprio 0
	s_setprio 1
	v_mfma_f32_16x16x32_bf16 v[44:47], v[166:169], v[182:185], v[44:47]
	v_mfma_f32_16x16x32_bf16 v[40:43], v[174:177], v[182:185], v[40:43]
	v_mfma_f32_16x16x32_bf16 v[24:27], v[174:177], v[194:197], v[24:27]
	v_mfma_f32_16x16x32_bf16 v[28:31], v[166:169], v[194:197], v[28:31]
	v_mfma_f32_16x16x32_bf16 v[12:15], v[166:169], v[202:205], v[12:15]
	v_mfma_f32_16x16x32_bf16 v[8:11], v[174:177], v[202:205], v[8:11]
	v_mfma_f32_16x16x32_bf16 v[0:3], v[174:177], v[210:213], v[0:3]
	v_mfma_f32_16x16x32_bf16 v[4:7], v[166:169], v[210:213], v[4:7]
	v_mfma_f32_16x16x32_bf16 v[44:47], v[170:173], v[186:189], v[44:47]
	v_mfma_f32_16x16x32_bf16 v[40:43], v[178:181], v[186:189], v[40:43]
	v_mfma_f32_16x16x32_bf16 v[24:27], v[178:181], v[198:201], v[24:27]
	v_mfma_f32_16x16x32_bf16 v[28:31], v[170:173], v[198:201], v[28:31]
	v_mfma_f32_16x16x32_bf16 v[12:15], v[170:173], v[206:209], v[12:15]
	v_mfma_f32_16x16x32_bf16 v[8:11], v[178:181], v[206:209], v[8:11]
	v_mfma_f32_16x16x32_bf16 v[0:3], v[178:181], v[214:217], v[0:3]
	v_mfma_f32_16x16x32_bf16 v[4:7], v[170:173], v[214:217], v[4:7]
	s_setprio 0
	s_waitcnt vmcnt(8)
	s_barrier
; #define PG8_STAGE(bufoff, gbase, voff) do { _Pragma("unroll") for (int _i = 0; _i < 2; ++_i) \
;         __builtin_amdgcn_global_load_lds((const unsigned*)((const char*)(gbase) + (voff)[_i]), (PG8_LAS unsigned*)(lds + (bufoff) + ldsw + _i * 8192), 16, 0, 0); } while (0)
; #define PG8_LDA(dst, b, h) do { _Pragma("unroll") for (int m = 0; m < 4; ++m) _Pragma("unroll") for (int k = 0; k < 2; ++k) dst[m][k] = *(const PG8_LAS bf16x8*)(lds + PG8_SA(b, h) + aoff + m * 2048 + k * 1024); } while (0)
; #define PG8_LDB(dst, b, h) do { _Pragma("unroll") for (int n = 0; n < 2; ++n) _Pragma("unroll") for (int k = 0; k < 2; ++k) dst[n][k] = *(const PG8_LAS bf16x8*)(lds + PG8_SB(b, h) + boff + n * 2048 + k * 1024); } while (0)
; #define PG8_MMA(ai, bj, At, Bt) do { __builtin_amdgcn_s_setprio(1); _Pragma("unroll") for (int m = 0; m < 4; ++m) _Pragma("unroll") for (int n = 0; n < 2; ++n) _Pragma("unroll") for (int k = 0; k < 2; ++k) \
;         acc[ai][bj][m][n] = __builtin_amdgcn_mfma_f32_16x16x32_bf16(Bt[n][k], At[m][k], acc[ai][bj][m][n], 0, 0, 0); __builtin_amdgcn_s_setprio(0); } while (0)
; #define PG8_WAIT_V(n) asm volatile("s_waitcnt vmcnt(" #n ")" ::: "memory")
; #define PG8_WAIT_L(n) asm volatile("s_waitcnt lgkmcnt(" #n ")" ::: "memory")
; #define PG8_BAR __builtin_amdgcn_s_barrier()
; #define PG8_SCHED __builtin_amdgcn_sched_barrier(0)
; template <class Epi, class Sched, bool ALIGN_EPI = false, bool SP2 = false>
; __device__ __forceinline__ void gemm_phase(PG8_LAS unsigned char* lds, const Gemm g, const Sched& S, const Epi& E) {
;     ...
;             PG8_LDB(B0, 1, 0); PG8_LDB(B1, 1, 1); PG8_SCHED; PG8_LDA(At, 1, 0); PG8_STAGE(PG8_SA(0, 1), a2 + hstep, voffA);
;             PG8_WAIT_V(8); PG8_WAIT_L(0); PG8_BAR; PG8_MMA(0, 0, At, B0); PG8_MMA(0, 1, At, B1); PG8_BAR; PG8_SCHED;
;             PG8_LDA(At, 1, 1); PG8_STAGE(PG8_SB(1, 0), b3, voffB); PG8_STAGE(PG8_SB(1, 1), b3 + hstep, voffB); PG8_STAGE(PG8_SA(1, 0), a3, voffA);
	s_add_i32 s55, 0, 0x18000
	s_add_i32 s56, 0, 0x1c000
	v_add_u32_e32 v162, s55, v145
	v_add_u32_e32 v178, s56, v145
	ds_read_b128 v[150:153], v162
	ds_read_b128 v[154:157], v162 offset:1024
	ds_read_b128 v[158:161], v162 offset:2048
	ds_read_b128 v[162:165], v162 offset:3072
	ds_read_b128 v[166:169], v178
	ds_read_b128 v[170:173], v178 offset:1024
	ds_read_b128 v[174:177], v178 offset:2048
	ds_read_b128 v[178:181], v178 offset:3072
	s_add_u32 s34, s34, 0x80000
	s_addc_u32 s35, s35, 0
	s_mov_b32 m0, s36
	v_lshl_add_u64 v[224:225], s[34:35], 0, v[134:135]
	ds_read_b128 v[182:185], v149 offset:32768
	ds_read_b128 v[186:189], v149 offset:33792
	ds_read_b128 v[194:197], v149 offset:34816
	ds_read_b128 v[198:201], v149 offset:35840
	ds_read_b128 v[202:205], v149 offset:36864
	ds_read_b128 v[206:209], v149 offset:37888
	ds_read_b128 v[210:213], v149 offset:38912
	ds_read_b128 v[214:217], v149 offset:39936
	global_load_lds_dwordx4 v[224:225], off
	v_lshl_add_u64 v[224:225], s[34:35], 0, v[130:131]
	s_mov_b32 m0, s37
	s_nop 0
	global_load_lds_dwordx4 v[224:225], off
	s_mov_b64 vcc, s[98:99]
	s_cbranch_vccnz .Lvw_46
	s_waitcnt vmcnt(8)
.Lvw_46:
	s_waitcnt lgkmcnt(0)
	s_barrier
	s_setprio 1
	s_waitcnt lgkmcnt(0)
	v_mfma_f32_16x16x32_bf16 v[124:127], v[150:153], v[182:185], v[124:127]
	v_mfma_f32_16x16x32_bf16 v[120:123], v[158:161], v[182:185], v[120:123]
	v_mfma_f32_16x16x32_bf16 v[112:115], v[158:161], v[194:197], v[112:115]
	v_mfma_f32_16x16x32_bf16 v[116:119], v[150:153], v[194:197], v[116:119]
	v_mfma_f32_16x16x32_bf16 v[100:103], v[150:153], v[202:205], v[100:103]
	v_mfma_f32_16x16x32_bf16 v[96:99], v[158:161], v[202:205], v[96:99]
	v_mfma_f32_16x16x32_bf16 v[80:83], v[158:161], v[210:213], v[80:83]
	v_mfma_f32_16x16x32_bf16 v[84:87], v[150:153], v[210:213], v[84:87]
	v_mfma_f32_16x16x32_bf16 v[124:127], v[154:157], v[186:189], v[124:127]
	v_mfma_f32_16x16x32_bf16 v[120:123], v[162:165], v[186:189], v[120:123]
	v_mfma_f32_16x16x32_bf16 v[112:115], v[162:165], v[198:201], v[112:115]
	v_mfma_f32_16x16x32_bf16 v[116:119], v[154:157], v[198:201], v[116:119]
	v_mfma_f32_16x16x32_bf16 v[100:103], v[154:157], v[206:209], v[100:103]
	v_mfma_f32_16x16x32_bf16 v[96:99], v[162:165], v[206:209], v[96:99]
	v_mfma_f32_16x16x32_bf16 v[80:83], v[162:165], v[214:217], v[80:83]
	v_mfma_f32_16x16x32_bf16 v[84:87], v[154:157], v[214:217], v[84:87]
	s_setprio 0
	s_setprio 1
	v_mfma_f32_16x16x32_bf16 v[108:111], v[166:169], v[182:185], v[108:111]
	v_mfma_f32_16x16x32_bf16 v[104:107], v[174:177], v[182:185], v[104:107]
	v_mfma_f32_16x16x32_bf16 v[88:91], v[174:177], v[194:197], v[88:91]
	v_mfma_f32_16x16x32_bf16 v[92:95], v[166:169], v[194:197], v[92:95]
	v_mfma_f32_16x16x32_bf16 v[76:79], v[166:169], v[202:205], v[76:79]
	v_mfma_f32_16x16x32_bf16 v[72:75], v[174:177], v[202:205], v[72:75]
	v_mfma_f32_16x16x32_bf16 v[64:67], v[174:177], v[210:213], v[64:67]
	v_mfma_f32_16x16x32_bf16 v[68:71], v[166:169], v[210:213], v[68:71]
	v_mfma_f32_16x16x32_bf16 v[108:111], v[170:173], v[186:189], v[108:111]
	v_mfma_f32_16x16x32_bf16 v[104:107], v[178:181], v[186:189], v[104:107]
	v_mfma_f32_16x16x32_bf16 v[88:91], v[178:181], v[198:201], v[88:91]
	v_mfma_f32_16x16x32_bf16 v[92:95], v[170:173], v[198:201], v[92:95]
	v_mfma_f32_16x16x32_bf16 v[76:79], v[170:173], v[206:209], v[76:79]
	v_mfma_f32_16x16x32_bf16 v[72:75], v[178:181], v[206:209], v[72:75]
	v_mfma_f32_16x16x32_bf16 v[64:67], v[178:181], v[214:217], v[64:67]
	v_mfma_f32_16x16x32_bf16 v[68:71], v[170:173], v[214:217], v[68:71]
	s_setprio 0
	s_waitcnt vmcnt(8)
	s_barrier
	s_add_i32 s34, s55, s2
	v_lshl_add_u64 v[190:191], v[190:191], 0, s[8:9]
	s_mov_b32 m0, s34
	ds_read_b128 v[182:185], v149 offset:49152
	ds_read_b128 v[186:189], v149 offset:50176
	ds_read_b128 v[194:197], v149 offset:51200
	ds_read_b128 v[198:201], v149 offset:52224
	ds_read_b128 v[202:205], v149 offset:53248
	ds_read_b128 v[206:209], v149 offset:54272
	ds_read_b128 v[210:213], v149 offset:55296
	ds_read_b128 v[214:217], v149 offset:56320
	global_load_lds_dwordx4 v[190:191], off
	s_add_i32 m0, s34, 0x2000
	s_add_u32 s30, s30, 0x80080
	v_lshl_add_u64 v[190:191], v[218:219], 0, s[8:9]
	s_addc_u32 s31, s31, 0
	s_add_i32 s34, s56, s2
	global_load_lds_dwordx4 v[190:191], off
	v_lshl_add_u64 v[190:191], s[30:31], 0, v[132:133]
	s_mov_b32 m0, s34
	s_nop 0
	global_load_lds_dwordx4 v[190:191], off
	v_lshl_add_u64 v[190:191], s[30:31], 0, v[128:129]
	s_add_i32 m0, s34, 0x2000
	s_nop 0
	global_load_lds_dwordx4 v[190:191], off
	v_lshl_add_u64 v[190:191], v[220:221], 0, s[8:9]
	s_mov_b32 m0, s39
	s_nop 0
	global_load_lds_dwordx4 v[190:191], off
	v_lshl_add_u64 v[190:191], v[222:223], 0, s[8:9]
	s_mov_b32 m0, s40
	s_nop 0
	global_load_lds_dwordx4 v[190:191], off
	s_mov_b64 vcc, s[98:99]
	s_cbranch_vccnz .Lvw_47
	s_waitcnt vmcnt(8)
; #define PG8_MMA(ai, bj, At, Bt) do { __builtin_amdgcn_s_setprio(1); _Pragma("unroll") for (int m = 0; m < 4; ++m) _Pragma("unroll") for (int n = 0; n < 2; ++n) _Pragma("unroll") for (int k = 0; k < 2; ++k) \
;         acc[ai][bj][m][n] = __builtin_amdgcn_mfma_f32_16x16x32_bf16(Bt[n][k], At[m][k], acc[ai][bj][m][n], 0, 0, 0); __builtin_amdgcn_s_setprio(0); } while (0)
; #define PG8_WAIT_V(n) asm volatile("s_waitcnt vmcnt(" #n ")" ::: "memory")
; #define PG8_WAIT_L(n) asm volatile("s_waitcnt lgkmcnt(" #n ")" ::: "memory")
; #define PG8_BAR __builtin_amdgcn_s_barrier()
; #define PG8_SCHED __builtin_amdgcn_sched_barrier(0)
; template <class Epi, class Sched, bool ALIGN_EPI = false, bool SP2 = false>
; __device__ __forceinline__ void gemm_phase(PG8_LAS unsigned char* lds, const Gemm g, const Sched& S, const Epi& E) {
;     ...
;             PG8_WAIT_V(8); PG8_WAIT_L(0); PG8_BAR; PG8_MMA(1, 0, At, B0); PG8_MMA(1, 1, At, B1); PG8_BAR; PG8_SCHED;
;     ...
;         if constexpr (ALIGN_EPI) { if (wr == 0) PG8_BAR; }
.Lvw_47:
	s_waitcnt lgkmcnt(0)
	s_barrier
	s_setprio 1
	s_waitcnt lgkmcnt(0)
	v_mfma_f32_16x16x32_bf16 v[60:63], v[150:153], v[182:185], v[60:63]
	v_mfma_f32_16x16x32_bf16 v[56:59], v[158:161], v[182:185], v[56:59]
	v_mfma_f32_16x16x32_bf16 v[48:51], v[158:161], v[194:197], v[48:51]
	v_mfma_f32_16x16x32_bf16 v[52:55], v[150:153], v[194:197], v[52:55]
	v_mfma_f32_16x16x32_bf16 v[36:39], v[150:153], v[202:205], v[36:39]
	v_mfma_f32_16x16x32_bf16 v[32:35], v[158:161], v[202:205], v[32:35]
	v_mfma_f32_16x16x32_bf16 v[16:19], v[158:161], v[210:213], v[16:19]
	v_mfma_f32_16x16x32_bf16 v[20:23], v[150:153], v[210:213], v[20:23]
	v_mfma_f32_16x16x32_bf16 v[60:63], v[154:157], v[186:189], v[60:63]
	v_mfma_f32_16x16x32_bf16 v[56:59], v[162:165], v[186:189], v[56:59]
	v_mfma_f32_16x16x32_bf16 v[48:51], v[162:165], v[198:201], v[48:51]
	v_mfma_f32_16x16x32_bf16 v[52:55], v[154:157], v[198:201], v[52:55]
	v_mfma_f32_16x16x32_bf16 v[36:39], v[154:157], v[206:209], v[36:39]
	v_mfma_f32_16x16x32_bf16 v[32:35], v[162:165], v[206:209], v[32:35]
	v_mfma_f32_16x16x32_bf16 v[16:19], v[162:165], v[214:217], v[16:19]
	v_mfma_f32_16x16x32_bf16 v[20:23], v[154:157], v[214:217], v[20:23]
	s_setprio 0
	s_setprio 1
	v_mfma_f32_16x16x32_bf16 v[44:47], v[166:169], v[182:185], v[44:47]
	v_mfma_f32_16x16x32_bf16 v[40:43], v[174:177], v[182:185], v[40:43]
	v_mfma_f32_16x16x32_bf16 v[24:27], v[174:177], v[194:197], v[24:27]
	v_mfma_f32_16x16x32_bf16 v[28:31], v[166:169], v[194:197], v[28:31]
	v_mfma_f32_16x16x32_bf16 v[12:15], v[166:169], v[202:205], v[12:15]
	v_mfma_f32_16x16x32_bf16 v[8:11], v[174:177], v[202:205], v[8:11]
	v_mfma_f32_16x16x32_bf16 v[0:3], v[174:177], v[210:213], v[0:3]
	v_mfma_f32_16x16x32_bf16 v[4:7], v[166:169], v[210:213], v[4:7]
	v_mfma_f32_16x16x32_bf16 v[44:47], v[170:173], v[186:189], v[44:47]
	v_mfma_f32_16x16x32_bf16 v[40:43], v[178:181], v[186:189], v[40:43]
	v_mfma_f32_16x16x32_bf16 v[24:27], v[178:181], v[198:201], v[24:27]
	v_mfma_f32_16x16x32_bf16 v[28:31], v[170:173], v[198:201], v[28:31]
	v_mfma_f32_16x16x32_bf16 v[12:15], v[170:173], v[206:209], v[12:15]
	v_mfma_f32_16x16x32_bf16 v[8:11], v[178:181], v[206:209], v[8:11]
	v_mfma_f32_16x16x32_bf16 v[0:3], v[178:181], v[214:217], v[0:3]
	v_mfma_f32_16x16x32_bf16 v[4:7], v[170:173], v[214:217], v[4:7]
	s_setprio 0
	s_waitcnt vmcnt(8)
	s_barrier
	s_add_i32 s54, s54, 2
	s_add_u32 s28, s28, 0x100
	s_addc_u32 s29, s29, 0
	s_add_u32 s52, s52, 0x100
	s_addc_u32 s53, s53, 0
	s_cmp_gt_u32 s54, 29
	s_cbranch_scc0 .LBB0_1013
	s_and_b64 vcc, exec, s[10:11]
	s_cbranch_vccz .LBB0_1016
	s_barrier

; #define PG8_STAGE(bufoff, gbase, voff) do { _Pragma("unroll") for (int _i = 0; _i < 2; ++_i) \
;         __builtin_amdgcn_global_load_lds((const unsigned*)((const char*)(gbase) + (voff)[_i]), (PG8_LAS unsigned*)(lds + (bufoff) + ldsw + _i * 8192), 16, 0, 0); } while (0)
; #define PG8_LDA(dst, b, h) do { _Pragma("unroll") for (int m = 0; m < 4; ++m) _Pragma("unroll") for (int k = 0; k < 2; ++k) dst[m][k] = *(const PG8_LAS bf16x8*)(lds + PG8_SA(b, h) + aoff + m * 2048 + k * 1024); } while (0)
; #define PG8_MMA(ai, bj, At, Bt) do { __builtin_amdgcn_s_setprio(1); _Pragma("unroll") for (int m = 0; m < 4; ++m) _Pragma("unroll") for (int n = 0; n < 2; ++n) _Pragma("unroll") for (int k = 0; k < 2; ++k) \
;         acc[ai][bj][m][n] = __builtin_amdgcn_mfma_f32_16x16x32_bf16(Bt[n][k], At[m][k], acc[ai][bj][m][n], 0, 0, 0); __builtin_amdgcn_s_setprio(0); } while (0)
; #define PG8_WAIT_V(n) asm volatile("s_waitcnt vmcnt(" #n ")" ::: "memory")
; #define PG8_WAIT_L(n) asm volatile("s_waitcnt lgkmcnt(" #n ")" ::: "memory")
; #define PG8_BAR __builtin_amdgcn_s_barrier()
; #define PG8_SCHED __builtin_amdgcn_sched_barrier(0)
; template <class Epi, class Sched, bool ALIGN_EPI = false, bool SP2 = false>
; __device__ __forceinline__ void gemm_phase(PG8_LAS unsigned char* lds, const Gemm g, const Sched& S, const Epi& E) {
;     ...
;             PG8_WAIT_V(8); PG8_WAIT_L(0); PG8_BAR; PG8_MMA(0, 0, At, B0); PG8_MMA(0, 1, At, B1); PG8_BAR; PG8_SCHED;
;             PG8_LDA(At, 0, 1); PG8_STAGE(PG8_SB(0, 0), b2, voffB); PG8_STAGE(PG8_SB(0, 1), b2 + hstep, voffB); PG8_STAGE(PG8_SA(0, 0), a2, voffA);
;             PG8_WAIT_V(8); PG8_WAIT_L(0); PG8_BAR; PG8_MMA(1, 0, At, B0); PG8_MMA(1, 1, At, B1); PG8_BAR; PG8_SCHED;
.Lvw_48:
	s_waitcnt lgkmcnt(0)
	s_barrier
	s_setprio 1
	s_waitcnt lgkmcnt(0)
	v_mfma_f32_16x16x32_bf16 v[124:127], v[150:153], v[182:185], v[124:127]
	v_mfma_f32_16x16x32_bf16 v[120:123], v[158:161], v[182:185], v[120:123]
	v_mfma_f32_16x16x32_bf16 v[104:107], v[158:161], v[194:197], v[104:107]
	v_mfma_f32_16x16x32_bf16 v[108:111], v[150:153], v[194:197], v[108:111]
	v_mfma_f32_16x16x32_bf16 v[92:95], v[150:153], v[202:205], v[92:95]
	v_mfma_f32_16x16x32_bf16 v[88:91], v[158:161], v[202:205], v[88:91]
	v_mfma_f32_16x16x32_bf16 v[72:75], v[158:161], v[210:213], v[72:75]
	v_mfma_f32_16x16x32_bf16 v[76:79], v[150:153], v[210:213], v[76:79]
	v_mfma_f32_16x16x32_bf16 v[124:127], v[154:157], v[186:189], v[124:127]
	v_mfma_f32_16x16x32_bf16 v[120:123], v[162:165], v[186:189], v[120:123]
	v_mfma_f32_16x16x32_bf16 v[104:107], v[162:165], v[198:201], v[104:107]
	v_mfma_f32_16x16x32_bf16 v[108:111], v[154:157], v[198:201], v[108:111]
	v_mfma_f32_16x16x32_bf16 v[92:95], v[154:157], v[206:209], v[92:95]
	v_mfma_f32_16x16x32_bf16 v[88:91], v[162:165], v[206:209], v[88:91]
	v_mfma_f32_16x16x32_bf16 v[72:75], v[162:165], v[214:217], v[72:75]
	v_mfma_f32_16x16x32_bf16 v[76:79], v[154:157], v[214:217], v[76:79]
	s_setprio 0
	s_setprio 1
	v_mfma_f32_16x16x32_bf16 v[116:119], v[166:169], v[182:185], v[116:119]
	v_mfma_f32_16x16x32_bf16 v[112:115], v[174:177], v[182:185], v[112:115]
	v_mfma_f32_16x16x32_bf16 v[96:99], v[174:177], v[194:197], v[96:99]
	v_mfma_f32_16x16x32_bf16 v[100:103], v[166:169], v[194:197], v[100:103]
	v_mfma_f32_16x16x32_bf16 v[84:87], v[166:169], v[202:205], v[84:87]
	v_mfma_f32_16x16x32_bf16 v[80:83], v[174:177], v[202:205], v[80:83]
	v_mfma_f32_16x16x32_bf16 v[64:67], v[174:177], v[210:213], v[64:67]
	v_mfma_f32_16x16x32_bf16 v[68:71], v[166:169], v[210:213], v[68:71]
	v_mfma_f32_16x16x32_bf16 v[116:119], v[170:173], v[186:189], v[116:119]
	v_mfma_f32_16x16x32_bf16 v[112:115], v[178:181], v[186:189], v[112:115]
	v_mfma_f32_16x16x32_bf16 v[96:99], v[178:181], v[198:201], v[96:99]
	v_mfma_f32_16x16x32_bf16 v[100:103], v[170:173], v[198:201], v[100:103]
	v_mfma_f32_16x16x32_bf16 v[84:87], v[170:173], v[206:209], v[84:87]
	v_mfma_f32_16x16x32_bf16 v[80:83], v[178:181], v[206:209], v[80:83]
	v_mfma_f32_16x16x32_bf16 v[64:67], v[178:181], v[214:217], v[64:67]
	v_mfma_f32_16x16x32_bf16 v[68:71], v[170:173], v[214:217], v[68:71]
	s_setprio 0
	s_waitcnt vmcnt(8)
	s_barrier
	s_add_i32 s47, s38, s3
	v_lshl_add_u64 v[190:191], s[22:23], 0, v[132:133]
	s_mov_b32 m0, s47
	ds_read_b128 v[182:185], v149 offset:16384
	ds_read_b128 v[186:189], v149 offset:17408
	ds_read_b128 v[194:197], v149 offset:18432
	ds_read_b128 v[198:201], v149 offset:19456
	ds_read_b128 v[202:205], v149 offset:20480
	ds_read_b128 v[206:209], v149 offset:21504
	ds_read_b128 v[210:213], v149 offset:22528
	ds_read_b128 v[214:217], v149 offset:23552
	global_load_lds_dwordx4 v[190:191], off
	s_add_i32 m0, s47, 0x2000
	s_add_u32 s48, s22, 0x80000
	v_lshl_add_u64 v[218:219], s[22:23], 0, v[128:129]
	s_addc_u32 s49, s23, 0
	s_add_i32 s47, s39, s3
	global_load_lds_dwordx4 v[218:219], off
	v_lshl_add_u64 v[220:221], s[48:49], 0, v[132:133]
	s_mov_b32 m0, s47
	v_lshl_add_u64 v[222:223], s[24:25], 0, v[130:131]
	global_load_lds_dwordx4 v[220:221], off
	v_lshl_add_u64 v[220:221], s[48:49], 0, v[128:129]
	s_add_i32 m0, s47, 0x2000
	s_nop 0
	global_load_lds_dwordx4 v[220:221], off
	v_lshl_add_u64 v[220:221], s[24:25], 0, v[134:135]
	s_mov_b32 m0, s19
	s_nop 0
	global_load_lds_dwordx4 v[220:221], off
	s_mov_b32 m0, s29
	s_nop 0
	global_load_lds_dwordx4 v[222:223], off
	s_mov_b64 vcc, s[98:99]
	s_cbranch_vccnz .Lvw_49
	s_waitcnt vmcnt(8)
.Lvw_49:
	s_waitcnt lgkmcnt(0)
	s_barrier
	s_setprio 1
	s_waitcnt lgkmcnt(0)
	v_mfma_f32_16x16x32_bf16 v[60:63], v[150:153], v[182:185], v[60:63]
	v_mfma_f32_16x16x32_bf16 v[56:59], v[158:161], v[182:185], v[56:59]
	v_mfma_f32_16x16x32_bf16 v[40:43], v[158:161], v[194:197], v[40:43]
	v_mfma_f32_16x16x32_bf16 v[44:47], v[150:153], v[194:197], v[44:47]
	v_mfma_f32_16x16x32_bf16 v[28:31], v[150:153], v[202:205], v[28:31]
	v_mfma_f32_16x16x32_bf16 v[24:27], v[158:161], v[202:205], v[24:27]
	v_mfma_f32_16x16x32_bf16 v[8:11], v[158:161], v[210:213], v[8:11]
	v_mfma_f32_16x16x32_bf16 v[12:15], v[150:153], v[210:213], v[12:15]
	v_mfma_f32_16x16x32_bf16 v[60:63], v[154:157], v[186:189], v[60:63]
	v_mfma_f32_16x16x32_bf16 v[56:59], v[162:165], v[186:189], v[56:59]
	v_mfma_f32_16x16x32_bf16 v[40:43], v[162:165], v[198:201], v[40:43]
	v_mfma_f32_16x16x32_bf16 v[44:47], v[154:157], v[198:201], v[44:47]
	v_mfma_f32_16x16x32_bf16 v[28:31], v[154:157], v[206:209], v[28:31]
	v_mfma_f32_16x16x32_bf16 v[24:27], v[162:165], v[206:209], v[24:27]
	v_mfma_f32_16x16x32_bf16 v[8:11], v[162:165], v[214:217], v[8:11]
	v_mfma_f32_16x16x32_bf16 v[12:15], v[154:157], v[214:217], v[12:15]
	s_setprio 0
	s_setprio 1
	v_mfma_f32_16x16x32_bf16 v[52:55], v[166:169], v[182:185], v[52:55]
	v_mfma_f32_16x16x32_bf16 v[48:51], v[174:177], v[182:185], v[48:51]
	v_mfma_f32_16x16x32_bf16 v[32:35], v[174:177], v[194:197], v[32:35]
	v_mfma_f32_16x16x32_bf16 v[36:39], v[166:169], v[194:197], v[36:39]
	v_mfma_f32_16x16x32_bf16 v[20:23], v[166:169], v[202:205], v[20:23]
	v_mfma_f32_16x16x32_bf16 v[16:19], v[174:177], v[202:205], v[16:19]
	v_mfma_f32_16x16x32_bf16 v[0:3], v[174:177], v[210:213], v[0:3]
	v_mfma_f32_16x16x32_bf16 v[4:7], v[166:169], v[210:213], v[4:7]
	v_mfma_f32_16x16x32_bf16 v[52:55], v[170:173], v[186:189], v[52:55]
	v_mfma_f32_16x16x32_bf16 v[48:51], v[178:181], v[186:189], v[48:51]
	v_mfma_f32_16x16x32_bf16 v[32:35], v[178:181], v[198:201], v[32:35]
	v_mfma_f32_16x16x32_bf16 v[36:39], v[170:173], v[198:201], v[36:39]
	v_mfma_f32_16x16x32_bf16 v[20:23], v[170:173], v[206:209], v[20:23]
	v_mfma_f32_16x16x32_bf16 v[16:19], v[178:181], v[206:209], v[16:19]
	v_mfma_f32_16x16x32_bf16 v[0:3], v[178:181], v[214:217], v[0:3]
	v_mfma_f32_16x16x32_bf16 v[4:7], v[170:173], v[214:217], v[4:7]
	s_setprio 0
	s_waitcnt vmcnt(8)
	s_barrier
; #define PG8_STAGE(bufoff, gbase, voff) do { _Pragma("unroll") for (int _i = 0; _i < 2; ++_i) \
;         __builtin_amdgcn_global_load_lds((const unsigned*)((const char*)(gbase) + (voff)[_i]), (PG8_LAS unsigned*)(lds + (bufoff) + ldsw + _i * 8192), 16, 0, 0); } while (0)
; #define PG8_LDA(dst, b, h) do { _Pragma("unroll") for (int m = 0; m < 4; ++m) _Pragma("unroll") for (int k = 0; k < 2; ++k) dst[m][k] = *(const PG8_LAS bf16x8*)(lds + PG8_SA(b, h) + aoff + m * 2048 + k * 1024); } while (0)
; #define PG8_LDB(dst, b, h) do { _Pragma("unroll") for (int n = 0; n < 2; ++n) _Pragma("unroll") for (int k = 0; k < 2; ++k) dst[n][k] = *(const PG8_LAS bf16x8*)(lds + PG8_SB(b, h) + boff + n * 2048 + k * 1024); } while (0)
; #define PG8_MMA(ai, bj, At, Bt) do { __builtin_amdgcn_s_setprio(1); _Pragma("unroll") for (int m = 0; m < 4; ++m) _Pragma("unroll") for (int n = 0; n < 2; ++n) _Pragma("unroll") for (int k = 0; k < 2; ++k) \
;         acc[ai][bj][m][n] = __builtin_amdgcn_mfma_f32_16x16x32_bf16(Bt[n][k], At[m][k], acc[ai][bj][m][n], 0, 0, 0); __builtin_amdgcn_s_setprio(0); } while (0)
; #define PG8_WAIT_V(n) asm volatile("s_waitcnt vmcnt(" #n ")" ::: "memory")
; #define PG8_WAIT_L(n) asm volatile("s_waitcnt lgkmcnt(" #n ")" ::: "memory")
; #define PG8_BAR __builtin_amdgcn_s_barrier()
; #define PG8_SCHED __builtin_amdgcn_sched_barrier(0)
; template <class Epi, class Sched, bool ALIGN_EPI = false, bool SP2 = false>
; __device__ __forceinline__ void gemm_phase(PG8_LAS unsigned char* lds, const Gemm g, const Sched& S, const Epi& E) {
;     ...
;             PG8_LDB(B0, 1, 0); PG8_LDB(B1, 1, 1); PG8_SCHED; PG8_LDA(At, 1, 0); PG8_STAGE(PG8_SA(0, 1), a2 + hstep, voffA);
;             PG8_WAIT_V(8); PG8_WAIT_L(0); PG8_BAR; PG8_MMA(0, 0, At, B0); PG8_MMA(0, 1, At, B1); PG8_BAR; PG8_SCHED;
;             PG8_LDA(At, 1, 1); PG8_STAGE(PG8_SB(1, 0), b3, voffB); PG8_STAGE(PG8_SB(1, 1), b3 + hstep, voffB); PG8_STAGE(PG8_SA(1, 0), a3, voffA);
	s_add_i32 s47, 0, 0x18000
	s_add_i32 s48, 0, 0x1c000
	v_add_u32_e32 v162, s47, v145
	v_add_u32_e32 v178, s48, v145
	ds_read_b128 v[150:153], v162
	ds_read_b128 v[154:157], v162 offset:1024
	ds_read_b128 v[158:161], v162 offset:2048
	ds_read_b128 v[162:165], v162 offset:3072
	ds_read_b128 v[166:169], v178
	ds_read_b128 v[170:173], v178 offset:1024
	ds_read_b128 v[174:177], v178 offset:2048
	ds_read_b128 v[178:181], v178 offset:3072
	s_add_u32 s24, s24, 0x80000
	s_addc_u32 s25, s25, 0
	s_mov_b32 m0, s30
	v_lshl_add_u64 v[224:225], s[24:25], 0, v[134:135]
	ds_read_b128 v[182:185], v149 offset:32768
	ds_read_b128 v[186:189], v149 offset:33792
	ds_read_b128 v[194:197], v149 offset:34816
	ds_read_b128 v[198:201], v149 offset:35840
	ds_read_b128 v[202:205], v149 offset:36864
	ds_read_b128 v[206:209], v149 offset:37888
	ds_read_b128 v[210:213], v149 offset:38912
	ds_read_b128 v[214:217], v149 offset:39936
	global_load_lds_dwordx4 v[224:225], off
	v_lshl_add_u64 v[224:225], s[24:25], 0, v[130:131]
	s_mov_b32 m0, s31
	s_nop 0
	global_load_lds_dwordx4 v[224:225], off
	s_mov_b64 vcc, s[98:99]
	s_cbranch_vccnz .Lvw_50
	s_waitcnt vmcnt(8)
.Lvw_50:
	s_waitcnt lgkmcnt(0)
	s_barrier
	s_setprio 1
	s_waitcnt lgkmcnt(0)
	v_mfma_f32_16x16x32_bf16 v[124:127], v[150:153], v[182:185], v[124:127]
	v_mfma_f32_16x16x32_bf16 v[120:123], v[158:161], v[182:185], v[120:123]
	v_mfma_f32_16x16x32_bf16 v[104:107], v[158:161], v[194:197], v[104:107]
	v_mfma_f32_16x16x32_bf16 v[108:111], v[150:153], v[194:197], v[108:111]
	v_mfma_f32_16x16x32_bf16 v[92:95], v[150:153], v[202:205], v[92:95]
	v_mfma_f32_16x16x32_bf16 v[88:91], v[158:161], v[202:205], v[88:91]
	v_mfma_f32_16x16x32_bf16 v[72:75], v[158:161], v[210:213], v[72:75]
	v_mfma_f32_16x16x32_bf16 v[76:79], v[150:153], v[210:213], v[76:79]
	v_mfma_f32_16x16x32_bf16 v[124:127], v[154:157], v[186:189], v[124:127]
	v_mfma_f32_16x16x32_bf16 v[120:123], v[162:165], v[186:189], v[120:123]
	v_mfma_f32_16x16x32_bf16 v[104:107], v[162:165], v[198:201], v[104:107]
	v_mfma_f32_16x16x32_bf16 v[108:111], v[154:157], v[198:201], v[108:111]
	v_mfma_f32_16x16x32_bf16 v[92:95], v[154:157], v[206:209], v[92:95]
	v_mfma_f32_16x16x32_bf16 v[88:91], v[162:165], v[206:209], v[88:91]
	v_mfma_f32_16x16x32_bf16 v[72:75], v[162:165], v[214:217], v[72:75]
	v_mfma_f32_16x16x32_bf16 v[76:79], v[154:157], v[214:217], v[76:79]
	s_setprio 0
	s_setprio 1
	v_mfma_f32_16x16x32_bf16 v[116:119], v[166:169], v[182:185], v[116:119]
	v_mfma_f32_16x16x32_bf16 v[112:115], v[174:177], v[182:185], v[112:115]
	v_mfma_f32_16x16x32_bf16 v[96:99], v[174:177], v[194:197], v[96:99]
	v_mfma_f32_16x16x32_bf16 v[100:103], v[166:169], v[194:197], v[100:103]
	v_mfma_f32_16x16x32_bf16 v[84:87], v[166:169], v[202:205], v[84:87]
	v_mfma_f32_16x16x32_bf16 v[80:83], v[174:177], v[202:205], v[80:83]
	v_mfma_f32_16x16x32_bf16 v[64:67], v[174:177], v[210:213], v[64:67]
	v_mfma_f32_16x16x32_bf16 v[68:71], v[166:169], v[210:213], v[68:71]
	v_mfma_f32_16x16x32_bf16 v[116:119], v[170:173], v[186:189], v[116:119]
	v_mfma_f32_16x16x32_bf16 v[112:115], v[178:181], v[186:189], v[112:115]
	v_mfma_f32_16x16x32_bf16 v[96:99], v[178:181], v[198:201], v[96:99]
	v_mfma_f32_16x16x32_bf16 v[100:103], v[170:173], v[198:201], v[100:103]
	v_mfma_f32_16x16x32_bf16 v[84:87], v[170:173], v[206:209], v[84:87]
	v_mfma_f32_16x16x32_bf16 v[80:83], v[178:181], v[206:209], v[80:83]
	v_mfma_f32_16x16x32_bf16 v[64:67], v[178:181], v[214:217], v[64:67]
	v_mfma_f32_16x16x32_bf16 v[68:71], v[170:173], v[214:217], v[68:71]
	s_setprio 0
	s_waitcnt vmcnt(8)
	s_barrier
	s_add_i32 s24, s47, s3
	v_lshl_add_u64 v[190:191], v[190:191], 0, s[6:7]
	s_mov_b32 m0, s24
	ds_read_b128 v[182:185], v149 offset:49152
	ds_read_b128 v[186:189], v149 offset:50176
	ds_read_b128 v[194:197], v149 offset:51200
	ds_read_b128 v[198:201], v149 offset:52224
	ds_read_b128 v[202:205], v149 offset:53248
	ds_read_b128 v[206:209], v149 offset:54272
	ds_read_b128 v[210:213], v149 offset:55296
	ds_read_b128 v[214:217], v149 offset:56320
	global_load_lds_dwordx4 v[190:191], off
	s_add_i32 m0, s24, 0x2000
	s_add_u32 s22, s22, 0x80080
	v_lshl_add_u64 v[190:191], v[218:219], 0, s[6:7]
	s_addc_u32 s23, s23, 0
	s_add_i32 s24, s48, s3
	global_load_lds_dwordx4 v[190:191], off
	v_lshl_add_u64 v[190:191], s[22:23], 0, v[132:133]
	s_mov_b32 m0, s24
	s_nop 0
	global_load_lds_dwordx4 v[190:191], off
	v_lshl_add_u64 v[190:191], s[22:23], 0, v[128:129]
	s_add_i32 m0, s24, 0x2000
	s_nop 0
	global_load_lds_dwordx4 v[190:191], off
	v_lshl_add_u64 v[190:191], v[220:221], 0, s[6:7]
	s_mov_b32 m0, s34
	s_nop 0
	global_load_lds_dwordx4 v[190:191], off
	v_lshl_add_u64 v[190:191], v[222:223], 0, s[6:7]
	s_mov_b32 m0, s35
	s_nop 0
	global_load_lds_dwordx4 v[190:191], off
	s_mov_b64 vcc, s[98:99]
	s_cbranch_vccnz .Lvw_51
	s_waitcnt vmcnt(8)
; #define PG8_MMA(ai, bj, At, Bt) do { __builtin_amdgcn_s_setprio(1); _Pragma("unroll") for (int m = 0; m < 4; ++m) _Pragma("unroll") for (int n = 0; n < 2; ++n) _Pragma("unroll") for (int k = 0; k < 2; ++k) \
;         acc[ai][bj][m][n] = __builtin_amdgcn_mfma_f32_16x16x32_bf16(Bt[n][k], At[m][k], acc[ai][bj][m][n], 0, 0, 0); __builtin_amdgcn_s_setprio(0); } while (0)
; #define PG8_WAIT_V(n) asm volatile("s_waitcnt vmcnt(" #n ")" ::: "memory")
; #define PG8_WAIT_L(n) asm volatile("s_waitcnt lgkmcnt(" #n ")" ::: "memory")
; #define PG8_BAR __builtin_amdgcn_s_barrier()
; #define PG8_SCHED __builtin_amdgcn_sched_barrier(0)
; template <class Epi, class Sched, bool ALIGN_EPI = false, bool SP2 = false>
; __device__ __forceinline__ void gemm_phase(PG8_LAS unsigned char* lds, const Gemm g, const Sched& S, const Epi& E) {
;     ...
;             PG8_WAIT_V(8); PG8_WAIT_L(0); PG8_BAR; PG8_MMA(1, 0, At, B0); PG8_MMA(1, 1, At, B1); PG8_BAR; PG8_SCHED;
;     ...
;         if constexpr (ALIGN_EPI) { if (wr == 0) PG8_BAR; }
.Lvw_51:
	s_waitcnt lgkmcnt(0)
	s_barrier
	s_setprio 1
	s_waitcnt lgkmcnt(0)
	v_mfma_f32_16x16x32_bf16 v[60:63], v[150:153], v[182:185], v[60:63]
	v_mfma_f32_16x16x32_bf16 v[56:59], v[158:161], v[182:185], v[56:59]
	v_mfma_f32_16x16x32_bf16 v[40:43], v[158:161], v[194:197], v[40:43]
	v_mfma_f32_16x16x32_bf16 v[44:47], v[150:153], v[194:197], v[44:47]
	v_mfma_f32_16x16x32_bf16 v[28:31], v[150:153], v[202:205], v[28:31]
	v_mfma_f32_16x16x32_bf16 v[24:27], v[158:161], v[202:205], v[24:27]
	v_mfma_f32_16x16x32_bf16 v[8:11], v[158:161], v[210:213], v[8:11]
	v_mfma_f32_16x16x32_bf16 v[12:15], v[150:153], v[210:213], v[12:15]
	v_mfma_f32_16x16x32_bf16 v[60:63], v[154:157], v[186:189], v[60:63]
	v_mfma_f32_16x16x32_bf16 v[56:59], v[162:165], v[186:189], v[56:59]
	v_mfma_f32_16x16x32_bf16 v[40:43], v[162:165], v[198:201], v[40:43]
	v_mfma_f32_16x16x32_bf16 v[44:47], v[154:157], v[198:201], v[44:47]
	v_mfma_f32_16x16x32_bf16 v[28:31], v[154:157], v[206:209], v[28:31]
	v_mfma_f32_16x16x32_bf16 v[24:27], v[162:165], v[206:209], v[24:27]
	v_mfma_f32_16x16x32_bf16 v[8:11], v[162:165], v[214:217], v[8:11]
	v_mfma_f32_16x16x32_bf16 v[12:15], v[154:157], v[214:217], v[12:15]
	s_setprio 0
	s_setprio 1
	v_mfma_f32_16x16x32_bf16 v[52:55], v[166:169], v[182:185], v[52:55]
	v_mfma_f32_16x16x32_bf16 v[48:51], v[174:177], v[182:185], v[48:51]
	v_mfma_f32_16x16x32_bf16 v[32:35], v[174:177], v[194:197], v[32:35]
	v_mfma_f32_16x16x32_bf16 v[36:39], v[166:169], v[194:197], v[36:39]
	v_mfma_f32_16x16x32_bf16 v[20:23], v[166:169], v[202:205], v[20:23]
	v_mfma_f32_16x16x32_bf16 v[16:19], v[174:177], v[202:205], v[16:19]
	v_mfma_f32_16x16x32_bf16 v[0:3], v[174:177], v[210:213], v[0:3]
	v_mfma_f32_16x16x32_bf16 v[4:7], v[166:169], v[210:213], v[4:7]
	v_mfma_f32_16x16x32_bf16 v[52:55], v[170:173], v[186:189], v[52:55]
	v_mfma_f32_16x16x32_bf16 v[48:51], v[178:181], v[186:189], v[48:51]
	v_mfma_f32_16x16x32_bf16 v[32:35], v[178:181], v[198:201], v[32:35]
	v_mfma_f32_16x16x32_bf16 v[36:39], v[170:173], v[198:201], v[36:39]
	v_mfma_f32_16x16x32_bf16 v[20:23], v[170:173], v[206:209], v[20:23]
	v_mfma_f32_16x16x32_bf16 v[16:19], v[178:181], v[206:209], v[16:19]
	v_mfma_f32_16x16x32_bf16 v[0:3], v[178:181], v[214:217], v[0:3]
	v_mfma_f32_16x16x32_bf16 v[4:7], v[170:173], v[214:217], v[4:7]
	s_setprio 0
	s_waitcnt vmcnt(8)
	s_barrier
	s_add_i32 s46, s46, 2
	s_add_u32 s20, s20, 0x100
	s_addc_u32 s21, s21, 0
	s_add_u32 s44, s44, 0x100
	s_addc_u32 s45, s45, 0
	s_cmp_gt_u32 s46, 29
	s_cbranch_scc0 .LBB0_1138
	s_and_b64 vcc, exec, s[8:9]
	s_cbranch_vccz .LBB0_1141
	s_barrier

; #define PG8_STAGE(bufoff, gbase, voff) do { _Pragma("unroll") for (int _i = 0; _i < 2; ++_i) \
;         __builtin_amdgcn_global_load_lds((const unsigned*)((const char*)(gbase) + (voff)[_i]), (PG8_LAS unsigned*)(lds + (bufoff) + ldsw + _i * 8192), 16, 0, 0); } while (0)
; #define PG8_LDA(dst, b, h) do { _Pragma("unroll") for (int m = 0; m < 4; ++m) _Pragma("unroll") for (int k = 0; k < 2; ++k) dst[m][k] = *(const PG8_LAS bf16x8*)(lds + PG8_SA(b, h) + aoff + m * 2048 + k * 1024); } while (0)
; #define PG8_MMA(ai, bj, At, Bt) do { __builtin_amdgcn_s_setprio(1); _Pragma("unroll") for (int m = 0; m < 4; ++m) _Pragma("unroll") for (int n = 0; n < 2; ++n) _Pragma("unroll") for (int k = 0; k < 2; ++k) \
;         acc[ai][bj][m][n] = __builtin_amdgcn_mfma_f32_16x16x32_bf16(Bt[n][k], At[m][k], acc[ai][bj][m][n], 0, 0, 0); __builtin_amdgcn_s_setprio(0); } while (0)
; #define PG8_WAIT_V(n) asm volatile("s_waitcnt vmcnt(" #n ")" ::: "memory")
; #define PG8_WAIT_L(n) asm volatile("s_waitcnt lgkmcnt(" #n ")" ::: "memory")
; #define PG8_BAR __builtin_amdgcn_s_barrier()
; #define PG8_SCHED __builtin_amdgcn_sched_barrier(0)
; template <class Epi, class Sched, bool ALIGN_EPI = false, bool SP2 = false>
; __device__ __forceinline__ void gemm_phase(PG8_LAS unsigned char* lds, const Gemm g, const Sched& S, const Epi& E) {
;     ...
;             PG8_WAIT_V(8); PG8_WAIT_L(0); PG8_BAR; PG8_MMA(0, 0, At, B0); PG8_MMA(0, 1, At, B1); PG8_BAR; PG8_SCHED;
;             PG8_LDA(At, 0, 1); PG8_STAGE(PG8_SB(0, 0), b2, voffB); PG8_STAGE(PG8_SB(0, 1), b2 + hstep, voffB); PG8_STAGE(PG8_SA(0, 0), a2, voffA);
;             PG8_WAIT_V(8); PG8_WAIT_L(0); PG8_BAR; PG8_MMA(1, 0, At, B0); PG8_MMA(1, 1, At, B1); PG8_BAR; PG8_SCHED;
.Lvw_52:
	s_waitcnt lgkmcnt(0)
	s_barrier
	s_setprio 1
	s_waitcnt lgkmcnt(0)
	v_mfma_f32_16x16x32_bf16 v[124:127], v[150:153], v[182:185], v[124:127]
	v_mfma_f32_16x16x32_bf16 v[120:123], v[158:161], v[182:185], v[120:123]
	v_mfma_f32_16x16x32_bf16 v[112:115], v[158:161], v[194:197], v[112:115]
	v_mfma_f32_16x16x32_bf16 v[116:119], v[150:153], v[194:197], v[116:119]
	v_mfma_f32_16x16x32_bf16 v[100:103], v[150:153], v[202:205], v[100:103]
	v_mfma_f32_16x16x32_bf16 v[96:99], v[158:161], v[202:205], v[96:99]
	v_mfma_f32_16x16x32_bf16 v[80:83], v[158:161], v[210:213], v[80:83]
	v_mfma_f32_16x16x32_bf16 v[84:87], v[150:153], v[210:213], v[84:87]
	v_mfma_f32_16x16x32_bf16 v[124:127], v[154:157], v[186:189], v[124:127]
	v_mfma_f32_16x16x32_bf16 v[120:123], v[162:165], v[186:189], v[120:123]
	v_mfma_f32_16x16x32_bf16 v[112:115], v[162:165], v[198:201], v[112:115]
	v_mfma_f32_16x16x32_bf16 v[116:119], v[154:157], v[198:201], v[116:119]
	v_mfma_f32_16x16x32_bf16 v[100:103], v[154:157], v[206:209], v[100:103]
	v_mfma_f32_16x16x32_bf16 v[96:99], v[162:165], v[206:209], v[96:99]
	v_mfma_f32_16x16x32_bf16 v[80:83], v[162:165], v[214:217], v[80:83]
	v_mfma_f32_16x16x32_bf16 v[84:87], v[154:157], v[214:217], v[84:87]
	s_setprio 0
	s_setprio 1
	v_mfma_f32_16x16x32_bf16 v[108:111], v[166:169], v[182:185], v[108:111]
	v_mfma_f32_16x16x32_bf16 v[104:107], v[174:177], v[182:185], v[104:107]
	v_mfma_f32_16x16x32_bf16 v[88:91], v[174:177], v[194:197], v[88:91]
	v_mfma_f32_16x16x32_bf16 v[92:95], v[166:169], v[194:197], v[92:95]
	v_mfma_f32_16x16x32_bf16 v[76:79], v[166:169], v[202:205], v[76:79]
	v_mfma_f32_16x16x32_bf16 v[72:75], v[174:177], v[202:205], v[72:75]
	v_mfma_f32_16x16x32_bf16 v[64:67], v[174:177], v[210:213], v[64:67]
	v_mfma_f32_16x16x32_bf16 v[68:71], v[166:169], v[210:213], v[68:71]
	v_mfma_f32_16x16x32_bf16 v[108:111], v[170:173], v[186:189], v[108:111]
	v_mfma_f32_16x16x32_bf16 v[104:107], v[178:181], v[186:189], v[104:107]
	v_mfma_f32_16x16x32_bf16 v[88:91], v[178:181], v[198:201], v[88:91]
	v_mfma_f32_16x16x32_bf16 v[92:95], v[170:173], v[198:201], v[92:95]
	v_mfma_f32_16x16x32_bf16 v[76:79], v[170:173], v[206:209], v[76:79]
	v_mfma_f32_16x16x32_bf16 v[72:75], v[178:181], v[206:209], v[72:75]
	v_mfma_f32_16x16x32_bf16 v[64:67], v[178:181], v[214:217], v[64:67]
	v_mfma_f32_16x16x32_bf16 v[68:71], v[170:173], v[214:217], v[68:71]
	s_setprio 0
	s_waitcnt vmcnt(8)
	s_barrier
	s_add_i32 s22, s40, s2
	v_lshl_add_u64 v[190:191], s[26:27], 0, v[132:133]
	s_mov_b32 m0, s22
	ds_read_b128 v[182:185], v149 offset:16384
	ds_read_b128 v[186:189], v149 offset:17408
	ds_read_b128 v[194:197], v149 offset:18432
	ds_read_b128 v[198:201], v149 offset:19456
	ds_read_b128 v[202:205], v149 offset:20480
	ds_read_b128 v[206:209], v149 offset:21504
	ds_read_b128 v[210:213], v149 offset:22528
	ds_read_b128 v[214:217], v149 offset:23552
	global_load_lds_dwordx4 v[190:191], off
	s_add_i32 m0, s22, 0x2000
	s_add_u32 s22, s26, 0x160000
	v_lshl_add_u64 v[218:219], s[26:27], 0, v[128:129]
	s_addc_u32 s23, s27, 0
	s_add_i32 s53, s41, s2
	global_load_lds_dwordx4 v[218:219], off
	v_lshl_add_u64 v[220:221], s[22:23], 0, v[132:133]
	s_mov_b32 m0, s53
	v_lshl_add_u64 v[222:223], s[28:29], 0, v[130:131]
	global_load_lds_dwordx4 v[220:221], off
	v_lshl_add_u64 v[220:221], s[22:23], 0, v[128:129]
	s_add_i32 m0, s53, 0x2000
	s_nop 0
	global_load_lds_dwordx4 v[220:221], off
	v_lshl_add_u64 v[220:221], s[28:29], 0, v[134:135]
	s_mov_b32 m0, s30
	s_nop 0
	global_load_lds_dwordx4 v[220:221], off
	s_mov_b32 m0, s31
	s_nop 0
	global_load_lds_dwordx4 v[222:223], off
	s_mov_b64 vcc, s[98:99]
	s_cbranch_vccnz .Lvw_53
	s_waitcnt vmcnt(8)
.Lvw_53:
	s_waitcnt lgkmcnt(0)
	s_barrier
	s_setprio 1
	s_waitcnt lgkmcnt(0)
	v_mfma_f32_16x16x32_bf16 v[60:63], v[150:153], v[182:185], v[60:63]
	v_mfma_f32_16x16x32_bf16 v[56:59], v[158:161], v[182:185], v[56:59]
	v_mfma_f32_16x16x32_bf16 v[48:51], v[158:161], v[194:197], v[48:51]
	v_mfma_f32_16x16x32_bf16 v[52:55], v[150:153], v[194:197], v[52:55]
	v_mfma_f32_16x16x32_bf16 v[36:39], v[150:153], v[202:205], v[36:39]
	v_mfma_f32_16x16x32_bf16 v[32:35], v[158:161], v[202:205], v[32:35]
	v_mfma_f32_16x16x32_bf16 v[16:19], v[158:161], v[210:213], v[16:19]
	v_mfma_f32_16x16x32_bf16 v[20:23], v[150:153], v[210:213], v[20:23]
	v_mfma_f32_16x16x32_bf16 v[60:63], v[154:157], v[186:189], v[60:63]
	v_mfma_f32_16x16x32_bf16 v[56:59], v[162:165], v[186:189], v[56:59]
	v_mfma_f32_16x16x32_bf16 v[48:51], v[162:165], v[198:201], v[48:51]
	v_mfma_f32_16x16x32_bf16 v[52:55], v[154:157], v[198:201], v[52:55]
	v_mfma_f32_16x16x32_bf16 v[36:39], v[154:157], v[206:209], v[36:39]
	v_mfma_f32_16x16x32_bf16 v[32:35], v[162:165], v[206:209], v[32:35]
	v_mfma_f32_16x16x32_bf16 v[16:19], v[162:165], v[214:217], v[16:19]
	v_mfma_f32_16x16x32_bf16 v[20:23], v[154:157], v[214:217], v[20:23]
	s_setprio 0
	s_setprio 1
	v_mfma_f32_16x16x32_bf16 v[44:47], v[166:169], v[182:185], v[44:47]
	v_mfma_f32_16x16x32_bf16 v[40:43], v[174:177], v[182:185], v[40:43]
	v_mfma_f32_16x16x32_bf16 v[24:27], v[174:177], v[194:197], v[24:27]
	v_mfma_f32_16x16x32_bf16 v[28:31], v[166:169], v[194:197], v[28:31]
	v_mfma_f32_16x16x32_bf16 v[12:15], v[166:169], v[202:205], v[12:15]
	v_mfma_f32_16x16x32_bf16 v[8:11], v[174:177], v[202:205], v[8:11]
	v_mfma_f32_16x16x32_bf16 v[0:3], v[174:177], v[210:213], v[0:3]
	v_mfma_f32_16x16x32_bf16 v[4:7], v[166:169], v[210:213], v[4:7]
	v_mfma_f32_16x16x32_bf16 v[44:47], v[170:173], v[186:189], v[44:47]
	v_mfma_f32_16x16x32_bf16 v[40:43], v[178:181], v[186:189], v[40:43]
	v_mfma_f32_16x16x32_bf16 v[24:27], v[178:181], v[198:201], v[24:27]
	v_mfma_f32_16x16x32_bf16 v[28:31], v[170:173], v[198:201], v[28:31]
	v_mfma_f32_16x16x32_bf16 v[12:15], v[170:173], v[206:209], v[12:15]
	v_mfma_f32_16x16x32_bf16 v[8:11], v[178:181], v[206:209], v[8:11]
	v_mfma_f32_16x16x32_bf16 v[0:3], v[178:181], v[214:217], v[0:3]
	v_mfma_f32_16x16x32_bf16 v[4:7], v[170:173], v[214:217], v[4:7]
	s_setprio 0
	s_waitcnt vmcnt(8)
	s_barrier
; #define PG8_STAGE(bufoff, gbase, voff) do { _Pragma("unroll") for (int _i = 0; _i < 2; ++_i) \
;         __builtin_amdgcn_global_load_lds((const unsigned*)((const char*)(gbase) + (voff)[_i]), (PG8_LAS unsigned*)(lds + (bufoff) + ldsw + _i * 8192), 16, 0, 0); } while (0)
; #define PG8_LDA(dst, b, h) do { _Pragma("unroll") for (int m = 0; m < 4; ++m) _Pragma("unroll") for (int k = 0; k < 2; ++k) dst[m][k] = *(const PG8_LAS bf16x8*)(lds + PG8_SA(b, h) + aoff + m * 2048 + k * 1024); } while (0)
; #define PG8_LDB(dst, b, h) do { _Pragma("unroll") for (int n = 0; n < 2; ++n) _Pragma("unroll") for (int k = 0; k < 2; ++k) dst[n][k] = *(const PG8_LAS bf16x8*)(lds + PG8_SB(b, h) + boff + n * 2048 + k * 1024); } while (0)
; #define PG8_MMA(ai, bj, At, Bt) do { __builtin_amdgcn_s_setprio(1); _Pragma("unroll") for (int m = 0; m < 4; ++m) _Pragma("unroll") for (int n = 0; n < 2; ++n) _Pragma("unroll") for (int k = 0; k < 2; ++k) \
;         acc[ai][bj][m][n] = __builtin_amdgcn_mfma_f32_16x16x32_bf16(Bt[n][k], At[m][k], acc[ai][bj][m][n], 0, 0, 0); __builtin_amdgcn_s_setprio(0); } while (0)
; #define PG8_WAIT_V(n) asm volatile("s_waitcnt vmcnt(" #n ")" ::: "memory")
; #define PG8_WAIT_L(n) asm volatile("s_waitcnt lgkmcnt(" #n ")" ::: "memory")
; #define PG8_BAR __builtin_amdgcn_s_barrier()
; #define PG8_SCHED __builtin_amdgcn_sched_barrier(0)
; template <class Epi, class Sched, bool ALIGN_EPI = false, bool SP2 = false>
; __device__ __forceinline__ void gemm_phase(PG8_LAS unsigned char* lds, const Gemm g, const Sched& S, const Epi& E) {
;     ...
;             PG8_LDB(B0, 1, 0); PG8_LDB(B1, 1, 1); PG8_SCHED; PG8_LDA(At, 1, 0); PG8_STAGE(PG8_SA(0, 1), a2 + hstep, voffA);
;             PG8_WAIT_V(8); PG8_WAIT_L(0); PG8_BAR; PG8_MMA(0, 0, At, B0); PG8_MMA(0, 1, At, B1); PG8_BAR; PG8_SCHED;
;             PG8_LDA(At, 1, 1); PG8_STAGE(PG8_SB(1, 0), b3, voffB); PG8_STAGE(PG8_SB(1, 1), b3 + hstep, voffB); PG8_STAGE(PG8_SA(1, 0), a3, voffA);
	s_add_i32 s53, 0, 0x18000
	s_add_i32 s54, 0, 0x1c000
	v_add_u32_e32 v162, s53, v145
	v_add_u32_e32 v178, s54, v145
	ds_read_b128 v[150:153], v162
	ds_read_b128 v[154:157], v162 offset:1024
	ds_read_b128 v[158:161], v162 offset:2048
	ds_read_b128 v[162:165], v162 offset:3072
	ds_read_b128 v[166:169], v178
	ds_read_b128 v[170:173], v178 offset:1024
	ds_read_b128 v[174:177], v178 offset:2048
	ds_read_b128 v[178:181], v178 offset:3072
	s_add_u32 s22, s28, 0x160000
	s_addc_u32 s23, s29, 0
	s_mov_b32 m0, s33
	v_lshl_add_u64 v[224:225], s[22:23], 0, v[134:135]
	ds_read_b128 v[182:185], v149 offset:32768
	ds_read_b128 v[186:189], v149 offset:33792
	ds_read_b128 v[194:197], v149 offset:34816
	ds_read_b128 v[198:201], v149 offset:35840
	ds_read_b128 v[202:205], v149 offset:36864
	ds_read_b128 v[206:209], v149 offset:37888
	ds_read_b128 v[210:213], v149 offset:38912
	ds_read_b128 v[214:217], v149 offset:39936
	global_load_lds_dwordx4 v[224:225], off
	v_lshl_add_u64 v[224:225], s[22:23], 0, v[130:131]
	s_mov_b32 m0, s34
	s_nop 0
	global_load_lds_dwordx4 v[224:225], off
	s_mov_b64 vcc, s[98:99]
	s_cbranch_vccnz .Lvw_54
	s_waitcnt vmcnt(8)
.Lvw_54:
	s_waitcnt lgkmcnt(0)
	s_barrier
	s_setprio 1
	s_waitcnt lgkmcnt(0)
	v_mfma_f32_16x16x32_bf16 v[124:127], v[150:153], v[182:185], v[124:127]
	v_mfma_f32_16x16x32_bf16 v[120:123], v[158:161], v[182:185], v[120:123]
	v_mfma_f32_16x16x32_bf16 v[112:115], v[158:161], v[194:197], v[112:115]
	v_mfma_f32_16x16x32_bf16 v[116:119], v[150:153], v[194:197], v[116:119]
	v_mfma_f32_16x16x32_bf16 v[100:103], v[150:153], v[202:205], v[100:103]
	v_mfma_f32_16x16x32_bf16 v[96:99], v[158:161], v[202:205], v[96:99]
	v_mfma_f32_16x16x32_bf16 v[80:83], v[158:161], v[210:213], v[80:83]
	v_mfma_f32_16x16x32_bf16 v[84:87], v[150:153], v[210:213], v[84:87]
	v_mfma_f32_16x16x32_bf16 v[124:127], v[154:157], v[186:189], v[124:127]
	v_mfma_f32_16x16x32_bf16 v[120:123], v[162:165], v[186:189], v[120:123]
	v_mfma_f32_16x16x32_bf16 v[112:115], v[162:165], v[198:201], v[112:115]
	v_mfma_f32_16x16x32_bf16 v[116:119], v[154:157], v[198:201], v[116:119]
	v_mfma_f32_16x16x32_bf16 v[100:103], v[154:157], v[206:209], v[100:103]
	v_mfma_f32_16x16x32_bf16 v[96:99], v[162:165], v[206:209], v[96:99]
	v_mfma_f32_16x16x32_bf16 v[80:83], v[162:165], v[214:217], v[80:83]
	v_mfma_f32_16x16x32_bf16 v[84:87], v[154:157], v[214:217], v[84:87]
	s_setprio 0
	s_setprio 1
	v_mfma_f32_16x16x32_bf16 v[108:111], v[166:169], v[182:185], v[108:111]
	v_mfma_f32_16x16x32_bf16 v[104:107], v[174:177], v[182:185], v[104:107]
	v_mfma_f32_16x16x32_bf16 v[88:91], v[174:177], v[194:197], v[88:91]
	v_mfma_f32_16x16x32_bf16 v[92:95], v[166:169], v[194:197], v[92:95]
	v_mfma_f32_16x16x32_bf16 v[76:79], v[166:169], v[202:205], v[76:79]
	v_mfma_f32_16x16x32_bf16 v[72:75], v[174:177], v[202:205], v[72:75]
	v_mfma_f32_16x16x32_bf16 v[64:67], v[174:177], v[210:213], v[64:67]
	v_mfma_f32_16x16x32_bf16 v[68:71], v[166:169], v[210:213], v[68:71]
	v_mfma_f32_16x16x32_bf16 v[108:111], v[170:173], v[186:189], v[108:111]
	v_mfma_f32_16x16x32_bf16 v[104:107], v[178:181], v[186:189], v[104:107]
	v_mfma_f32_16x16x32_bf16 v[88:91], v[178:181], v[198:201], v[88:91]
	v_mfma_f32_16x16x32_bf16 v[92:95], v[170:173], v[198:201], v[92:95]
	v_mfma_f32_16x16x32_bf16 v[76:79], v[170:173], v[206:209], v[76:79]
	v_mfma_f32_16x16x32_bf16 v[72:75], v[178:181], v[206:209], v[72:75]
	v_mfma_f32_16x16x32_bf16 v[64:67], v[178:181], v[214:217], v[64:67]
	v_mfma_f32_16x16x32_bf16 v[68:71], v[170:173], v[214:217], v[68:71]
	s_setprio 0
	s_waitcnt vmcnt(8)
	s_barrier
	s_add_i32 s22, s53, s2
	v_lshl_add_u64 v[190:191], v[190:191], 0, s[8:9]
	s_mov_b32 m0, s22
	ds_read_b128 v[182:185], v149 offset:49152
	ds_read_b128 v[186:189], v149 offset:50176
	ds_read_b128 v[194:197], v149 offset:51200
	ds_read_b128 v[198:201], v149 offset:52224
	ds_read_b128 v[202:205], v149 offset:53248
	ds_read_b128 v[206:209], v149 offset:54272
	ds_read_b128 v[210:213], v149 offset:55296
	ds_read_b128 v[214:217], v149 offset:56320
	global_load_lds_dwordx4 v[190:191], off
	s_add_i32 m0, s22, 0x2000
	s_add_u32 s22, s26, 0x160080
	v_lshl_add_u64 v[190:191], v[218:219], 0, s[8:9]
	s_addc_u32 s23, s27, 0
	s_add_i32 s26, s54, s2
	global_load_lds_dwordx4 v[190:191], off
	v_lshl_add_u64 v[190:191], s[22:23], 0, v[132:133]
	s_mov_b32 m0, s26
	s_nop 0
	global_load_lds_dwordx4 v[190:191], off
	v_lshl_add_u64 v[190:191], s[22:23], 0, v[128:129]
	s_add_i32 m0, s26, 0x2000
	s_nop 0
	global_load_lds_dwordx4 v[190:191], off
	v_lshl_add_u64 v[190:191], v[220:221], 0, s[8:9]
	s_mov_b32 m0, s36
	s_nop 0
	global_load_lds_dwordx4 v[190:191], off
	v_lshl_add_u64 v[190:191], v[222:223], 0, s[8:9]
	s_mov_b32 m0, s37
	s_nop 0
	global_load_lds_dwordx4 v[190:191], off
	s_mov_b64 vcc, s[98:99]
	s_cbranch_vccnz .Lvw_55
	s_waitcnt vmcnt(8)
; #define PG8_MMA(ai, bj, At, Bt) do { __builtin_amdgcn_s_setprio(1); _Pragma("unroll") for (int m = 0; m < 4; ++m) _Pragma("unroll") for (int n = 0; n < 2; ++n) _Pragma("unroll") for (int k = 0; k < 2; ++k) \
;         acc[ai][bj][m][n] = __builtin_amdgcn_mfma_f32_16x16x32_bf16(Bt[n][k], At[m][k], acc[ai][bj][m][n], 0, 0, 0); __builtin_amdgcn_s_setprio(0); } while (0)
; #define PG8_WAIT_V(n) asm volatile("s_waitcnt vmcnt(" #n ")" ::: "memory")
; #define PG8_WAIT_L(n) asm volatile("s_waitcnt lgkmcnt(" #n ")" ::: "memory")
; #define PG8_BAR __builtin_amdgcn_s_barrier()
; #define PG8_SCHED __builtin_amdgcn_sched_barrier(0)
; template <class Epi, class Sched, bool ALIGN_EPI = false, bool SP2 = false>
; __device__ __forceinline__ void gemm_phase(PG8_LAS unsigned char* lds, const Gemm g, const Sched& S, const Epi& E) {
;     ...
;             PG8_WAIT_V(8); PG8_WAIT_L(0); PG8_BAR; PG8_MMA(1, 0, At, B0); PG8_MMA(1, 1, At, B1); PG8_BAR; PG8_SCHED;
;     ...
;         if constexpr (ALIGN_EPI) { if (wr == 0) PG8_BAR; }
.Lvw_55:
	s_waitcnt lgkmcnt(0)
	s_barrier
	s_setprio 1
	s_waitcnt lgkmcnt(0)
	v_mfma_f32_16x16x32_bf16 v[60:63], v[150:153], v[182:185], v[60:63]
	v_mfma_f32_16x16x32_bf16 v[56:59], v[158:161], v[182:185], v[56:59]
	v_mfma_f32_16x16x32_bf16 v[48:51], v[158:161], v[194:197], v[48:51]
	v_mfma_f32_16x16x32_bf16 v[52:55], v[150:153], v[194:197], v[52:55]
	v_mfma_f32_16x16x32_bf16 v[36:39], v[150:153], v[202:205], v[36:39]
	v_mfma_f32_16x16x32_bf16 v[32:35], v[158:161], v[202:205], v[32:35]
	v_mfma_f32_16x16x32_bf16 v[16:19], v[158:161], v[210:213], v[16:19]
	v_mfma_f32_16x16x32_bf16 v[20:23], v[150:153], v[210:213], v[20:23]
	v_mfma_f32_16x16x32_bf16 v[60:63], v[154:157], v[186:189], v[60:63]
	v_mfma_f32_16x16x32_bf16 v[56:59], v[162:165], v[186:189], v[56:59]
	v_mfma_f32_16x16x32_bf16 v[48:51], v[162:165], v[198:201], v[48:51]
	v_mfma_f32_16x16x32_bf16 v[52:55], v[154:157], v[198:201], v[52:55]
	v_mfma_f32_16x16x32_bf16 v[36:39], v[154:157], v[206:209], v[36:39]
	v_mfma_f32_16x16x32_bf16 v[32:35], v[162:165], v[206:209], v[32:35]
	v_mfma_f32_16x16x32_bf16 v[16:19], v[162:165], v[214:217], v[16:19]
	v_mfma_f32_16x16x32_bf16 v[20:23], v[154:157], v[214:217], v[20:23]
	s_setprio 0
	s_setprio 1
	v_mfma_f32_16x16x32_bf16 v[44:47], v[166:169], v[182:185], v[44:47]
	v_mfma_f32_16x16x32_bf16 v[40:43], v[174:177], v[182:185], v[40:43]
	v_mfma_f32_16x16x32_bf16 v[24:27], v[174:177], v[194:197], v[24:27]
	v_mfma_f32_16x16x32_bf16 v[28:31], v[166:169], v[194:197], v[28:31]
	v_mfma_f32_16x16x32_bf16 v[12:15], v[166:169], v[202:205], v[12:15]
	v_mfma_f32_16x16x32_bf16 v[8:11], v[174:177], v[202:205], v[8:11]
	v_mfma_f32_16x16x32_bf16 v[0:3], v[174:177], v[210:213], v[0:3]
	v_mfma_f32_16x16x32_bf16 v[4:7], v[166:169], v[210:213], v[4:7]
	v_mfma_f32_16x16x32_bf16 v[44:47], v[170:173], v[186:189], v[44:47]
	v_mfma_f32_16x16x32_bf16 v[40:43], v[178:181], v[186:189], v[40:43]
	v_mfma_f32_16x16x32_bf16 v[24:27], v[178:181], v[198:201], v[24:27]
	v_mfma_f32_16x16x32_bf16 v[28:31], v[170:173], v[198:201], v[28:31]
	v_mfma_f32_16x16x32_bf16 v[12:15], v[170:173], v[206:209], v[12:15]
	v_mfma_f32_16x16x32_bf16 v[8:11], v[178:181], v[206:209], v[8:11]
	v_mfma_f32_16x16x32_bf16 v[0:3], v[178:181], v[214:217], v[0:3]
	v_mfma_f32_16x16x32_bf16 v[4:7], v[170:173], v[214:217], v[4:7]
	s_setprio 0
	s_waitcnt vmcnt(8)
	s_barrier
	s_add_i32 s52, s52, 2
	s_add_u32 s50, s50, 0x100
	s_addc_u32 s51, s51, 0
	s_cmpk_gt_u32 s52, 0x55
	s_mov_b64 s[22:23], s[24:25]
	s_cbranch_scc0 .LBB0_1210
	s_and_b64 vcc, exec, s[10:11]
	s_cbranch_vccz .LBB0_1213
	s_barrier
